# GEMM K-loops (11 loops): LDS-DMA addresses in saddr form (SGPR tile base + 32-bit lane offset), 14-16 v_lshl_add_u64 per iteration removed; +0x80 bases kept in spare SGPR pairs
# speedup vs baseline: 1.0094x; 1.0039x over previous
; #define PG8_STAGE(bufoff, gbase, voff) do { _Pragma("unroll") for (int _i = 0; _i < 2; ++_i) \
;         __builtin_amdgcn_global_load_lds((const unsigned*)((const char*)(gbase) + (voff)[_i]), (PG8_LAS unsigned*)(lds + (bufoff) + ldsw + _i * 8192), 16, 0, 0); } while (0)
; #define PG8_LDA(dst, b, h) do { _Pragma("unroll") for (int m = 0; m < 4; ++m) _Pragma("unroll") for (int k = 0; k < 2; ++k) dst[m][k] = *(const PG8_LAS bf16x8*)(lds + PG8_SA(b, h) + aoff + m * 2048 + k * 1024); } while (0)
; #define PG8_LDB(dst, b, h) do { _Pragma("unroll") for (int n = 0; n < 2; ++n) _Pragma("unroll") for (int k = 0; k < 2; ++k) dst[n][k] = *(const PG8_LAS bf16x8*)(lds + PG8_SB(b, h) + boff + n * 2048 + k * 1024); } while (0)
; #define PG8_MMA(ai, bj, At, Bt) do { __builtin_amdgcn_s_setprio(1); _Pragma("unroll") for (int m = 0; m < 4; ++m) _Pragma("unroll") for (int n = 0; n < 2; ++n) _Pragma("unroll") for (int k = 0; k < 2; ++k) \
;         acc[ai][bj][m][n] = __builtin_amdgcn_mfma_f32_16x16x32_bf16(Bt[n][k], At[m][k], acc[ai][bj][m][n], 0, 0, 0); __builtin_amdgcn_s_setprio(0); } while (0)
; #define PG8_WAIT_V(n) asm volatile("s_waitcnt vmcnt(" #n ")" ::: "memory")
; template <class Epi, class Sched, bool ALIGN_EPI = false, bool SP2 = false>
; __device__ __forceinline__ void gemm_phase(PG8_LAS unsigned char* lds, const Gemm g, const Sched& S, const Epi& E) {
;     ...
;             PG8_LDB(B0, 0, 0); PG8_LDB(B1, 0, 1); PG8_SCHED; PG8_LDA(At, 0, 0); PG8_STAGE(PG8_SA(1, 1), a1 + hstepA, voffA);
;             PG8_WAIT_V(8); PG8_WAIT_L(0); PG8_BAR; PG8_MMA(0, 0, At, B0); PG8_MMA(0, 1, At, B1); PG8_BAR; PG8_SCHED;
;             PG8_LDA(At, 0, 1); PG8_STAGE(PG8_SB(0, 0), b2, voffB); PG8_STAGE(PG8_SB(0, 1), b2 + hstepB, voffB); PG8_STAGE(PG8_SA(0, 0), a2, voffA);
;             PG8_WAIT_V(8); PG8_WAIT_L(0); PG8_BAR; PG8_MMA(1, 0, At, B0); PG8_MMA(1, 1, At, B1); PG8_BAR; PG8_SCHED;
;             PG8_LDB(B0, 1, 0); PG8_LDB(B1, 1, 1); PG8_SCHED; PG8_LDA(At, 1, 0); PG8_STAGE(PG8_SA(0, 1), a2 + hstepA, voffA);
;             PG8_WAIT_V(8); PG8_WAIT_L(0); PG8_BAR; PG8_MMA(0, 0, At, B0); PG8_MMA(0, 1, At, B1); PG8_BAR; PG8_SCHED;
;             PG8_LDA(At, 1, 1); PG8_STAGE(PG8_SB(1, 0), b3, voffB); PG8_STAGE(PG8_SB(1, 1), b3 + hstepB, voffB); PG8_STAGE(PG8_SA(1, 0), a3, voffA);
;             PG8_WAIT_V(8); PG8_WAIT_L(0); PG8_BAR; PG8_MMA(1, 0, At, B0); PG8_MMA(1, 1, At, B1); PG8_BAR; PG8_SCHED;
.LBB0_318:
	ds_read_b128 v[156:159], v153
	ds_read_b128 v[160:163], v153 offset:1024
	ds_read_b128 v[164:167], v153 offset:2048
	ds_read_b128 v[168:171], v153 offset:3072
	ds_read_b128 v[172:175], v154
	ds_read_b128 v[176:179], v154 offset:1024
	ds_read_b128 v[180:183], v154 offset:2048
	ds_read_b128 v[184:187], v154 offset:3072
	s_add_u32 s8, s6, 0xfffc0080
	s_addc_u32 s9, s7, -1
	s_cmp_eq_u32 s36, 12
	s_cselect_b32 s31, s1, s9
	s_cselect_b32 s30, s5, s8
	s_cselect_b32 s9, s23, s35
	s_cselect_b32 s8, s25, s34
	s_add_i32 m0, s42, 0xc000
	ds_read_b128 v[188:191], v155
	ds_read_b128 v[192:195], v155 offset:1024
	ds_read_b128 v[196:199], v155 offset:2048
	ds_read_b128 v[200:203], v155 offset:3072
	ds_read_b128 v[204:207], v155 offset:4096
	ds_read_b128 v[208:211], v155 offset:5120
	ds_read_b128 v[212:215], v155 offset:6144
	ds_read_b128 v[216:219], v155 offset:7168
	global_load_lds_dwordx4 v140, s[6:7]
	s_add_i32 m0, s42, 0xe000
	s_nop 0
	global_load_lds_dwordx4 v142, s[6:7]
	s_waitcnt vmcnt(8)
	s_waitcnt lgkmcnt(0)
	s_barrier
	s_setprio 1
	s_waitcnt lgkmcnt(0)
	v_mfma_f32_16x16x32_bf16 v[126:129], v[156:159], v[188:191], v[126:129]
	v_mfma_f32_16x16x32_bf16 v[122:125], v[164:167], v[188:191], v[122:125]
	v_mfma_f32_16x16x32_bf16 v[110:113], v[156:159], v[196:199], v[110:113]
	v_mfma_f32_16x16x32_bf16 v[106:109], v[164:167], v[196:199], v[106:109]
	v_mfma_f32_16x16x32_bf16 v[94:97], v[156:159], v[204:207], v[94:97]
	v_mfma_f32_16x16x32_bf16 v[90:93], v[164:167], v[204:207], v[90:93]
	v_mfma_f32_16x16x32_bf16 v[78:81], v[156:159], v[212:215], v[78:81]
	v_mfma_f32_16x16x32_bf16 v[74:77], v[164:167], v[212:215], v[74:77]
	v_mfma_f32_16x16x32_bf16 v[126:129], v[160:163], v[192:195], v[126:129]
	v_mfma_f32_16x16x32_bf16 v[122:125], v[168:171], v[192:195], v[122:125]
	v_mfma_f32_16x16x32_bf16 v[110:113], v[160:163], v[200:203], v[110:113]
	v_mfma_f32_16x16x32_bf16 v[106:109], v[168:171], v[200:203], v[106:109]
	v_mfma_f32_16x16x32_bf16 v[94:97], v[160:163], v[208:211], v[94:97]
	v_mfma_f32_16x16x32_bf16 v[90:93], v[168:171], v[208:211], v[90:93]
	v_mfma_f32_16x16x32_bf16 v[78:81], v[160:163], v[216:219], v[78:81]
	v_mfma_f32_16x16x32_bf16 v[74:77], v[168:171], v[216:219], v[74:77]
	s_setprio 0
	s_setprio 1
	v_mfma_f32_16x16x32_bf16 v[118:121], v[172:175], v[188:191], v[118:121]
	v_mfma_f32_16x16x32_bf16 v[114:117], v[180:183], v[188:191], v[114:117]
	v_mfma_f32_16x16x32_bf16 v[102:105], v[172:175], v[196:199], v[102:105]
	v_mfma_f32_16x16x32_bf16 v[98:101], v[180:183], v[196:199], v[98:101]
	v_mfma_f32_16x16x32_bf16 v[86:89], v[172:175], v[204:207], v[86:89]
	v_mfma_f32_16x16x32_bf16 v[82:85], v[180:183], v[204:207], v[82:85]
	v_mfma_f32_16x16x32_bf16 v[70:73], v[172:175], v[212:215], v[70:73]
	v_mfma_f32_16x16x32_bf16 v[66:69], v[180:183], v[212:215], v[66:69]
	v_mfma_f32_16x16x32_bf16 v[118:121], v[176:179], v[192:195], v[118:121]
	v_mfma_f32_16x16x32_bf16 v[114:117], v[184:187], v[192:195], v[114:117]
	v_mfma_f32_16x16x32_bf16 v[102:105], v[176:179], v[200:203], v[102:105]
	v_mfma_f32_16x16x32_bf16 v[98:101], v[184:187], v[200:203], v[98:101]
	v_mfma_f32_16x16x32_bf16 v[86:89], v[176:179], v[208:211], v[86:89]
	v_mfma_f32_16x16x32_bf16 v[82:85], v[184:187], v[208:211], v[82:85]
	v_mfma_f32_16x16x32_bf16 v[70:73], v[176:179], v[216:219], v[70:73]
	v_mfma_f32_16x16x32_bf16 v[66:69], v[184:187], v[216:219], v[66:69]
	s_setprio 0
	s_barrier
	s_add_i32 s37, s59, s41
	s_add_u32 s98, s8, 0x80
	s_addc_u32 s99, s9, 0
	s_mov_b32 m0, s37
	ds_read_b128 v[188:191], v155 offset:16384
	ds_read_b128 v[192:195], v155 offset:17408
	ds_read_b128 v[196:199], v155 offset:18432
	ds_read_b128 v[200:203], v155 offset:19456
	ds_read_b128 v[204:207], v155 offset:20480
	ds_read_b128 v[208:211], v155 offset:21504
	ds_read_b128 v[212:215], v155 offset:22528
	ds_read_b128 v[216:219], v155 offset:23552
	global_load_lds_dwordx4 v132, s[8:9]
	s_add_i32 m0, s37, 0x2000
	s_add_u32 s72, s8, 0x40000
	s_addc_u32 s73, s9, 0
	s_add_i32 s37, s60, s41
	global_load_lds_dwordx4 v136, s[8:9]
	s_mov_b32 m0, s37
	s_nop 0
	global_load_lds_dwordx4 v132, s[72:73]
	s_add_i32 m0, s37, 0x2000
	s_nop 0
	global_load_lds_dwordx4 v136, s[72:73]
	s_add_u32 s100, s30, 0x80
	s_addc_u32 s101, s31, 0
	s_mov_b32 m0, s42
	s_nop 0
	global_load_lds_dwordx4 v130, s[30:31]
	s_mov_b32 m0, s43
	s_nop 0
	global_load_lds_dwordx4 v134, s[30:31]
	s_waitcnt vmcnt(8)
	s_waitcnt lgkmcnt(0)
	s_barrier
	s_setprio 1
	s_waitcnt lgkmcnt(0)
	v_mfma_f32_16x16x32_bf16 v[62:65], v[156:159], v[188:191], v[62:65]
	v_mfma_f32_16x16x32_bf16 v[58:61], v[164:167], v[188:191], v[58:61]
	v_mfma_f32_16x16x32_bf16 v[46:49], v[156:159], v[196:199], v[46:49]
	v_mfma_f32_16x16x32_bf16 v[42:45], v[164:167], v[196:199], v[42:45]
	v_mfma_f32_16x16x32_bf16 v[30:33], v[156:159], v[204:207], v[30:33]
	v_mfma_f32_16x16x32_bf16 v[26:29], v[164:167], v[204:207], v[26:29]
	v_mfma_f32_16x16x32_bf16 v[14:17], v[156:159], v[212:215], v[14:17]
	v_mfma_f32_16x16x32_bf16 v[10:13], v[164:167], v[212:215], v[10:13]
	v_mfma_f32_16x16x32_bf16 v[62:65], v[160:163], v[192:195], v[62:65]
	v_mfma_f32_16x16x32_bf16 v[58:61], v[168:171], v[192:195], v[58:61]
	v_mfma_f32_16x16x32_bf16 v[46:49], v[160:163], v[200:203], v[46:49]
	v_mfma_f32_16x16x32_bf16 v[42:45], v[168:171], v[200:203], v[42:45]
	v_mfma_f32_16x16x32_bf16 v[30:33], v[160:163], v[208:211], v[30:33]
	v_mfma_f32_16x16x32_bf16 v[26:29], v[168:171], v[208:211], v[26:29]
	v_mfma_f32_16x16x32_bf16 v[14:17], v[160:163], v[216:219], v[14:17]
	v_mfma_f32_16x16x32_bf16 v[10:13], v[168:171], v[216:219], v[10:13]
	s_setprio 0
	s_setprio 1
	v_mfma_f32_16x16x32_bf16 v[54:57], v[172:175], v[188:191], v[54:57]
	v_mfma_f32_16x16x32_bf16 v[50:53], v[180:183], v[188:191], v[50:53]
	v_mfma_f32_16x16x32_bf16 v[38:41], v[172:175], v[196:199], v[38:41]
	v_mfma_f32_16x16x32_bf16 v[34:37], v[180:183], v[196:199], v[34:37]
	v_mfma_f32_16x16x32_bf16 v[22:25], v[172:175], v[204:207], v[22:25]
	v_mfma_f32_16x16x32_bf16 v[18:21], v[180:183], v[204:207], v[18:21]
	v_mfma_f32_16x16x32_bf16 v[6:9], v[172:175], v[212:215], v[6:9]
	v_mfma_f32_16x16x32_bf16 v[2:5], v[180:183], v[212:215], v[2:5]
	v_mfma_f32_16x16x32_bf16 v[54:57], v[176:179], v[192:195], v[54:57]
	v_mfma_f32_16x16x32_bf16 v[50:53], v[184:187], v[192:195], v[50:53]
	v_mfma_f32_16x16x32_bf16 v[38:41], v[176:179], v[200:203], v[38:41]
	v_mfma_f32_16x16x32_bf16 v[34:37], v[184:187], v[200:203], v[34:37]
	v_mfma_f32_16x16x32_bf16 v[22:25], v[176:179], v[208:211], v[22:25]
	v_mfma_f32_16x16x32_bf16 v[18:21], v[184:187], v[208:211], v[18:21]
	v_mfma_f32_16x16x32_bf16 v[6:9], v[176:179], v[216:219], v[6:9]
	v_mfma_f32_16x16x32_bf16 v[2:5], v[184:187], v[216:219], v[2:5]
	s_setprio 0
	s_barrier
; #define PG8_STAGE(bufoff, gbase, voff) do { _Pragma("unroll") for (int _i = 0; _i < 2; ++_i) \
;         __builtin_amdgcn_global_load_lds((const unsigned*)((const char*)(gbase) + (voff)[_i]), (PG8_LAS unsigned*)(lds + (bufoff) + ldsw + _i * 8192), 16, 0, 0); } while (0)
; #define PG8_LDA(dst, b, h) do { _Pragma("unroll") for (int m = 0; m < 4; ++m) _Pragma("unroll") for (int k = 0; k < 2; ++k) dst[m][k] = *(const PG8_LAS bf16x8*)(lds + PG8_SA(b, h) + aoff + m * 2048 + k * 1024); } while (0)
; #define PG8_LDB(dst, b, h) do { _Pragma("unroll") for (int n = 0; n < 2; ++n) _Pragma("unroll") for (int k = 0; k < 2; ++k) dst[n][k] = *(const PG8_LAS bf16x8*)(lds + PG8_SB(b, h) + boff + n * 2048 + k * 1024); } while (0)
; #define PG8_MMA(ai, bj, At, Bt) do { __builtin_amdgcn_s_setprio(1); _Pragma("unroll") for (int m = 0; m < 4; ++m) _Pragma("unroll") for (int n = 0; n < 2; ++n) _Pragma("unroll") for (int k = 0; k < 2; ++k) \
;         acc[ai][bj][m][n] = __builtin_amdgcn_mfma_f32_16x16x32_bf16(Bt[n][k], At[m][k], acc[ai][bj][m][n], 0, 0, 0); __builtin_amdgcn_s_setprio(0); } while (0)
; #define PG8_WAIT_V(n) asm volatile("s_waitcnt vmcnt(" #n ")" ::: "memory")
; template <class Epi, class Sched, bool ALIGN_EPI = false, bool SP2 = false>
; __device__ __forceinline__ void gemm_phase(PG8_LAS unsigned char* lds, const Gemm g, const Sched& S, const Epi& E) {
;     ...
;             PG8_LDB(B0, 0, 0); PG8_LDB(B1, 0, 1); PG8_SCHED; PG8_LDA(At, 0, 0); PG8_STAGE(PG8_SA(1, 1), a1 + hstepA, voffA);
;             PG8_WAIT_V(8); PG8_WAIT_L(0); PG8_BAR; PG8_MMA(0, 0, At, B0); PG8_MMA(0, 1, At, B1); PG8_BAR; PG8_SCHED;
;             PG8_LDA(At, 0, 1); PG8_STAGE(PG8_SB(0, 0), b2, voffB); PG8_STAGE(PG8_SB(0, 1), b2 + hstepB, voffB); PG8_STAGE(PG8_SA(0, 0), a2, voffA);
;             PG8_WAIT_V(8); PG8_WAIT_L(0); PG8_BAR; PG8_MMA(1, 0, At, B0); PG8_MMA(1, 1, At, B1); PG8_BAR; PG8_SCHED;
;             PG8_LDB(B0, 1, 0); PG8_LDB(B1, 1, 1); PG8_SCHED; PG8_LDA(At, 1, 0); PG8_STAGE(PG8_SA(0, 1), a2 + hstepA, voffA);
;             PG8_WAIT_V(8); PG8_WAIT_L(0); PG8_BAR; PG8_MMA(0, 0, At, B0); PG8_MMA(0, 1, At, B1); PG8_BAR; PG8_SCHED;
;             PG8_LDA(At, 1, 1); PG8_STAGE(PG8_SB(1, 0), b3, voffB); PG8_STAGE(PG8_SB(1, 1), b3 + hstepB, voffB); PG8_STAGE(PG8_SA(1, 0), a3, voffA);
;             PG8_WAIT_V(8); PG8_WAIT_L(0); PG8_BAR; PG8_MMA(1, 0, At, B0); PG8_MMA(1, 1, At, B1); PG8_BAR; PG8_SCHED;
	s_add_i32 s37, 0, 0x18000
	v_add_u32_e32 v138, s37, v152
	s_add_i32 s71, 0, 0x1c000
	ds_read_b128 v[156:159], v138
	ds_read_b128 v[160:163], v138 offset:1024
	ds_read_b128 v[164:167], v138 offset:2048
	ds_read_b128 v[168:171], v138 offset:3072
	v_add_u32_e32 v138, s71, v152
	ds_read_b128 v[172:175], v138
	ds_read_b128 v[176:179], v138 offset:1024
	ds_read_b128 v[180:183], v138 offset:2048
	ds_read_b128 v[184:187], v138 offset:3072
	s_add_u32 s30, s30, 0x40000
	s_addc_u32 s31, s31, 0
	s_mov_b32 m0, s44
	ds_read_b128 v[188:191], v155 offset:32768
	ds_read_b128 v[192:195], v155 offset:33792
	ds_read_b128 v[196:199], v155 offset:34816
	ds_read_b128 v[200:203], v155 offset:35840
	ds_read_b128 v[204:207], v155 offset:36864
	ds_read_b128 v[208:211], v155 offset:37888
	ds_read_b128 v[212:215], v155 offset:38912
	ds_read_b128 v[216:219], v155 offset:39936
	global_load_lds_dwordx4 v130, s[30:31]
	s_mov_b32 m0, s45
	s_nop 0
	global_load_lds_dwordx4 v134, s[30:31]
	s_waitcnt vmcnt(8)
	s_waitcnt lgkmcnt(0)
	s_barrier
	s_setprio 1
	s_waitcnt lgkmcnt(0)
	v_mfma_f32_16x16x32_bf16 v[126:129], v[156:159], v[188:191], v[126:129]
	v_mfma_f32_16x16x32_bf16 v[122:125], v[164:167], v[188:191], v[122:125]
	v_mfma_f32_16x16x32_bf16 v[110:113], v[156:159], v[196:199], v[110:113]
	v_mfma_f32_16x16x32_bf16 v[106:109], v[164:167], v[196:199], v[106:109]
	v_mfma_f32_16x16x32_bf16 v[94:97], v[156:159], v[204:207], v[94:97]
	v_mfma_f32_16x16x32_bf16 v[90:93], v[164:167], v[204:207], v[90:93]
	v_mfma_f32_16x16x32_bf16 v[78:81], v[156:159], v[212:215], v[78:81]
	v_mfma_f32_16x16x32_bf16 v[74:77], v[164:167], v[212:215], v[74:77]
	v_mfma_f32_16x16x32_bf16 v[126:129], v[160:163], v[192:195], v[126:129]
	v_mfma_f32_16x16x32_bf16 v[122:125], v[168:171], v[192:195], v[122:125]
	v_mfma_f32_16x16x32_bf16 v[110:113], v[160:163], v[200:203], v[110:113]
	v_mfma_f32_16x16x32_bf16 v[106:109], v[168:171], v[200:203], v[106:109]
	v_mfma_f32_16x16x32_bf16 v[94:97], v[160:163], v[208:211], v[94:97]
	v_mfma_f32_16x16x32_bf16 v[90:93], v[168:171], v[208:211], v[90:93]
	v_mfma_f32_16x16x32_bf16 v[78:81], v[160:163], v[216:219], v[78:81]
	v_mfma_f32_16x16x32_bf16 v[74:77], v[168:171], v[216:219], v[74:77]
	s_setprio 0
	s_setprio 1
	v_mfma_f32_16x16x32_bf16 v[118:121], v[172:175], v[188:191], v[118:121]
	v_mfma_f32_16x16x32_bf16 v[114:117], v[180:183], v[188:191], v[114:117]
	v_mfma_f32_16x16x32_bf16 v[102:105], v[172:175], v[196:199], v[102:105]
	v_mfma_f32_16x16x32_bf16 v[98:101], v[180:183], v[196:199], v[98:101]
	v_mfma_f32_16x16x32_bf16 v[86:89], v[172:175], v[204:207], v[86:89]
	v_mfma_f32_16x16x32_bf16 v[82:85], v[180:183], v[204:207], v[82:85]
	v_mfma_f32_16x16x32_bf16 v[70:73], v[172:175], v[212:215], v[70:73]
	v_mfma_f32_16x16x32_bf16 v[66:69], v[180:183], v[212:215], v[66:69]
	v_mfma_f32_16x16x32_bf16 v[118:121], v[176:179], v[192:195], v[118:121]
	v_mfma_f32_16x16x32_bf16 v[114:117], v[184:187], v[192:195], v[114:117]
	v_mfma_f32_16x16x32_bf16 v[102:105], v[176:179], v[200:203], v[102:105]
	v_mfma_f32_16x16x32_bf16 v[98:101], v[184:187], v[200:203], v[98:101]
	v_mfma_f32_16x16x32_bf16 v[86:89], v[176:179], v[208:211], v[86:89]
	v_mfma_f32_16x16x32_bf16 v[82:85], v[184:187], v[208:211], v[82:85]
	v_mfma_f32_16x16x32_bf16 v[70:73], v[176:179], v[216:219], v[70:73]
	v_mfma_f32_16x16x32_bf16 v[66:69], v[184:187], v[216:219], v[66:69]
	s_setprio 0
	s_barrier
	s_add_i32 s30, s37, s41
	s_mov_b32 m0, s30
	ds_read_b128 v[188:191], v155 offset:49152
	ds_read_b128 v[192:195], v155 offset:50176
	ds_read_b128 v[196:199], v155 offset:51200
	ds_read_b128 v[200:203], v155 offset:52224
	ds_read_b128 v[204:207], v155 offset:53248
	ds_read_b128 v[208:211], v155 offset:54272
	ds_read_b128 v[212:215], v155 offset:55296
	ds_read_b128 v[216:219], v155 offset:56320
	global_load_lds_dwordx4 v132, s[98:99]
	s_add_i32 m0, s30, 0x2000
	s_add_u32 s8, s8, 0x40080
	s_addc_u32 s9, s9, 0
	s_add_i32 s30, s71, s41
	global_load_lds_dwordx4 v136, s[98:99]
	s_mov_b32 m0, s30
	s_nop 0
	global_load_lds_dwordx4 v132, s[8:9]
	s_add_i32 m0, s30, 0x2000
	s_nop 0
	global_load_lds_dwordx4 v136, s[8:9]
	s_mov_b32 m0, s54
	s_nop 0
	global_load_lds_dwordx4 v130, s[100:101]
	s_mov_b32 m0, s55
	s_nop 0
	global_load_lds_dwordx4 v134, s[100:101]
	s_waitcnt vmcnt(8)
	s_waitcnt lgkmcnt(0)
	s_barrier
	s_setprio 1
	s_waitcnt lgkmcnt(0)
	v_mfma_f32_16x16x32_bf16 v[62:65], v[156:159], v[188:191], v[62:65]
	v_mfma_f32_16x16x32_bf16 v[58:61], v[164:167], v[188:191], v[58:61]
	v_mfma_f32_16x16x32_bf16 v[46:49], v[156:159], v[196:199], v[46:49]
	v_mfma_f32_16x16x32_bf16 v[42:45], v[164:167], v[196:199], v[42:45]
	v_mfma_f32_16x16x32_bf16 v[30:33], v[156:159], v[204:207], v[30:33]
	v_mfma_f32_16x16x32_bf16 v[26:29], v[164:167], v[204:207], v[26:29]
	v_mfma_f32_16x16x32_bf16 v[14:17], v[156:159], v[212:215], v[14:17]
	v_mfma_f32_16x16x32_bf16 v[10:13], v[164:167], v[212:215], v[10:13]
	v_mfma_f32_16x16x32_bf16 v[62:65], v[160:163], v[192:195], v[62:65]
	v_mfma_f32_16x16x32_bf16 v[58:61], v[168:171], v[192:195], v[58:61]
	v_mfma_f32_16x16x32_bf16 v[46:49], v[160:163], v[200:203], v[46:49]
	v_mfma_f32_16x16x32_bf16 v[42:45], v[168:171], v[200:203], v[42:45]
	v_mfma_f32_16x16x32_bf16 v[30:33], v[160:163], v[208:211], v[30:33]
	v_mfma_f32_16x16x32_bf16 v[26:29], v[168:171], v[208:211], v[26:29]
	v_mfma_f32_16x16x32_bf16 v[14:17], v[160:163], v[216:219], v[14:17]
	v_mfma_f32_16x16x32_bf16 v[10:13], v[168:171], v[216:219], v[10:13]
	s_setprio 0
	s_setprio 1
	v_mfma_f32_16x16x32_bf16 v[54:57], v[172:175], v[188:191], v[54:57]
	v_mfma_f32_16x16x32_bf16 v[50:53], v[180:183], v[188:191], v[50:53]
	v_mfma_f32_16x16x32_bf16 v[38:41], v[172:175], v[196:199], v[38:41]
	v_mfma_f32_16x16x32_bf16 v[34:37], v[180:183], v[196:199], v[34:37]
	v_mfma_f32_16x16x32_bf16 v[22:25], v[172:175], v[204:207], v[22:25]
	v_mfma_f32_16x16x32_bf16 v[18:21], v[180:183], v[204:207], v[18:21]
	v_mfma_f32_16x16x32_bf16 v[6:9], v[172:175], v[212:215], v[6:9]
	v_mfma_f32_16x16x32_bf16 v[2:5], v[180:183], v[212:215], v[2:5]
	v_mfma_f32_16x16x32_bf16 v[54:57], v[176:179], v[192:195], v[54:57]
	v_mfma_f32_16x16x32_bf16 v[50:53], v[184:187], v[192:195], v[50:53]
	v_mfma_f32_16x16x32_bf16 v[38:41], v[176:179], v[200:203], v[38:41]
	v_mfma_f32_16x16x32_bf16 v[34:37], v[184:187], v[200:203], v[34:37]
	v_mfma_f32_16x16x32_bf16 v[22:25], v[176:179], v[208:211], v[22:25]
	v_mfma_f32_16x16x32_bf16 v[18:21], v[184:187], v[208:211], v[18:21]
	v_mfma_f32_16x16x32_bf16 v[6:9], v[176:179], v[216:219], v[6:9]
	v_mfma_f32_16x16x32_bf16 v[2:5], v[184:187], v[216:219], v[2:5]
	s_setprio 0
	s_barrier
	s_add_i32 s36, s36, 2
	s_add_u32 s6, s6, 0x100
	s_addc_u32 s7, s7, 0
	s_add_u32 s34, s34, 0x100
	s_addc_u32 s35, s35, 0
	s_cmp_gt_u32 s36, 13
	s_cbranch_scc0 .LBB0_318
	s_and_b64 vcc, exec, s[18:19]
	s_cbranch_vccz .LBB0_321
	s_barrier

; #define PG8_STAGE(bufoff, gbase, voff) do { _Pragma("unroll") for (int _i = 0; _i < 2; ++_i) \
;         __builtin_amdgcn_global_load_lds((const unsigned*)((const char*)(gbase) + (voff)[_i]), (PG8_LAS unsigned*)(lds + (bufoff) + ldsw + _i * 8192), 16, 0, 0); } while (0)
; #define PG8_LDA(dst, b, h) do { _Pragma("unroll") for (int m = 0; m < 4; ++m) _Pragma("unroll") for (int k = 0; k < 2; ++k) dst[m][k] = *(const PG8_LAS bf16x8*)(lds + PG8_SA(b, h) + aoff + m * 2048 + k * 1024); } while (0)
; #define PG8_LDB(dst, b, h) do { _Pragma("unroll") for (int n = 0; n < 2; ++n) _Pragma("unroll") for (int k = 0; k < 2; ++k) dst[n][k] = *(const PG8_LAS bf16x8*)(lds + PG8_SB(b, h) + boff + n * 2048 + k * 1024); } while (0)
; #define PG8_MMA(ai, bj, At, Bt) do { __builtin_amdgcn_s_setprio(1); _Pragma("unroll") for (int m = 0; m < 4; ++m) _Pragma("unroll") for (int n = 0; n < 2; ++n) _Pragma("unroll") for (int k = 0; k < 2; ++k) \
;         acc[ai][bj][m][n] = __builtin_amdgcn_mfma_f32_16x16x32_bf16(Bt[n][k], At[m][k], acc[ai][bj][m][n], 0, 0, 0); __builtin_amdgcn_s_setprio(0); } while (0)
; #define PG8_WAIT_V(n) asm volatile("s_waitcnt vmcnt(" #n ")" ::: "memory")
; template <class Epi, class Sched, bool ALIGN_EPI = false, bool SP2 = false>
; __device__ __forceinline__ void gemm_phase(PG8_LAS unsigned char* lds, const Gemm g, const Sched& S, const Epi& E) {
;     ...
;             PG8_LDB(B0, 0, 0); PG8_LDB(B1, 0, 1); PG8_SCHED; PG8_LDA(At, 0, 0); PG8_STAGE(PG8_SA(1, 1), a1 + hstepA, voffA);
;             PG8_WAIT_V(8); PG8_WAIT_L(0); PG8_BAR; PG8_MMA(0, 0, At, B0); PG8_MMA(0, 1, At, B1); PG8_BAR; PG8_SCHED;
;             PG8_LDA(At, 0, 1); PG8_STAGE(PG8_SB(0, 0), b2, voffB); PG8_STAGE(PG8_SB(0, 1), b2 + hstepB, voffB); PG8_STAGE(PG8_SA(0, 0), a2, voffA);
;             PG8_WAIT_V(8); PG8_WAIT_L(0); PG8_BAR; PG8_MMA(1, 0, At, B0); PG8_MMA(1, 1, At, B1); PG8_BAR; PG8_SCHED;
;             PG8_LDB(B0, 1, 0); PG8_LDB(B1, 1, 1); PG8_SCHED; PG8_LDA(At, 1, 0); PG8_STAGE(PG8_SA(0, 1), a2 + hstepA, voffA);
;             PG8_WAIT_V(8); PG8_WAIT_L(0); PG8_BAR; PG8_MMA(0, 0, At, B0); PG8_MMA(0, 1, At, B1); PG8_BAR; PG8_SCHED;
;             PG8_LDA(At, 1, 1); PG8_STAGE(PG8_SB(1, 0), b3, voffB); PG8_STAGE(PG8_SB(1, 1), b3 + hstepB, voffB); PG8_STAGE(PG8_SA(1, 0), a3, voffA);
;             PG8_WAIT_V(8); PG8_WAIT_L(0); PG8_BAR; PG8_MMA(1, 0, At, B0); PG8_MMA(1, 1, At, B1); PG8_BAR; PG8_SCHED;
.LBB0_780:
	ds_read_b128 v[148:151], v165
	ds_read_b128 v[152:155], v165 offset:1024
	ds_read_b128 v[156:159], v165 offset:2048
	ds_read_b128 v[170:173], v165 offset:3072
	ds_read_b128 v[174:177], v166
	ds_read_b128 v[178:181], v166 offset:1024
	ds_read_b128 v[182:185], v166 offset:2048
	ds_read_b128 v[186:189], v166 offset:3072
	s_add_u32 s0, s6, 0x100
	s_addc_u32 s1, s7, 0
	s_cmp_eq_u32 s66, 2
	s_cselect_b32 s29, s25, s1
	s_cselect_b32 s28, s24, s0
	s_cselect_b32 s9, s27, s65
	s_cselect_b32 s8, s26, s64
	v_lshl_add_u64 v[222:223], s[6:7], 0, v[140:141]
	s_add_i32 m0, s36, 0xc000
	ds_read_b128 v[190:193], v167
	ds_read_b128 v[194:197], v167 offset:1024
	ds_read_b128 v[198:201], v167 offset:2048
	ds_read_b128 v[202:205], v167 offset:3072
	ds_read_b128 v[206:209], v167 offset:4096
	ds_read_b128 v[210:213], v167 offset:5120
	ds_read_b128 v[214:217], v167 offset:6144
	ds_read_b128 v[218:221], v167 offset:7168
	global_load_lds_dwordx4 v[222:223], off
	v_lshl_add_u64 v[222:223], s[6:7], 0, v[142:143]
	s_add_i32 m0, s36, 0xe000
	s_nop 0
	global_load_lds_dwordx4 v[222:223], off
	s_waitcnt vmcnt(8)
	s_waitcnt lgkmcnt(0)
	s_barrier
	s_setprio 1
	s_waitcnt lgkmcnt(0)
	v_mfma_f32_16x16x32_bf16 v[126:129], v[148:151], v[190:193], v[126:129]
	v_mfma_f32_16x16x32_bf16 v[122:125], v[156:159], v[190:193], v[122:125]
	v_mfma_f32_16x16x32_bf16 v[110:113], v[148:151], v[198:201], v[110:113]
	v_mfma_f32_16x16x32_bf16 v[106:109], v[156:159], v[198:201], v[106:109]
	v_mfma_f32_16x16x32_bf16 v[94:97], v[148:151], v[206:209], v[94:97]
	v_mfma_f32_16x16x32_bf16 v[90:93], v[156:159], v[206:209], v[90:93]
	v_mfma_f32_16x16x32_bf16 v[78:81], v[148:151], v[214:217], v[78:81]
	v_mfma_f32_16x16x32_bf16 v[74:77], v[156:159], v[214:217], v[74:77]
	v_mfma_f32_16x16x32_bf16 v[126:129], v[152:155], v[194:197], v[126:129]
	v_mfma_f32_16x16x32_bf16 v[122:125], v[170:173], v[194:197], v[122:125]
	v_mfma_f32_16x16x32_bf16 v[110:113], v[152:155], v[202:205], v[110:113]
	v_mfma_f32_16x16x32_bf16 v[106:109], v[170:173], v[202:205], v[106:109]
	v_mfma_f32_16x16x32_bf16 v[94:97], v[152:155], v[210:213], v[94:97]
	v_mfma_f32_16x16x32_bf16 v[90:93], v[170:173], v[210:213], v[90:93]
	v_mfma_f32_16x16x32_bf16 v[78:81], v[152:155], v[218:221], v[78:81]
	v_mfma_f32_16x16x32_bf16 v[74:77], v[170:173], v[218:221], v[74:77]
	s_setprio 0
	s_setprio 1
	v_mfma_f32_16x16x32_bf16 v[118:121], v[174:177], v[190:193], v[118:121]
	v_mfma_f32_16x16x32_bf16 v[114:117], v[182:185], v[190:193], v[114:117]
	v_mfma_f32_16x16x32_bf16 v[102:105], v[174:177], v[198:201], v[102:105]
	v_mfma_f32_16x16x32_bf16 v[98:101], v[182:185], v[198:201], v[98:101]
	v_mfma_f32_16x16x32_bf16 v[86:89], v[174:177], v[206:209], v[86:89]
	v_mfma_f32_16x16x32_bf16 v[82:85], v[182:185], v[206:209], v[82:85]
	v_mfma_f32_16x16x32_bf16 v[70:73], v[174:177], v[214:217], v[70:73]
	v_mfma_f32_16x16x32_bf16 v[66:69], v[182:185], v[214:217], v[66:69]
	v_mfma_f32_16x16x32_bf16 v[118:121], v[178:181], v[194:197], v[118:121]
	v_mfma_f32_16x16x32_bf16 v[114:117], v[186:189], v[194:197], v[114:117]
	v_mfma_f32_16x16x32_bf16 v[102:105], v[178:181], v[202:205], v[102:105]
	v_mfma_f32_16x16x32_bf16 v[98:101], v[186:189], v[202:205], v[98:101]
	v_mfma_f32_16x16x32_bf16 v[86:89], v[178:181], v[210:213], v[86:89]
	v_mfma_f32_16x16x32_bf16 v[82:85], v[186:189], v[210:213], v[82:85]
	v_mfma_f32_16x16x32_bf16 v[70:73], v[178:181], v[218:221], v[70:73]
	v_mfma_f32_16x16x32_bf16 v[66:69], v[186:189], v[218:221], v[66:69]
	s_setprio 0
	s_barrier
	s_add_i32 s6, s48, s35
	s_add_u32 s98, s8, 0x80
	s_addc_u32 s99, s9, 0
	s_mov_b32 m0, s6
	ds_read_b128 v[190:193], v167 offset:16384
	ds_read_b128 v[194:197], v167 offset:17408
	ds_read_b128 v[198:201], v167 offset:18432
	ds_read_b128 v[202:205], v167 offset:19456
	ds_read_b128 v[206:209], v167 offset:20480
	ds_read_b128 v[210:213], v167 offset:21504
	ds_read_b128 v[214:217], v167 offset:22528
	ds_read_b128 v[218:221], v167 offset:23552
	global_load_lds_dwordx4 v132, s[8:9]
	s_add_i32 m0, s6, 0x2000
	s_add_u32 s6, s8, 0x18000
	s_addc_u32 s7, s9, 0
	s_add_i32 s67, s49, s35
	global_load_lds_dwordx4 v136, s[8:9]
	s_mov_b32 m0, s67
	s_nop 0
	global_load_lds_dwordx4 v132, s[6:7]
	s_add_i32 m0, s67, 0x2000
	s_nop 0
	global_load_lds_dwordx4 v136, s[6:7]
	s_add_u32 s100, s28, 0x80
	s_addc_u32 s101, s29, 0
	s_mov_b32 m0, s36
	s_nop 0
	global_load_lds_dwordx4 v130, s[28:29]
	s_mov_b32 m0, s37
	s_nop 0
	global_load_lds_dwordx4 v134, s[28:29]
	s_waitcnt vmcnt(8)
	s_waitcnt lgkmcnt(0)
	s_barrier
	s_setprio 1
	s_waitcnt lgkmcnt(0)
	v_mfma_f32_16x16x32_bf16 v[62:65], v[148:151], v[190:193], v[62:65]
	v_mfma_f32_16x16x32_bf16 v[58:61], v[156:159], v[190:193], v[58:61]
	v_mfma_f32_16x16x32_bf16 v[46:49], v[148:151], v[198:201], v[46:49]
	v_mfma_f32_16x16x32_bf16 v[42:45], v[156:159], v[198:201], v[42:45]
	v_mfma_f32_16x16x32_bf16 v[30:33], v[148:151], v[206:209], v[30:33]
	v_mfma_f32_16x16x32_bf16 v[26:29], v[156:159], v[206:209], v[26:29]
	v_mfma_f32_16x16x32_bf16 v[14:17], v[148:151], v[214:217], v[14:17]
	v_mfma_f32_16x16x32_bf16 v[10:13], v[156:159], v[214:217], v[10:13]
	v_mfma_f32_16x16x32_bf16 v[62:65], v[152:155], v[194:197], v[62:65]
	v_mfma_f32_16x16x32_bf16 v[58:61], v[170:173], v[194:197], v[58:61]
	v_mfma_f32_16x16x32_bf16 v[46:49], v[152:155], v[202:205], v[46:49]
	v_mfma_f32_16x16x32_bf16 v[42:45], v[170:173], v[202:205], v[42:45]
	v_mfma_f32_16x16x32_bf16 v[30:33], v[152:155], v[210:213], v[30:33]
	v_mfma_f32_16x16x32_bf16 v[26:29], v[170:173], v[210:213], v[26:29]
	v_mfma_f32_16x16x32_bf16 v[14:17], v[152:155], v[218:221], v[14:17]
	v_mfma_f32_16x16x32_bf16 v[10:13], v[170:173], v[218:221], v[10:13]
	s_setprio 0
	s_setprio 1
	v_mfma_f32_16x16x32_bf16 v[54:57], v[174:177], v[190:193], v[54:57]
	v_mfma_f32_16x16x32_bf16 v[50:53], v[182:185], v[190:193], v[50:53]
	v_mfma_f32_16x16x32_bf16 v[38:41], v[174:177], v[198:201], v[38:41]
	v_mfma_f32_16x16x32_bf16 v[34:37], v[182:185], v[198:201], v[34:37]
	v_mfma_f32_16x16x32_bf16 v[22:25], v[174:177], v[206:209], v[22:25]
	v_mfma_f32_16x16x32_bf16 v[18:21], v[182:185], v[206:209], v[18:21]
	v_mfma_f32_16x16x32_bf16 v[6:9], v[174:177], v[214:217], v[6:9]
	v_mfma_f32_16x16x32_bf16 v[2:5], v[182:185], v[214:217], v[2:5]
	v_mfma_f32_16x16x32_bf16 v[54:57], v[178:181], v[194:197], v[54:57]
	v_mfma_f32_16x16x32_bf16 v[50:53], v[186:189], v[194:197], v[50:53]
	v_mfma_f32_16x16x32_bf16 v[38:41], v[178:181], v[202:205], v[38:41]
	v_mfma_f32_16x16x32_bf16 v[34:37], v[186:189], v[202:205], v[34:37]
	v_mfma_f32_16x16x32_bf16 v[22:25], v[178:181], v[210:213], v[22:25]
	v_mfma_f32_16x16x32_bf16 v[18:21], v[186:189], v[210:213], v[18:21]
	v_mfma_f32_16x16x32_bf16 v[6:9], v[178:181], v[218:221], v[6:9]
	v_mfma_f32_16x16x32_bf16 v[2:5], v[186:189], v[218:221], v[2:5]
	s_setprio 0
	s_barrier
; #define PG8_STAGE(bufoff, gbase, voff) do { _Pragma("unroll") for (int _i = 0; _i < 2; ++_i) \
;         __builtin_amdgcn_global_load_lds((const unsigned*)((const char*)(gbase) + (voff)[_i]), (PG8_LAS unsigned*)(lds + (bufoff) + ldsw + _i * 8192), 16, 0, 0); } while (0)
; #define PG8_LDA(dst, b, h) do { _Pragma("unroll") for (int m = 0; m < 4; ++m) _Pragma("unroll") for (int k = 0; k < 2; ++k) dst[m][k] = *(const PG8_LAS bf16x8*)(lds + PG8_SA(b, h) + aoff + m * 2048 + k * 1024); } while (0)
; #define PG8_LDB(dst, b, h) do { _Pragma("unroll") for (int n = 0; n < 2; ++n) _Pragma("unroll") for (int k = 0; k < 2; ++k) dst[n][k] = *(const PG8_LAS bf16x8*)(lds + PG8_SB(b, h) + boff + n * 2048 + k * 1024); } while (0)
; #define PG8_MMA(ai, bj, At, Bt) do { __builtin_amdgcn_s_setprio(1); _Pragma("unroll") for (int m = 0; m < 4; ++m) _Pragma("unroll") for (int n = 0; n < 2; ++n) _Pragma("unroll") for (int k = 0; k < 2; ++k) \
;         acc[ai][bj][m][n] = __builtin_amdgcn_mfma_f32_16x16x32_bf16(Bt[n][k], At[m][k], acc[ai][bj][m][n], 0, 0, 0); __builtin_amdgcn_s_setprio(0); } while (0)
; #define PG8_WAIT_V(n) asm volatile("s_waitcnt vmcnt(" #n ")" ::: "memory")
; template <class Epi, class Sched, bool ALIGN_EPI = false, bool SP2 = false>
; __device__ __forceinline__ void gemm_phase(PG8_LAS unsigned char* lds, const Gemm g, const Sched& S, const Epi& E) {
;     ...
;             PG8_LDB(B0, 0, 0); PG8_LDB(B1, 0, 1); PG8_SCHED; PG8_LDA(At, 0, 0); PG8_STAGE(PG8_SA(1, 1), a1 + hstepA, voffA);
;             PG8_WAIT_V(8); PG8_WAIT_L(0); PG8_BAR; PG8_MMA(0, 0, At, B0); PG8_MMA(0, 1, At, B1); PG8_BAR; PG8_SCHED;
;             PG8_LDA(At, 0, 1); PG8_STAGE(PG8_SB(0, 0), b2, voffB); PG8_STAGE(PG8_SB(0, 1), b2 + hstepB, voffB); PG8_STAGE(PG8_SA(0, 0), a2, voffA);
;             PG8_WAIT_V(8); PG8_WAIT_L(0); PG8_BAR; PG8_MMA(1, 0, At, B0); PG8_MMA(1, 1, At, B1); PG8_BAR; PG8_SCHED;
;             PG8_LDB(B0, 1, 0); PG8_LDB(B1, 1, 1); PG8_SCHED; PG8_LDA(At, 1, 0); PG8_STAGE(PG8_SA(0, 1), a2 + hstepA, voffA);
;             PG8_WAIT_V(8); PG8_WAIT_L(0); PG8_BAR; PG8_MMA(0, 0, At, B0); PG8_MMA(0, 1, At, B1); PG8_BAR; PG8_SCHED;
;             PG8_LDA(At, 1, 1); PG8_STAGE(PG8_SB(1, 0), b3, voffB); PG8_STAGE(PG8_SB(1, 1), b3 + hstepB, voffB); PG8_STAGE(PG8_SA(1, 0), a3, voffA);
;             PG8_WAIT_V(8); PG8_WAIT_L(0); PG8_BAR; PG8_MMA(1, 0, At, B0); PG8_MMA(1, 1, At, B1); PG8_BAR; PG8_SCHED;
	s_add_i32 s67, 0, 0x18000
	v_add_u32_e32 v138, s67, v160
	s_add_i32 s68, 0, 0x1c000
	ds_read_b128 v[148:151], v138
	ds_read_b128 v[152:155], v138 offset:1024
	ds_read_b128 v[156:159], v138 offset:2048
	ds_read_b128 v[170:173], v138 offset:3072
	v_add_u32_e32 v138, s68, v160
	ds_read_b128 v[174:177], v138
	ds_read_b128 v[178:181], v138 offset:1024
	ds_read_b128 v[182:185], v138 offset:2048
	ds_read_b128 v[186:189], v138 offset:3072
	s_add_u32 s6, s28, 0x2a000
	s_addc_u32 s7, s29, 0
	s_mov_b32 m0, s38
	ds_read_b128 v[190:193], v167 offset:32768
	ds_read_b128 v[194:197], v167 offset:33792
	ds_read_b128 v[198:201], v167 offset:34816
	ds_read_b128 v[202:205], v167 offset:35840
	ds_read_b128 v[206:209], v167 offset:36864
	ds_read_b128 v[210:213], v167 offset:37888
	ds_read_b128 v[214:217], v167 offset:38912
	ds_read_b128 v[218:221], v167 offset:39936
	global_load_lds_dwordx4 v130, s[6:7]
	s_mov_b32 m0, s39
	s_nop 0
	global_load_lds_dwordx4 v134, s[6:7]
	s_waitcnt vmcnt(8)
	s_waitcnt lgkmcnt(0)
	s_barrier
	s_setprio 1
	s_waitcnt lgkmcnt(0)
	v_mfma_f32_16x16x32_bf16 v[126:129], v[148:151], v[190:193], v[126:129]
	v_mfma_f32_16x16x32_bf16 v[122:125], v[156:159], v[190:193], v[122:125]
	v_mfma_f32_16x16x32_bf16 v[110:113], v[148:151], v[198:201], v[110:113]
	v_mfma_f32_16x16x32_bf16 v[106:109], v[156:159], v[198:201], v[106:109]
	v_mfma_f32_16x16x32_bf16 v[94:97], v[148:151], v[206:209], v[94:97]
	v_mfma_f32_16x16x32_bf16 v[90:93], v[156:159], v[206:209], v[90:93]
	v_mfma_f32_16x16x32_bf16 v[78:81], v[148:151], v[214:217], v[78:81]
	v_mfma_f32_16x16x32_bf16 v[74:77], v[156:159], v[214:217], v[74:77]
	v_mfma_f32_16x16x32_bf16 v[126:129], v[152:155], v[194:197], v[126:129]
	v_mfma_f32_16x16x32_bf16 v[122:125], v[170:173], v[194:197], v[122:125]
	v_mfma_f32_16x16x32_bf16 v[110:113], v[152:155], v[202:205], v[110:113]
	v_mfma_f32_16x16x32_bf16 v[106:109], v[170:173], v[202:205], v[106:109]
	v_mfma_f32_16x16x32_bf16 v[94:97], v[152:155], v[210:213], v[94:97]
	v_mfma_f32_16x16x32_bf16 v[90:93], v[170:173], v[210:213], v[90:93]
	v_mfma_f32_16x16x32_bf16 v[78:81], v[152:155], v[218:221], v[78:81]
	v_mfma_f32_16x16x32_bf16 v[74:77], v[170:173], v[218:221], v[74:77]
	s_setprio 0
	s_setprio 1
	v_mfma_f32_16x16x32_bf16 v[118:121], v[174:177], v[190:193], v[118:121]
	v_mfma_f32_16x16x32_bf16 v[114:117], v[182:185], v[190:193], v[114:117]
	v_mfma_f32_16x16x32_bf16 v[102:105], v[174:177], v[198:201], v[102:105]
	v_mfma_f32_16x16x32_bf16 v[98:101], v[182:185], v[198:201], v[98:101]
	v_mfma_f32_16x16x32_bf16 v[86:89], v[174:177], v[206:209], v[86:89]
	v_mfma_f32_16x16x32_bf16 v[82:85], v[182:185], v[206:209], v[82:85]
	v_mfma_f32_16x16x32_bf16 v[70:73], v[174:177], v[214:217], v[70:73]
	v_mfma_f32_16x16x32_bf16 v[66:69], v[182:185], v[214:217], v[66:69]
	v_mfma_f32_16x16x32_bf16 v[118:121], v[178:181], v[194:197], v[118:121]
	v_mfma_f32_16x16x32_bf16 v[114:117], v[186:189], v[194:197], v[114:117]
	v_mfma_f32_16x16x32_bf16 v[102:105], v[178:181], v[202:205], v[102:105]
	v_mfma_f32_16x16x32_bf16 v[98:101], v[186:189], v[202:205], v[98:101]
	v_mfma_f32_16x16x32_bf16 v[86:89], v[178:181], v[210:213], v[86:89]
	v_mfma_f32_16x16x32_bf16 v[82:85], v[186:189], v[210:213], v[82:85]
	v_mfma_f32_16x16x32_bf16 v[70:73], v[178:181], v[218:221], v[70:73]
	v_mfma_f32_16x16x32_bf16 v[66:69], v[186:189], v[218:221], v[66:69]
	s_setprio 0
	s_barrier
	s_add_i32 s6, s67, s35
	s_mov_b32 m0, s6
	ds_read_b128 v[190:193], v167 offset:49152
	ds_read_b128 v[194:197], v167 offset:50176
	ds_read_b128 v[198:201], v167 offset:51200
	ds_read_b128 v[202:205], v167 offset:52224
	ds_read_b128 v[206:209], v167 offset:53248
	ds_read_b128 v[210:213], v167 offset:54272
	ds_read_b128 v[214:217], v167 offset:55296
	ds_read_b128 v[218:221], v167 offset:56320
	global_load_lds_dwordx4 v132, s[98:99]
	s_add_i32 m0, s6, 0x2000
	s_add_u32 s6, s8, 0x18080
	s_addc_u32 s7, s9, 0
	s_add_i32 s8, s68, s35
	global_load_lds_dwordx4 v136, s[98:99]
	s_mov_b32 m0, s8
	s_nop 0
	global_load_lds_dwordx4 v132, s[6:7]
	s_add_i32 m0, s8, 0x2000
	s_nop 0
	global_load_lds_dwordx4 v136, s[6:7]
	s_mov_b32 m0, s45
	s_nop 0
	global_load_lds_dwordx4 v130, s[100:101]
	s_mov_b32 m0, s46
	s_nop 0
	global_load_lds_dwordx4 v134, s[100:101]
	s_waitcnt vmcnt(8)
	s_waitcnt lgkmcnt(0)
	s_barrier
	s_setprio 1
	s_waitcnt lgkmcnt(0)
	v_mfma_f32_16x16x32_bf16 v[62:65], v[148:151], v[190:193], v[62:65]
	v_mfma_f32_16x16x32_bf16 v[58:61], v[156:159], v[190:193], v[58:61]
	v_mfma_f32_16x16x32_bf16 v[46:49], v[148:151], v[198:201], v[46:49]
	v_mfma_f32_16x16x32_bf16 v[42:45], v[156:159], v[198:201], v[42:45]
	v_mfma_f32_16x16x32_bf16 v[30:33], v[148:151], v[206:209], v[30:33]
	v_mfma_f32_16x16x32_bf16 v[26:29], v[156:159], v[206:209], v[26:29]
	v_mfma_f32_16x16x32_bf16 v[14:17], v[148:151], v[214:217], v[14:17]
	v_mfma_f32_16x16x32_bf16 v[10:13], v[156:159], v[214:217], v[10:13]
	v_mfma_f32_16x16x32_bf16 v[62:65], v[152:155], v[194:197], v[62:65]
	v_mfma_f32_16x16x32_bf16 v[58:61], v[170:173], v[194:197], v[58:61]
	v_mfma_f32_16x16x32_bf16 v[46:49], v[152:155], v[202:205], v[46:49]
	v_mfma_f32_16x16x32_bf16 v[42:45], v[170:173], v[202:205], v[42:45]
	v_mfma_f32_16x16x32_bf16 v[30:33], v[152:155], v[210:213], v[30:33]
	v_mfma_f32_16x16x32_bf16 v[26:29], v[170:173], v[210:213], v[26:29]
	v_mfma_f32_16x16x32_bf16 v[14:17], v[152:155], v[218:221], v[14:17]
	v_mfma_f32_16x16x32_bf16 v[10:13], v[170:173], v[218:221], v[10:13]
	s_setprio 0
	s_setprio 1
	v_mfma_f32_16x16x32_bf16 v[54:57], v[174:177], v[190:193], v[54:57]
	v_mfma_f32_16x16x32_bf16 v[50:53], v[182:185], v[190:193], v[50:53]
	v_mfma_f32_16x16x32_bf16 v[38:41], v[174:177], v[198:201], v[38:41]
	v_mfma_f32_16x16x32_bf16 v[34:37], v[182:185], v[198:201], v[34:37]
	v_mfma_f32_16x16x32_bf16 v[22:25], v[174:177], v[206:209], v[22:25]
	v_mfma_f32_16x16x32_bf16 v[18:21], v[182:185], v[206:209], v[18:21]
	v_mfma_f32_16x16x32_bf16 v[6:9], v[174:177], v[214:217], v[6:9]
	v_mfma_f32_16x16x32_bf16 v[2:5], v[182:185], v[214:217], v[2:5]
	v_mfma_f32_16x16x32_bf16 v[54:57], v[178:181], v[194:197], v[54:57]
	v_mfma_f32_16x16x32_bf16 v[50:53], v[186:189], v[194:197], v[50:53]
	v_mfma_f32_16x16x32_bf16 v[38:41], v[178:181], v[202:205], v[38:41]
	v_mfma_f32_16x16x32_bf16 v[34:37], v[186:189], v[202:205], v[34:37]
	v_mfma_f32_16x16x32_bf16 v[22:25], v[178:181], v[210:213], v[22:25]
	v_mfma_f32_16x16x32_bf16 v[18:21], v[186:189], v[210:213], v[18:21]
	v_mfma_f32_16x16x32_bf16 v[6:9], v[178:181], v[218:221], v[6:9]
	v_mfma_f32_16x16x32_bf16 v[2:5], v[186:189], v[218:221], v[2:5]
	s_setprio 0
	s_barrier
	s_add_i32 s66, s66, 2
	s_add_u32 s64, s64, 0x100
	s_addc_u32 s65, s65, 0
	s_cmp_gt_u32 s66, 3
	s_mov_b64 s[6:7], s[0:1]
	s_cbranch_scc0 .LBB0_780
	s_and_b64 vcc, exec, s[20:21]
	s_cbranch_vccz .LBB0_783
	s_barrier

; #define PG8_STAGE(bufoff, gbase, voff) do { _Pragma("unroll") for (int _i = 0; _i < 2; ++_i) \
;         __builtin_amdgcn_global_load_lds((const unsigned*)((const char*)(gbase) + (voff)[_i]), (PG8_LAS unsigned*)(lds + (bufoff) + ldsw + _i * 8192), 16, 0, 0); } while (0)
; #define PG8_LDA(dst, b, h) do { _Pragma("unroll") for (int m = 0; m < 4; ++m) _Pragma("unroll") for (int k = 0; k < 2; ++k) dst[m][k] = *(const PG8_LAS bf16x8*)(lds + PG8_SA(b, h) + aoff + m * 2048 + k * 1024); } while (0)
; #define PG8_LDB(dst, b, h) do { _Pragma("unroll") for (int n = 0; n < 2; ++n) _Pragma("unroll") for (int k = 0; k < 2; ++k) dst[n][k] = *(const PG8_LAS bf16x8*)(lds + PG8_SB(b, h) + boff + n * 2048 + k * 1024); } while (0)
; #define PG8_MMA(ai, bj, At, Bt) do { __builtin_amdgcn_s_setprio(1); _Pragma("unroll") for (int m = 0; m < 4; ++m) _Pragma("unroll") for (int n = 0; n < 2; ++n) _Pragma("unroll") for (int k = 0; k < 2; ++k) \
;         acc[ai][bj][m][n] = __builtin_amdgcn_mfma_f32_16x16x32_bf16(Bt[n][k], At[m][k], acc[ai][bj][m][n], 0, 0, 0); __builtin_amdgcn_s_setprio(0); } while (0)
; #define PG8_WAIT_V(n) asm volatile("s_waitcnt vmcnt(" #n ")" ::: "memory")
; template <class Epi, class Sched, bool ALIGN_EPI = false, bool SP2 = false>
; __device__ __forceinline__ void gemm_phase(PG8_LAS unsigned char* lds, const Gemm g, const Sched& S, const Epi& E) {
;     ...
;             PG8_LDB(B0, 0, 0); PG8_LDB(B1, 0, 1); PG8_SCHED; PG8_LDA(At, 0, 0); PG8_STAGE(PG8_SA(1, 1), a1 + hstepA, voffA);
;             PG8_WAIT_V(8); PG8_WAIT_L(0); PG8_BAR; PG8_MMA(0, 0, At, B0); PG8_MMA(0, 1, At, B1); PG8_BAR; PG8_SCHED;
;             PG8_LDA(At, 0, 1); PG8_STAGE(PG8_SB(0, 0), b2, voffB); PG8_STAGE(PG8_SB(0, 1), b2 + hstepB, voffB); PG8_STAGE(PG8_SA(0, 0), a2, voffA);
;             PG8_WAIT_V(8); PG8_WAIT_L(0); PG8_BAR; PG8_MMA(1, 0, At, B0); PG8_MMA(1, 1, At, B1); PG8_BAR; PG8_SCHED;
;             PG8_LDB(B0, 1, 0); PG8_LDB(B1, 1, 1); PG8_SCHED; PG8_LDA(At, 1, 0); PG8_STAGE(PG8_SA(0, 1), a2 + hstepA, voffA);
;             PG8_WAIT_V(8); PG8_WAIT_L(0); PG8_BAR; PG8_MMA(0, 0, At, B0); PG8_MMA(0, 1, At, B1); PG8_BAR; PG8_SCHED;
;             PG8_LDA(At, 1, 1); PG8_STAGE(PG8_SB(1, 0), b3, voffB); PG8_STAGE(PG8_SB(1, 1), b3 + hstepB, voffB); PG8_STAGE(PG8_SA(1, 0), a3, voffA);
;             PG8_WAIT_V(8); PG8_WAIT_L(0); PG8_BAR; PG8_MMA(1, 0, At, B0); PG8_MMA(1, 1, At, B1); PG8_BAR; PG8_SCHED;
.LBB0_1086:
	ds_read_b128 v[130:133], v168
	ds_read_b128 v[134:137], v168 offset:1024
	ds_read_b128 v[138:141], v168 offset:2048
	ds_read_b128 v[158:161], v168 offset:3072
	ds_read_b128 v[162:165], v169
	ds_read_b128 v[172:175], v169 offset:1024
	ds_read_b128 v[176:179], v169 offset:2048
	ds_read_b128 v[180:183], v169 offset:3072
	s_add_u32 s26, s24, 0xfffe0080
	s_addc_u32 s27, s25, -1
	s_cmp_eq_u32 s49, 4
	s_cselect_b32 s29, s17, s27
	s_cselect_b32 s28, s45, s26
	s_cselect_b32 s27, s15, s48
	s_cselect_b32 s26, s46, s47
	s_add_i32 m0, s23, 0xc000
	ds_read_b128 v[184:187], v170
	ds_read_b128 v[188:191], v170 offset:1024
	ds_read_b128 v[192:195], v170 offset:2048
	ds_read_b128 v[196:199], v170 offset:3072
	ds_read_b128 v[200:203], v170 offset:4096
	ds_read_b128 v[204:207], v170 offset:5120
	ds_read_b128 v[208:211], v170 offset:6144
	ds_read_b128 v[212:215], v170 offset:7168
	global_load_lds_dwordx4 v150, s[24:25]
	s_add_i32 m0, s23, 0xe000
	s_nop 0
	global_load_lds_dwordx4 v152, s[24:25]
	s_waitcnt vmcnt(8)
	s_waitcnt lgkmcnt(0)
	s_barrier
	s_setprio 1
	s_waitcnt lgkmcnt(0)
	v_mfma_f32_16x16x32_bf16 v[126:129], v[130:133], v[184:187], v[126:129]
	v_mfma_f32_16x16x32_bf16 v[122:125], v[138:141], v[184:187], v[122:125]
	v_mfma_f32_16x16x32_bf16 v[110:113], v[130:133], v[192:195], v[110:113]
	v_mfma_f32_16x16x32_bf16 v[106:109], v[138:141], v[192:195], v[106:109]
	v_mfma_f32_16x16x32_bf16 v[94:97], v[130:133], v[200:203], v[94:97]
	v_mfma_f32_16x16x32_bf16 v[90:93], v[138:141], v[200:203], v[90:93]
	v_mfma_f32_16x16x32_bf16 v[78:81], v[130:133], v[208:211], v[78:81]
	v_mfma_f32_16x16x32_bf16 v[74:77], v[138:141], v[208:211], v[74:77]
	v_mfma_f32_16x16x32_bf16 v[126:129], v[134:137], v[188:191], v[126:129]
	v_mfma_f32_16x16x32_bf16 v[122:125], v[158:161], v[188:191], v[122:125]
	v_mfma_f32_16x16x32_bf16 v[110:113], v[134:137], v[196:199], v[110:113]
	v_mfma_f32_16x16x32_bf16 v[106:109], v[158:161], v[196:199], v[106:109]
	v_mfma_f32_16x16x32_bf16 v[94:97], v[134:137], v[204:207], v[94:97]
	v_mfma_f32_16x16x32_bf16 v[90:93], v[158:161], v[204:207], v[90:93]
	v_mfma_f32_16x16x32_bf16 v[78:81], v[134:137], v[212:215], v[78:81]
	v_mfma_f32_16x16x32_bf16 v[74:77], v[158:161], v[212:215], v[74:77]
	s_setprio 0
	s_setprio 1
	v_mfma_f32_16x16x32_bf16 v[118:121], v[162:165], v[184:187], v[118:121]
	v_mfma_f32_16x16x32_bf16 v[114:117], v[176:179], v[184:187], v[114:117]
	v_mfma_f32_16x16x32_bf16 v[102:105], v[162:165], v[192:195], v[102:105]
	v_mfma_f32_16x16x32_bf16 v[98:101], v[176:179], v[192:195], v[98:101]
	v_mfma_f32_16x16x32_bf16 v[86:89], v[162:165], v[200:203], v[86:89]
	v_mfma_f32_16x16x32_bf16 v[82:85], v[176:179], v[200:203], v[82:85]
	v_mfma_f32_16x16x32_bf16 v[70:73], v[162:165], v[208:211], v[70:73]
	v_mfma_f32_16x16x32_bf16 v[66:69], v[176:179], v[208:211], v[66:69]
	v_mfma_f32_16x16x32_bf16 v[118:121], v[172:175], v[188:191], v[118:121]
	v_mfma_f32_16x16x32_bf16 v[114:117], v[180:183], v[188:191], v[114:117]
	v_mfma_f32_16x16x32_bf16 v[102:105], v[172:175], v[196:199], v[102:105]
	v_mfma_f32_16x16x32_bf16 v[98:101], v[180:183], v[196:199], v[98:101]
	v_mfma_f32_16x16x32_bf16 v[86:89], v[172:175], v[204:207], v[86:89]
	v_mfma_f32_16x16x32_bf16 v[82:85], v[180:183], v[204:207], v[82:85]
	v_mfma_f32_16x16x32_bf16 v[70:73], v[172:175], v[212:215], v[70:73]
	v_mfma_f32_16x16x32_bf16 v[66:69], v[180:183], v[212:215], v[66:69]
	s_setprio 0
	s_barrier
	s_add_i32 s50, s42, s34
	s_add_u32 s98, s26, 0x80
	s_addc_u32 s99, s27, 0
	s_mov_b32 m0, s50
	ds_read_b128 v[184:187], v170 offset:16384
	ds_read_b128 v[188:191], v170 offset:17408
	ds_read_b128 v[192:195], v170 offset:18432
	ds_read_b128 v[196:199], v170 offset:19456
	ds_read_b128 v[200:203], v170 offset:20480
	ds_read_b128 v[204:207], v170 offset:21504
	ds_read_b128 v[208:211], v170 offset:22528
	ds_read_b128 v[212:215], v170 offset:23552
	global_load_lds_dwordx4 v144, s[26:27]
	s_add_i32 m0, s50, 0x2000
	s_add_u32 s50, s26, 0x20000
	s_addc_u32 s51, s27, 0
	s_add_i32 s52, s43, s34
	global_load_lds_dwordx4 v148, s[26:27]
	s_mov_b32 m0, s52
	s_nop 0
	global_load_lds_dwordx4 v144, s[50:51]
	s_add_i32 m0, s52, 0x2000
	s_nop 0
	global_load_lds_dwordx4 v148, s[50:51]
	s_add_u32 s100, s28, 0x80
	s_addc_u32 s101, s29, 0
	s_mov_b32 m0, s23
	s_nop 0
	global_load_lds_dwordx4 v142, s[28:29]
	s_mov_b32 m0, s35
	s_nop 0
	global_load_lds_dwordx4 v146, s[28:29]
	s_waitcnt vmcnt(8)
	s_waitcnt lgkmcnt(0)
	s_barrier
	s_setprio 1
	s_waitcnt lgkmcnt(0)
	v_mfma_f32_16x16x32_bf16 v[62:65], v[130:133], v[184:187], v[62:65]
	v_mfma_f32_16x16x32_bf16 v[58:61], v[138:141], v[184:187], v[58:61]
	v_mfma_f32_16x16x32_bf16 v[46:49], v[130:133], v[192:195], v[46:49]
	v_mfma_f32_16x16x32_bf16 v[42:45], v[138:141], v[192:195], v[42:45]
	v_mfma_f32_16x16x32_bf16 v[30:33], v[130:133], v[200:203], v[30:33]
	v_mfma_f32_16x16x32_bf16 v[26:29], v[138:141], v[200:203], v[26:29]
	v_mfma_f32_16x16x32_bf16 v[14:17], v[130:133], v[208:211], v[14:17]
	v_mfma_f32_16x16x32_bf16 v[10:13], v[138:141], v[208:211], v[10:13]
	v_mfma_f32_16x16x32_bf16 v[62:65], v[134:137], v[188:191], v[62:65]
	v_mfma_f32_16x16x32_bf16 v[58:61], v[158:161], v[188:191], v[58:61]
	v_mfma_f32_16x16x32_bf16 v[46:49], v[134:137], v[196:199], v[46:49]
	v_mfma_f32_16x16x32_bf16 v[42:45], v[158:161], v[196:199], v[42:45]
	v_mfma_f32_16x16x32_bf16 v[30:33], v[134:137], v[204:207], v[30:33]
	v_mfma_f32_16x16x32_bf16 v[26:29], v[158:161], v[204:207], v[26:29]
	v_mfma_f32_16x16x32_bf16 v[14:17], v[134:137], v[212:215], v[14:17]
	v_mfma_f32_16x16x32_bf16 v[10:13], v[158:161], v[212:215], v[10:13]
	s_setprio 0
	s_setprio 1
	v_mfma_f32_16x16x32_bf16 v[54:57], v[162:165], v[184:187], v[54:57]
	v_mfma_f32_16x16x32_bf16 v[50:53], v[176:179], v[184:187], v[50:53]
	v_mfma_f32_16x16x32_bf16 v[38:41], v[162:165], v[192:195], v[38:41]
	v_mfma_f32_16x16x32_bf16 v[34:37], v[176:179], v[192:195], v[34:37]
	v_mfma_f32_16x16x32_bf16 v[22:25], v[162:165], v[200:203], v[22:25]
	v_mfma_f32_16x16x32_bf16 v[18:21], v[176:179], v[200:203], v[18:21]
	v_mfma_f32_16x16x32_bf16 v[6:9], v[162:165], v[208:211], v[6:9]
	v_mfma_f32_16x16x32_bf16 v[2:5], v[176:179], v[208:211], v[2:5]
	v_mfma_f32_16x16x32_bf16 v[54:57], v[172:175], v[188:191], v[54:57]
	v_mfma_f32_16x16x32_bf16 v[50:53], v[180:183], v[188:191], v[50:53]
	v_mfma_f32_16x16x32_bf16 v[38:41], v[172:175], v[196:199], v[38:41]
	v_mfma_f32_16x16x32_bf16 v[34:37], v[180:183], v[196:199], v[34:37]
	v_mfma_f32_16x16x32_bf16 v[22:25], v[172:175], v[204:207], v[22:25]
	v_mfma_f32_16x16x32_bf16 v[18:21], v[180:183], v[204:207], v[18:21]
	v_mfma_f32_16x16x32_bf16 v[6:9], v[172:175], v[212:215], v[6:9]
	v_mfma_f32_16x16x32_bf16 v[2:5], v[180:183], v[212:215], v[2:5]
	s_setprio 0
	s_barrier
; #define PG8_STAGE(bufoff, gbase, voff) do { _Pragma("unroll") for (int _i = 0; _i < 2; ++_i) \
;         __builtin_amdgcn_global_load_lds((const unsigned*)((const char*)(gbase) + (voff)[_i]), (PG8_LAS unsigned*)(lds + (bufoff) + ldsw + _i * 8192), 16, 0, 0); } while (0)
; #define PG8_LDA(dst, b, h) do { _Pragma("unroll") for (int m = 0; m < 4; ++m) _Pragma("unroll") for (int k = 0; k < 2; ++k) dst[m][k] = *(const PG8_LAS bf16x8*)(lds + PG8_SA(b, h) + aoff + m * 2048 + k * 1024); } while (0)
; #define PG8_LDB(dst, b, h) do { _Pragma("unroll") for (int n = 0; n < 2; ++n) _Pragma("unroll") for (int k = 0; k < 2; ++k) dst[n][k] = *(const PG8_LAS bf16x8*)(lds + PG8_SB(b, h) + boff + n * 2048 + k * 1024); } while (0)
; #define PG8_MMA(ai, bj, At, Bt) do { __builtin_amdgcn_s_setprio(1); _Pragma("unroll") for (int m = 0; m < 4; ++m) _Pragma("unroll") for (int n = 0; n < 2; ++n) _Pragma("unroll") for (int k = 0; k < 2; ++k) \
;         acc[ai][bj][m][n] = __builtin_amdgcn_mfma_f32_16x16x32_bf16(Bt[n][k], At[m][k], acc[ai][bj][m][n], 0, 0, 0); __builtin_amdgcn_s_setprio(0); } while (0)
; #define PG8_WAIT_V(n) asm volatile("s_waitcnt vmcnt(" #n ")" ::: "memory")
; template <class Epi, class Sched, bool ALIGN_EPI = false, bool SP2 = false>
; __device__ __forceinline__ void gemm_phase(PG8_LAS unsigned char* lds, const Gemm g, const Sched& S, const Epi& E) {
;     ...
;             PG8_LDB(B0, 0, 0); PG8_LDB(B1, 0, 1); PG8_SCHED; PG8_LDA(At, 0, 0); PG8_STAGE(PG8_SA(1, 1), a1 + hstepA, voffA);
;             PG8_WAIT_V(8); PG8_WAIT_L(0); PG8_BAR; PG8_MMA(0, 0, At, B0); PG8_MMA(0, 1, At, B1); PG8_BAR; PG8_SCHED;
;             PG8_LDA(At, 0, 1); PG8_STAGE(PG8_SB(0, 0), b2, voffB); PG8_STAGE(PG8_SB(0, 1), b2 + hstepB, voffB); PG8_STAGE(PG8_SA(0, 0), a2, voffA);
;             PG8_WAIT_V(8); PG8_WAIT_L(0); PG8_BAR; PG8_MMA(1, 0, At, B0); PG8_MMA(1, 1, At, B1); PG8_BAR; PG8_SCHED;
;             PG8_LDB(B0, 1, 0); PG8_LDB(B1, 1, 1); PG8_SCHED; PG8_LDA(At, 1, 0); PG8_STAGE(PG8_SA(0, 1), a2 + hstepA, voffA);
;             PG8_WAIT_V(8); PG8_WAIT_L(0); PG8_BAR; PG8_MMA(0, 0, At, B0); PG8_MMA(0, 1, At, B1); PG8_BAR; PG8_SCHED;
;             PG8_LDA(At, 1, 1); PG8_STAGE(PG8_SB(1, 0), b3, voffB); PG8_STAGE(PG8_SB(1, 1), b3 + hstepB, voffB); PG8_STAGE(PG8_SA(1, 0), a3, voffA);
;             PG8_WAIT_V(8); PG8_WAIT_L(0); PG8_BAR; PG8_MMA(1, 0, At, B0); PG8_MMA(1, 1, At, B1); PG8_BAR; PG8_SCHED;
	s_add_i32 s50, 0, 0x18000
	s_add_i32 s51, 0, 0x1c000
	v_add_u32_e32 v158, s50, v166
	v_add_u32_e32 v171, s51, v166
	ds_read_b128 v[130:133], v158
	ds_read_b128 v[134:137], v158 offset:1024
	ds_read_b128 v[138:141], v158 offset:2048
	ds_read_b128 v[158:161], v158 offset:3072
	ds_read_b128 v[162:165], v171
	ds_read_b128 v[172:175], v171 offset:1024
	ds_read_b128 v[176:179], v171 offset:2048
	ds_read_b128 v[180:183], v171 offset:3072
	s_add_u32 s28, s28, 0x20000
	s_addc_u32 s29, s29, 0
	s_mov_b32 m0, s36
	ds_read_b128 v[184:187], v170 offset:32768
	ds_read_b128 v[188:191], v170 offset:33792
	ds_read_b128 v[192:195], v170 offset:34816
	ds_read_b128 v[196:199], v170 offset:35840
	ds_read_b128 v[200:203], v170 offset:36864
	ds_read_b128 v[204:207], v170 offset:37888
	ds_read_b128 v[208:211], v170 offset:38912
	ds_read_b128 v[212:215], v170 offset:39936
	global_load_lds_dwordx4 v142, s[28:29]
	s_mov_b32 m0, s37
	s_nop 0
	global_load_lds_dwordx4 v146, s[28:29]
	s_waitcnt vmcnt(8)
	s_waitcnt lgkmcnt(0)
	s_barrier
	s_setprio 1
	s_waitcnt lgkmcnt(0)
	v_mfma_f32_16x16x32_bf16 v[126:129], v[130:133], v[184:187], v[126:129]
	v_mfma_f32_16x16x32_bf16 v[122:125], v[138:141], v[184:187], v[122:125]
	v_mfma_f32_16x16x32_bf16 v[110:113], v[130:133], v[192:195], v[110:113]
	v_mfma_f32_16x16x32_bf16 v[106:109], v[138:141], v[192:195], v[106:109]
	v_mfma_f32_16x16x32_bf16 v[94:97], v[130:133], v[200:203], v[94:97]
	v_mfma_f32_16x16x32_bf16 v[90:93], v[138:141], v[200:203], v[90:93]
	v_mfma_f32_16x16x32_bf16 v[78:81], v[130:133], v[208:211], v[78:81]
	v_mfma_f32_16x16x32_bf16 v[74:77], v[138:141], v[208:211], v[74:77]
	v_mfma_f32_16x16x32_bf16 v[126:129], v[134:137], v[188:191], v[126:129]
	v_mfma_f32_16x16x32_bf16 v[122:125], v[158:161], v[188:191], v[122:125]
	v_mfma_f32_16x16x32_bf16 v[110:113], v[134:137], v[196:199], v[110:113]
	v_mfma_f32_16x16x32_bf16 v[106:109], v[158:161], v[196:199], v[106:109]
	v_mfma_f32_16x16x32_bf16 v[94:97], v[134:137], v[204:207], v[94:97]
	v_mfma_f32_16x16x32_bf16 v[90:93], v[158:161], v[204:207], v[90:93]
	v_mfma_f32_16x16x32_bf16 v[78:81], v[134:137], v[212:215], v[78:81]
	v_mfma_f32_16x16x32_bf16 v[74:77], v[158:161], v[212:215], v[74:77]
	s_setprio 0
	s_setprio 1
	v_mfma_f32_16x16x32_bf16 v[118:121], v[162:165], v[184:187], v[118:121]
	v_mfma_f32_16x16x32_bf16 v[114:117], v[176:179], v[184:187], v[114:117]
	v_mfma_f32_16x16x32_bf16 v[102:105], v[162:165], v[192:195], v[102:105]
	v_mfma_f32_16x16x32_bf16 v[98:101], v[176:179], v[192:195], v[98:101]
	v_mfma_f32_16x16x32_bf16 v[86:89], v[162:165], v[200:203], v[86:89]
	v_mfma_f32_16x16x32_bf16 v[82:85], v[176:179], v[200:203], v[82:85]
	v_mfma_f32_16x16x32_bf16 v[70:73], v[162:165], v[208:211], v[70:73]
	v_mfma_f32_16x16x32_bf16 v[66:69], v[176:179], v[208:211], v[66:69]
	v_mfma_f32_16x16x32_bf16 v[118:121], v[172:175], v[188:191], v[118:121]
	v_mfma_f32_16x16x32_bf16 v[114:117], v[180:183], v[188:191], v[114:117]
	v_mfma_f32_16x16x32_bf16 v[102:105], v[172:175], v[196:199], v[102:105]
	v_mfma_f32_16x16x32_bf16 v[98:101], v[180:183], v[196:199], v[98:101]
	v_mfma_f32_16x16x32_bf16 v[86:89], v[172:175], v[204:207], v[86:89]
	v_mfma_f32_16x16x32_bf16 v[82:85], v[180:183], v[204:207], v[82:85]
	v_mfma_f32_16x16x32_bf16 v[70:73], v[172:175], v[212:215], v[70:73]
	v_mfma_f32_16x16x32_bf16 v[66:69], v[180:183], v[212:215], v[66:69]
	s_setprio 0
	s_barrier
	s_add_i32 s28, s50, s34
	s_mov_b32 m0, s28
	ds_read_b128 v[184:187], v170 offset:49152
	ds_read_b128 v[188:191], v170 offset:50176
	ds_read_b128 v[192:195], v170 offset:51200
	ds_read_b128 v[196:199], v170 offset:52224
	ds_read_b128 v[200:203], v170 offset:53248
	ds_read_b128 v[204:207], v170 offset:54272
	ds_read_b128 v[208:211], v170 offset:55296
	ds_read_b128 v[212:215], v170 offset:56320
	global_load_lds_dwordx4 v144, s[98:99]
	s_add_i32 m0, s28, 0x2000
	s_add_u32 s26, s26, 0x20080
	s_addc_u32 s27, s27, 0
	s_add_i32 s28, s51, s34
	global_load_lds_dwordx4 v148, s[98:99]
	s_mov_b32 m0, s28
	s_nop 0
	global_load_lds_dwordx4 v144, s[26:27]
	s_add_i32 m0, s28, 0x2000
	s_nop 0
	global_load_lds_dwordx4 v148, s[26:27]
	s_mov_b32 m0, s39
	s_nop 0
	global_load_lds_dwordx4 v142, s[100:101]
	s_mov_b32 m0, s40
	s_nop 0
	global_load_lds_dwordx4 v146, s[100:101]
	s_waitcnt vmcnt(8)
	s_waitcnt lgkmcnt(0)
	s_barrier
	s_setprio 1
	s_waitcnt lgkmcnt(0)
	v_mfma_f32_16x16x32_bf16 v[62:65], v[130:133], v[184:187], v[62:65]
	v_mfma_f32_16x16x32_bf16 v[58:61], v[138:141], v[184:187], v[58:61]
	v_mfma_f32_16x16x32_bf16 v[46:49], v[130:133], v[192:195], v[46:49]
	v_mfma_f32_16x16x32_bf16 v[42:45], v[138:141], v[192:195], v[42:45]
	v_mfma_f32_16x16x32_bf16 v[30:33], v[130:133], v[200:203], v[30:33]
	v_mfma_f32_16x16x32_bf16 v[26:29], v[138:141], v[200:203], v[26:29]
	v_mfma_f32_16x16x32_bf16 v[14:17], v[130:133], v[208:211], v[14:17]
	v_mfma_f32_16x16x32_bf16 v[10:13], v[138:141], v[208:211], v[10:13]
	v_mfma_f32_16x16x32_bf16 v[62:65], v[134:137], v[188:191], v[62:65]
	v_mfma_f32_16x16x32_bf16 v[58:61], v[158:161], v[188:191], v[58:61]
	v_mfma_f32_16x16x32_bf16 v[46:49], v[134:137], v[196:199], v[46:49]
	v_mfma_f32_16x16x32_bf16 v[42:45], v[158:161], v[196:199], v[42:45]
	v_mfma_f32_16x16x32_bf16 v[30:33], v[134:137], v[204:207], v[30:33]
	v_mfma_f32_16x16x32_bf16 v[26:29], v[158:161], v[204:207], v[26:29]
	v_mfma_f32_16x16x32_bf16 v[14:17], v[134:137], v[212:215], v[14:17]
	v_mfma_f32_16x16x32_bf16 v[10:13], v[158:161], v[212:215], v[10:13]
	s_setprio 0
	s_setprio 1
	v_mfma_f32_16x16x32_bf16 v[54:57], v[162:165], v[184:187], v[54:57]
	v_mfma_f32_16x16x32_bf16 v[50:53], v[176:179], v[184:187], v[50:53]
	v_mfma_f32_16x16x32_bf16 v[38:41], v[162:165], v[192:195], v[38:41]
	v_mfma_f32_16x16x32_bf16 v[34:37], v[176:179], v[192:195], v[34:37]
	v_mfma_f32_16x16x32_bf16 v[22:25], v[162:165], v[200:203], v[22:25]
	v_mfma_f32_16x16x32_bf16 v[18:21], v[176:179], v[200:203], v[18:21]
	v_mfma_f32_16x16x32_bf16 v[6:9], v[162:165], v[208:211], v[6:9]
	v_mfma_f32_16x16x32_bf16 v[2:5], v[176:179], v[208:211], v[2:5]
	v_mfma_f32_16x16x32_bf16 v[54:57], v[172:175], v[188:191], v[54:57]
	v_mfma_f32_16x16x32_bf16 v[50:53], v[180:183], v[188:191], v[50:53]
	v_mfma_f32_16x16x32_bf16 v[38:41], v[172:175], v[196:199], v[38:41]
	v_mfma_f32_16x16x32_bf16 v[34:37], v[180:183], v[196:199], v[34:37]
	v_mfma_f32_16x16x32_bf16 v[22:25], v[172:175], v[204:207], v[22:25]
	v_mfma_f32_16x16x32_bf16 v[18:21], v[180:183], v[204:207], v[18:21]
	v_mfma_f32_16x16x32_bf16 v[6:9], v[172:175], v[212:215], v[6:9]
	v_mfma_f32_16x16x32_bf16 v[2:5], v[180:183], v[212:215], v[2:5]
	s_setprio 0
	s_barrier
	s_add_i32 s49, s49, 2
	s_add_u32 s24, s24, 0x100
	s_addc_u32 s25, s25, 0
	s_add_u32 s47, s47, 0x100
	s_addc_u32 s48, s48, 0
	s_cmp_gt_u32 s49, 5
	s_cbranch_scc0 .LBB0_1086
	s_and_b64 vcc, exec, s[12:13]
	s_cbranch_vccz .LBB0_1089
	s_barrier

; #define PG8_STAGE(bufoff, gbase, voff) do { _Pragma("unroll") for (int _i = 0; _i < 2; ++_i) \
;         __builtin_amdgcn_global_load_lds((const unsigned*)((const char*)(gbase) + (voff)[_i]), (PG8_LAS unsigned*)(lds + (bufoff) + ldsw + _i * 8192), 16, 0, 0); } while (0)
; #define PG8_LDA(dst, b, h) do { _Pragma("unroll") for (int m = 0; m < 4; ++m) _Pragma("unroll") for (int k = 0; k < 2; ++k) dst[m][k] = *(const PG8_LAS bf16x8*)(lds + PG8_SA(b, h) + aoff + m * 2048 + k * 1024); } while (0)
; #define PG8_LDB(dst, b, h) do { _Pragma("unroll") for (int n = 0; n < 2; ++n) _Pragma("unroll") for (int k = 0; k < 2; ++k) dst[n][k] = *(const PG8_LAS bf16x8*)(lds + PG8_SB(b, h) + boff + n * 2048 + k * 1024); } while (0)
; #define PG8_MMA(ai, bj, At, Bt) do { __builtin_amdgcn_s_setprio(1); _Pragma("unroll") for (int m = 0; m < 4; ++m) _Pragma("unroll") for (int n = 0; n < 2; ++n) _Pragma("unroll") for (int k = 0; k < 2; ++k) \
;         acc[ai][bj][m][n] = __builtin_amdgcn_mfma_f32_16x16x32_bf16(Bt[n][k], At[m][k], acc[ai][bj][m][n], 0, 0, 0); __builtin_amdgcn_s_setprio(0); } while (0)
; #define PG8_WAIT_V(n) asm volatile("s_waitcnt vmcnt(" #n ")" ::: "memory")
; #define PG8_WAIT_L(n) asm volatile("s_waitcnt lgkmcnt(" #n ")" ::: "memory")
; #define PG8_BAR __builtin_amdgcn_s_barrier()
; #define PG8_SCHED __builtin_amdgcn_sched_barrier(0)
; template <class Epi, class Sched, bool ALIGN_EPI = false, bool SP2 = false>
; __device__ __forceinline__ void gemm_phase(PG8_LAS unsigned char* lds, const Gemm g, const Sched& S, const Epi& E) {
;     ...
;             PG8_LDB(B0, 0, 0); PG8_LDB(B1, 0, 1); PG8_SCHED; PG8_LDA(At, 0, 0); PG8_STAGE(PG8_SA(1, 1), a1 + hstepA, voffA);
;             PG8_WAIT_V(8); PG8_WAIT_L(0); PG8_BAR; PG8_MMA(0, 0, At, B0); PG8_MMA(0, 1, At, B1); PG8_BAR; PG8_SCHED;
;             PG8_LDA(At, 0, 1); PG8_STAGE(PG8_SB(0, 0), b2, voffB); PG8_STAGE(PG8_SB(0, 1), b2 + hstepB, voffB); PG8_STAGE(PG8_SA(0, 0), a2, voffA);
;             PG8_WAIT_V(8); PG8_WAIT_L(0); PG8_BAR; PG8_MMA(1, 0, At, B0); PG8_MMA(1, 1, At, B1); PG8_BAR; PG8_SCHED;
.LBB0_1269:
	v_add_u32_e32 v24, s56, v22
	ds_read_b128 v[50:53], v24
	ds_read_b128 v[54:57], v24 offset:1024
	ds_read_b128 v[70:73], v24 offset:2048
	ds_read_b128 v[74:77], v24 offset:3072
	v_add_u32_e32 v24, s57, v22
	s_add_u32 s36, s20, s34
	ds_read_b128 v[78:81], v24
	ds_read_b128 v[90:93], v24 offset:1024
	ds_read_b128 v[94:97], v24 offset:2048
	ds_read_b128 v[154:157], v24 offset:3072
	s_addc_u32 s37, s21, s35
	s_add_u32 s36, s36, 0x100
	s_addc_u32 s37, s37, 0
	s_add_u32 s64, s59, s34
	s_addc_u32 s65, s60, s35
	s_cmpk_eq_i32 s34, 0x700
	s_cselect_b32 s39, s27, s37
	s_cselect_b32 s38, s61, s36
	s_cselect_b32 s37, s25, s65
	s_cselect_b32 s36, s62, s64
	v_lshl_add_u64 v[24:25], v[18:19], 0, s[34:35]
	s_add_i32 m0, s48, 0xc000
	ds_read_b128 v[158:161], v23
	ds_read_b128 v[178:181], v23 offset:1024
	ds_read_b128 v[194:197], v23 offset:2048
	ds_read_b128 v[198:201], v23 offset:3072
	ds_read_b128 v[202:205], v23 offset:4096
	ds_read_b128 v[206:209], v23 offset:5120
	ds_read_b128 v[210:213], v23 offset:6144
	ds_read_b128 v[214:217], v23 offset:7168
	global_load_lds_dwordx4 v[24:25], off
	v_lshl_add_u64 v[24:25], v[20:21], 0, s[34:35]
	s_add_i32 m0, s48, 0xe000
	s_nop 0
	global_load_lds_dwordx4 v[24:25], off
	s_waitcnt vmcnt(8)
	s_waitcnt lgkmcnt(0)
	s_barrier
	s_setprio 1
	s_waitcnt lgkmcnt(0)
	v_mfma_f32_16x16x32_bf16 v[62:65], v[50:53], v[158:161], v[62:65]
	v_mfma_f32_16x16x32_bf16 v[170:173], v[70:73], v[158:161], v[170:173]
	v_mfma_f32_16x16x32_bf16 v[166:169], v[50:53], v[194:197], v[166:169]
	v_mfma_f32_16x16x32_bf16 v[162:165], v[70:73], v[194:197], v[162:165]
	v_mfma_f32_16x16x32_bf16 v[174:177], v[50:53], v[202:205], v[174:177]
	v_mfma_f32_16x16x32_bf16 v[190:193], v[70:73], v[202:205], v[190:193]
	v_mfma_f32_16x16x32_bf16 v[186:189], v[50:53], v[210:213], v[186:189]
	v_mfma_f32_16x16x32_bf16 v[182:185], v[70:73], v[210:213], v[182:185]
	v_mfma_f32_16x16x32_bf16 v[62:65], v[54:57], v[178:181], v[62:65]
	v_mfma_f32_16x16x32_bf16 v[170:173], v[74:77], v[178:181], v[170:173]
	v_mfma_f32_16x16x32_bf16 v[166:169], v[54:57], v[198:201], v[166:169]
	v_mfma_f32_16x16x32_bf16 v[162:165], v[74:77], v[198:201], v[162:165]
	v_mfma_f32_16x16x32_bf16 v[174:177], v[54:57], v[206:209], v[174:177]
	v_mfma_f32_16x16x32_bf16 v[190:193], v[74:77], v[206:209], v[190:193]
	v_mfma_f32_16x16x32_bf16 v[186:189], v[54:57], v[214:217], v[186:189]
	v_mfma_f32_16x16x32_bf16 v[182:185], v[74:77], v[214:217], v[182:185]
	s_setprio 0
	s_setprio 1
	v_mfma_f32_16x16x32_bf16 v[86:89], v[78:81], v[158:161], v[86:89]
	v_mfma_f32_16x16x32_bf16 v[82:85], v[94:97], v[158:161], v[82:85]
	v_mfma_f32_16x16x32_bf16 v[66:69], v[78:81], v[194:197], v[66:69]
	v_mfma_f32_16x16x32_bf16 v[58:61], v[94:97], v[194:197], v[58:61]
	v_mfma_f32_16x16x32_bf16 v[114:117], v[78:81], v[202:205], v[114:117]
	v_mfma_f32_16x16x32_bf16 v[110:113], v[94:97], v[202:205], v[110:113]
	v_mfma_f32_16x16x32_bf16 v[106:109], v[78:81], v[210:213], v[106:109]
	v_mfma_f32_16x16x32_bf16 v[102:105], v[94:97], v[210:213], v[102:105]
	v_mfma_f32_16x16x32_bf16 v[86:89], v[90:93], v[178:181], v[86:89]
	v_mfma_f32_16x16x32_bf16 v[82:85], v[154:157], v[178:181], v[82:85]
	v_mfma_f32_16x16x32_bf16 v[66:69], v[90:93], v[198:201], v[66:69]
	v_mfma_f32_16x16x32_bf16 v[58:61], v[154:157], v[198:201], v[58:61]
	v_mfma_f32_16x16x32_bf16 v[114:117], v[90:93], v[206:209], v[114:117]
	v_mfma_f32_16x16x32_bf16 v[110:113], v[154:157], v[206:209], v[110:113]
	v_mfma_f32_16x16x32_bf16 v[106:109], v[90:93], v[214:217], v[106:109]
	v_mfma_f32_16x16x32_bf16 v[102:105], v[154:157], v[214:217], v[102:105]
	s_setprio 0
	s_barrier
	s_add_i32 s64, s56, s47
	s_add_u32 s98, s36, 0x80
	s_addc_u32 s99, s37, 0
	s_mov_b32 m0, s64
	ds_read_b128 v[158:161], v23 offset:16384
	ds_read_b128 v[178:181], v23 offset:17408
	ds_read_b128 v[194:197], v23 offset:18432
	ds_read_b128 v[198:201], v23 offset:19456
	ds_read_b128 v[202:205], v23 offset:20480
	ds_read_b128 v[206:209], v23 offset:21504
	ds_read_b128 v[210:213], v23 offset:22528
	ds_read_b128 v[214:217], v23 offset:23552
	global_load_lds_dwordx4 v4, s[36:37]
	s_add_i32 m0, s64, 0x2000
	s_add_u32 s64, s36, 0x40000
	s_addc_u32 s65, s37, 0
	s_add_i32 s66, s57, s47
	global_load_lds_dwordx4 v8, s[36:37]
	s_mov_b32 m0, s66
	s_add_u32 s100, s38, 0x80
	s_addc_u32 s101, s39, 0
	global_load_lds_dwordx4 v4, s[64:65]
	s_add_i32 m0, s66, 0x2000
	s_nop 0
	global_load_lds_dwordx4 v8, s[64:65]
	s_mov_b32 m0, s48
	s_nop 0
	global_load_lds_dwordx4 v2, s[38:39]
	s_mov_b32 m0, s49
	s_nop 0
	global_load_lds_dwordx4 v6, s[38:39]
	s_waitcnt vmcnt(8)
	s_waitcnt lgkmcnt(0)
	s_barrier
; #define PG8_STAGE(bufoff, gbase, voff) do { _Pragma("unroll") for (int _i = 0; _i < 2; ++_i) \
;         __builtin_amdgcn_global_load_lds((const unsigned*)((const char*)(gbase) + (voff)[_i]), (PG8_LAS unsigned*)(lds + (bufoff) + ldsw + _i * 8192), 16, 0, 0); } while (0)
; #define PG8_LDA(dst, b, h) do { _Pragma("unroll") for (int m = 0; m < 4; ++m) _Pragma("unroll") for (int k = 0; k < 2; ++k) dst[m][k] = *(const PG8_LAS bf16x8*)(lds + PG8_SA(b, h) + aoff + m * 2048 + k * 1024); } while (0)
; #define PG8_LDB(dst, b, h) do { _Pragma("unroll") for (int n = 0; n < 2; ++n) _Pragma("unroll") for (int k = 0; k < 2; ++k) dst[n][k] = *(const PG8_LAS bf16x8*)(lds + PG8_SB(b, h) + boff + n * 2048 + k * 1024); } while (0)
; #define PG8_MMA(ai, bj, At, Bt) do { __builtin_amdgcn_s_setprio(1); _Pragma("unroll") for (int m = 0; m < 4; ++m) _Pragma("unroll") for (int n = 0; n < 2; ++n) _Pragma("unroll") for (int k = 0; k < 2; ++k) \
;         acc[ai][bj][m][n] = __builtin_amdgcn_mfma_f32_16x16x32_bf16(Bt[n][k], At[m][k], acc[ai][bj][m][n], 0, 0, 0); __builtin_amdgcn_s_setprio(0); } while (0)
; #define PG8_WAIT_V(n) asm volatile("s_waitcnt vmcnt(" #n ")" ::: "memory")
; #define PG8_WAIT_L(n) asm volatile("s_waitcnt lgkmcnt(" #n ")" ::: "memory")
; #define PG8_BAR __builtin_amdgcn_s_barrier()
; #define PG8_SCHED __builtin_amdgcn_sched_barrier(0)
; template <class Epi, class Sched, bool ALIGN_EPI = false, bool SP2 = false>
; __device__ __forceinline__ void gemm_phase(PG8_LAS unsigned char* lds, const Gemm g, const Sched& S, const Epi& E) {
;     ...
;             PG8_WAIT_V(8); PG8_WAIT_L(0); PG8_BAR; PG8_MMA(1, 0, At, B0); PG8_MMA(1, 1, At, B1); PG8_BAR; PG8_SCHED;
;             PG8_LDB(B0, 1, 0); PG8_LDB(B1, 1, 1); PG8_SCHED; PG8_LDA(At, 1, 0); PG8_STAGE(PG8_SA(0, 1), a2 + hstepA, voffA);
;             PG8_WAIT_V(8); PG8_WAIT_L(0); PG8_BAR; PG8_MMA(0, 0, At, B0); PG8_MMA(0, 1, At, B1); PG8_BAR; PG8_SCHED;
	s_setprio 1
	s_waitcnt lgkmcnt(0)
	v_mfma_f32_16x16x32_bf16 v[150:153], v[50:53], v[158:161], v[150:153]
	v_mfma_f32_16x16x32_bf16 v[146:149], v[70:73], v[158:161], v[146:149]
	v_mfma_f32_16x16x32_bf16 v[142:145], v[50:53], v[194:197], v[142:145]
	v_mfma_f32_16x16x32_bf16 v[138:141], v[70:73], v[194:197], v[138:141]
	v_mfma_f32_16x16x32_bf16 v[126:129], v[50:53], v[202:205], v[126:129]
	v_mfma_f32_16x16x32_bf16 v[98:101], v[70:73], v[202:205], v[98:101]
	v_mfma_f32_16x16x32_bf16 v[46:49], v[50:53], v[210:213], v[46:49]
	v_mfma_f32_16x16x32_bf16 v[42:45], v[70:73], v[210:213], v[42:45]
	v_mfma_f32_16x16x32_bf16 v[150:153], v[54:57], v[178:181], v[150:153]
	v_mfma_f32_16x16x32_bf16 v[146:149], v[74:77], v[178:181], v[146:149]
	v_mfma_f32_16x16x32_bf16 v[142:145], v[54:57], v[198:201], v[142:145]
	v_mfma_f32_16x16x32_bf16 v[138:141], v[74:77], v[198:201], v[138:141]
	v_mfma_f32_16x16x32_bf16 v[126:129], v[54:57], v[206:209], v[126:129]
	v_mfma_f32_16x16x32_bf16 v[98:101], v[74:77], v[206:209], v[98:101]
	v_mfma_f32_16x16x32_bf16 v[46:49], v[54:57], v[214:217], v[46:49]
	v_mfma_f32_16x16x32_bf16 v[42:45], v[74:77], v[214:217], v[42:45]
	s_setprio 0
	s_setprio 1
	v_mfma_f32_16x16x32_bf16 v[38:41], v[78:81], v[202:205], v[38:41]
	v_mfma_f32_16x16x32_bf16 v[34:37], v[94:97], v[202:205], v[34:37]
	v_mfma_f32_16x16x32_bf16 v[30:33], v[78:81], v[210:213], v[30:33]
	v_mfma_f32_16x16x32_bf16 v[24:27], v[94:97], v[210:213], v[26:29]
	v_mfma_f32_16x16x32_bf16 v[50:53], v[78:81], v[158:161], v[134:137]
	v_mfma_f32_16x16x32_bf16 v[54:57], v[94:97], v[158:161], v[130:133]
	v_mfma_f32_16x16x32_bf16 v[70:73], v[78:81], v[194:197], v[122:125]
	v_mfma_f32_16x16x32_bf16 v[74:77], v[94:97], v[194:197], v[118:121]
	v_mfma_f32_16x16x32_bf16 v[38:41], v[90:93], v[206:209], v[38:41]
	v_mfma_f32_16x16x32_bf16 v[34:37], v[154:157], v[206:209], v[34:37]
	v_mfma_f32_16x16x32_bf16 v[30:33], v[90:93], v[214:217], v[30:33]
	v_mfma_f32_16x16x32_bf16 v[24:27], v[154:157], v[214:217], v[24:27]
	v_mfma_f32_16x16x32_bf16 v[50:53], v[90:93], v[178:181], v[50:53]
	v_mfma_f32_16x16x32_bf16 v[54:57], v[154:157], v[178:181], v[54:57]
	v_mfma_f32_16x16x32_bf16 v[70:73], v[90:93], v[198:201], v[70:73]
	v_mfma_f32_16x16x32_bf16 v[74:77], v[154:157], v[198:201], v[74:77]
	s_setprio 0
	s_barrier
	s_add_i32 s64, 0, 0x18000
	v_add_u32_e32 v28, s64, v22
	s_add_i32 s65, 0, 0x1c000
	ds_read_b128 v[78:81], v28
	ds_read_b128 v[90:93], v28 offset:1024
	ds_read_b128 v[94:97], v28 offset:2048
	ds_read_b128 v[118:121], v28 offset:3072
	v_add_u32_e32 v28, s65, v22
	ds_read_b128 v[154:157], v28
	ds_read_b128 v[158:161], v28 offset:1024
	ds_read_b128 v[178:181], v28 offset:2048
	ds_read_b128 v[194:197], v28 offset:3072
	s_add_u32 s38, s38, 0x40000
	s_addc_u32 s39, s39, 0
	s_mov_b32 m0, s51
	ds_read_b128 v[122:125], v23 offset:32768
	ds_read_b128 v[130:133], v23 offset:33792
	ds_read_b128 v[134:137], v23 offset:34816
	ds_read_b128 v[198:201], v23 offset:35840
	ds_read_b128 v[202:205], v23 offset:36864
	ds_read_b128 v[206:209], v23 offset:37888
	ds_read_b128 v[210:213], v23 offset:38912
	ds_read_b128 v[214:217], v23 offset:39936
	global_load_lds_dwordx4 v2, s[38:39]
	s_mov_b32 m0, s52
	s_nop 0
	global_load_lds_dwordx4 v6, s[38:39]
	s_waitcnt vmcnt(8)
	s_waitcnt lgkmcnt(0)
	s_barrier
	s_setprio 1
	s_waitcnt lgkmcnt(0)
	v_mfma_f32_16x16x32_bf16 v[62:65], v[78:81], v[122:125], v[62:65]
	v_mfma_f32_16x16x32_bf16 v[170:173], v[94:97], v[122:125], v[170:173]
	v_mfma_f32_16x16x32_bf16 v[166:169], v[78:81], v[134:137], v[166:169]
	v_mfma_f32_16x16x32_bf16 v[162:165], v[94:97], v[134:137], v[162:165]
	v_mfma_f32_16x16x32_bf16 v[174:177], v[78:81], v[202:205], v[174:177]
	v_mfma_f32_16x16x32_bf16 v[190:193], v[94:97], v[202:205], v[190:193]
	v_mfma_f32_16x16x32_bf16 v[186:189], v[78:81], v[210:213], v[186:189]
	v_mfma_f32_16x16x32_bf16 v[182:185], v[94:97], v[210:213], v[182:185]
	v_mfma_f32_16x16x32_bf16 v[62:65], v[90:93], v[130:133], v[62:65]
	v_mfma_f32_16x16x32_bf16 v[170:173], v[118:121], v[130:133], v[170:173]
	v_mfma_f32_16x16x32_bf16 v[166:169], v[90:93], v[198:201], v[166:169]
	v_mfma_f32_16x16x32_bf16 v[162:165], v[118:121], v[198:201], v[162:165]
	v_mfma_f32_16x16x32_bf16 v[174:177], v[90:93], v[206:209], v[174:177]
	v_mfma_f32_16x16x32_bf16 v[190:193], v[118:121], v[206:209], v[190:193]
	v_mfma_f32_16x16x32_bf16 v[186:189], v[90:93], v[214:217], v[186:189]
	v_mfma_f32_16x16x32_bf16 v[182:185], v[118:121], v[214:217], v[182:185]
	s_setprio 0
	s_setprio 1
	v_mfma_f32_16x16x32_bf16 v[86:89], v[154:157], v[122:125], v[86:89]
	v_mfma_f32_16x16x32_bf16 v[82:85], v[178:181], v[122:125], v[82:85]
	v_mfma_f32_16x16x32_bf16 v[66:69], v[154:157], v[134:137], v[66:69]
	v_mfma_f32_16x16x32_bf16 v[58:61], v[178:181], v[134:137], v[58:61]
	v_mfma_f32_16x16x32_bf16 v[114:117], v[154:157], v[202:205], v[114:117]
	v_mfma_f32_16x16x32_bf16 v[110:113], v[178:181], v[202:205], v[110:113]
	v_mfma_f32_16x16x32_bf16 v[106:109], v[154:157], v[210:213], v[106:109]
	v_mfma_f32_16x16x32_bf16 v[102:105], v[178:181], v[210:213], v[102:105]
	v_mfma_f32_16x16x32_bf16 v[86:89], v[158:161], v[130:133], v[86:89]
	v_mfma_f32_16x16x32_bf16 v[82:85], v[194:197], v[130:133], v[82:85]
	v_mfma_f32_16x16x32_bf16 v[66:69], v[158:161], v[198:201], v[66:69]
	v_mfma_f32_16x16x32_bf16 v[58:61], v[194:197], v[198:201], v[58:61]
	v_mfma_f32_16x16x32_bf16 v[114:117], v[158:161], v[206:209], v[114:117]
	v_mfma_f32_16x16x32_bf16 v[110:113], v[194:197], v[206:209], v[110:113]
	v_mfma_f32_16x16x32_bf16 v[106:109], v[158:161], v[214:217], v[106:109]
	v_mfma_f32_16x16x32_bf16 v[102:105], v[194:197], v[214:217], v[102:105]
	s_setprio 0
	s_barrier
; #define PG8_STAGE(bufoff, gbase, voff) do { _Pragma("unroll") for (int _i = 0; _i < 2; ++_i) \
;         __builtin_amdgcn_global_load_lds((const unsigned*)((const char*)(gbase) + (voff)[_i]), (PG8_LAS unsigned*)(lds + (bufoff) + ldsw + _i * 8192), 16, 0, 0); } while (0)
; #define PG8_LDA(dst, b, h) do { _Pragma("unroll") for (int m = 0; m < 4; ++m) _Pragma("unroll") for (int k = 0; k < 2; ++k) dst[m][k] = *(const PG8_LAS bf16x8*)(lds + PG8_SA(b, h) + aoff + m * 2048 + k * 1024); } while (0)
; #define PG8_MMA(ai, bj, At, Bt) do { __builtin_amdgcn_s_setprio(1); _Pragma("unroll") for (int m = 0; m < 4; ++m) _Pragma("unroll") for (int n = 0; n < 2; ++n) _Pragma("unroll") for (int k = 0; k < 2; ++k) \
;         acc[ai][bj][m][n] = __builtin_amdgcn_mfma_f32_16x16x32_bf16(Bt[n][k], At[m][k], acc[ai][bj][m][n], 0, 0, 0); __builtin_amdgcn_s_setprio(0); } while (0)
; #define PG8_WAIT_V(n) asm volatile("s_waitcnt vmcnt(" #n ")" ::: "memory")
; #define PG8_WAIT_L(n) asm volatile("s_waitcnt lgkmcnt(" #n ")" ::: "memory")
; #define PG8_BAR __builtin_amdgcn_s_barrier()
; #define PG8_SCHED __builtin_amdgcn_sched_barrier(0)
; template <class Epi, class Sched, bool ALIGN_EPI = false, bool SP2 = false>
; __device__ __forceinline__ void gemm_phase(PG8_LAS unsigned char* lds, const Gemm g, const Sched& S, const Epi& E) {
;     ...
;             PG8_LDA(At, 1, 1); PG8_STAGE(PG8_SB(1, 0), b3, voffB); PG8_STAGE(PG8_SB(1, 1), b3 + hstepB, voffB); PG8_STAGE(PG8_SA(1, 0), a3, voffA);
;             PG8_WAIT_V(8); PG8_WAIT_L(0); PG8_BAR; PG8_MMA(1, 0, At, B0); PG8_MMA(1, 1, At, B1); PG8_BAR; PG8_SCHED;
;     ...
; #pragma unroll
;         for (int a = 0; a < 2; ++a)
; #pragma unroll
;             for (int b = 0; b < 2; ++b)
; #pragma unroll
;                 for (int m = 0; m < 4; ++m)
; #pragma unroll
;                     for (int n = 0; n < 2; ++n) acc[a][b][m][n] = (f32x4){0.f, 0.f, 0.f, 0.f};
;         cur = nxt; cA = nA; cB = nB; ++ui;
	s_add_i32 s38, s64, s47
	s_mov_b32 m0, s38
	ds_read_b128 v[122:125], v23 offset:49152
	ds_read_b128 v[130:133], v23 offset:50176
	ds_read_b128 v[198:201], v23 offset:51200
	ds_read_b128 v[202:205], v23 offset:52224
	ds_read_b128 v[206:209], v23 offset:53248
	ds_read_b128 v[210:213], v23 offset:54272
	ds_read_b128 v[214:217], v23 offset:55296
	ds_read_b128 v[218:221], v23 offset:56320
	global_load_lds_dwordx4 v4, s[98:99]
	s_add_i32 m0, s38, 0x2000
	s_add_u32 s36, s36, 0x40080
	s_addc_u32 s37, s37, 0
	s_add_i32 s38, s65, s47
	global_load_lds_dwordx4 v8, s[98:99]
	s_mov_b32 m0, s38
	s_nop 0
	global_load_lds_dwordx4 v4, s[36:37]
	s_add_i32 m0, s38, 0x2000
	s_nop 0
	global_load_lds_dwordx4 v8, s[36:37]
	s_mov_b32 m0, s54
	s_nop 0
	global_load_lds_dwordx4 v2, s[100:101]
	s_mov_b32 m0, s55
	s_nop 0
	global_load_lds_dwordx4 v6, s[100:101]
	s_waitcnt vmcnt(8)
	s_waitcnt lgkmcnt(0)
	s_barrier
	s_setprio 1
	s_waitcnt lgkmcnt(0)
	v_mfma_f32_16x16x32_bf16 v[134:137], v[78:81], v[122:125], v[150:153]
	v_mfma_f32_16x16x32_bf16 v[150:153], v[90:93], v[130:133], v[134:137]
	v_mfma_f32_16x16x32_bf16 v[134:137], v[94:97], v[122:125], v[146:149]
	v_mfma_f32_16x16x32_bf16 v[146:149], v[118:121], v[130:133], v[134:137]
	v_mfma_f32_16x16x32_bf16 v[134:137], v[78:81], v[198:201], v[142:145]
	v_mfma_f32_16x16x32_bf16 v[142:145], v[90:93], v[202:205], v[134:137]
	v_mfma_f32_16x16x32_bf16 v[134:137], v[94:97], v[198:201], v[138:141]
	v_mfma_f32_16x16x32_bf16 v[126:129], v[78:81], v[206:209], v[126:129]
	v_mfma_f32_16x16x32_bf16 v[98:101], v[94:97], v[206:209], v[98:101]
	v_mfma_f32_16x16x32_bf16 v[46:49], v[78:81], v[214:217], v[46:49]
	v_mfma_f32_16x16x32_bf16 v[42:45], v[94:97], v[214:217], v[42:45]
	v_mfma_f32_16x16x32_bf16 v[138:141], v[118:121], v[202:205], v[134:137]
	v_mfma_f32_16x16x32_bf16 v[126:129], v[90:93], v[210:213], v[126:129]
	v_mfma_f32_16x16x32_bf16 v[98:101], v[118:121], v[210:213], v[98:101]
	v_mfma_f32_16x16x32_bf16 v[46:49], v[90:93], v[218:221], v[46:49]
	v_mfma_f32_16x16x32_bf16 v[42:45], v[118:121], v[218:221], v[42:45]
	s_setprio 0
	s_setprio 1
	v_mfma_f32_16x16x32_bf16 v[50:53], v[154:157], v[122:125], v[50:53]
	v_mfma_f32_16x16x32_bf16 v[134:137], v[158:161], v[130:133], v[50:53]
	v_mfma_f32_16x16x32_bf16 v[50:53], v[178:181], v[122:125], v[54:57]
	v_mfma_f32_16x16x32_bf16 v[130:133], v[194:197], v[130:133], v[50:53]
	v_mfma_f32_16x16x32_bf16 v[50:53], v[154:157], v[198:201], v[70:73]
	v_mfma_f32_16x16x32_bf16 v[122:125], v[158:161], v[202:205], v[50:53]
	v_mfma_f32_16x16x32_bf16 v[50:53], v[178:181], v[198:201], v[74:77]
	v_mfma_f32_16x16x32_bf16 v[38:41], v[154:157], v[206:209], v[38:41]
	v_mfma_f32_16x16x32_bf16 v[34:37], v[178:181], v[206:209], v[34:37]
	v_mfma_f32_16x16x32_bf16 v[28:31], v[154:157], v[214:217], v[30:33]
	v_mfma_f32_16x16x32_bf16 v[24:27], v[178:181], v[214:217], v[24:27]
	v_mfma_f32_16x16x32_bf16 v[118:121], v[194:197], v[202:205], v[50:53]
	v_mfma_f32_16x16x32_bf16 v[38:41], v[158:161], v[210:213], v[38:41]
	v_mfma_f32_16x16x32_bf16 v[34:37], v[194:197], v[210:213], v[34:37]
	v_mfma_f32_16x16x32_bf16 v[30:33], v[158:161], v[218:221], v[28:31]
	v_mfma_f32_16x16x32_bf16 v[26:29], v[194:197], v[218:221], v[24:27]
	s_setprio 0
	s_barrier
	s_add_i32 s63, s63, 2
	s_add_u32 s34, s34, 0x100
	s_addc_u32 s35, s35, 0
	s_cmp_gt_u32 s63, 13
	s_cbranch_scc0 .LBB0_1269
	s_add_u32 s34, s59, 0xffffff00
	s_addc_u32 s35, s60, -1
	s_andn2_b64 vcc, exec, s[4:5]
	s_cbranch_vccnz .LBB0_1260
	v_mov_b32_e32 v26, 0
	s_mov_b32 s14, s24
	s_mov_b32 s12, s26
	s_mov_b64 s[20:21], s[30:31]
	s_mov_b32 s53, s58
	v_mov_b32_e32 v27, v26
	v_mov_b32_e32 v28, v26
	v_mov_b32_e32 v29, v26
	v_mov_b32_e32 v30, v26
	v_mov_b32_e32 v31, v26
	v_mov_b32_e32 v32, v26
	v_mov_b32_e32 v33, v26
	v_mov_b32_e32 v34, v26
	v_mov_b32_e32 v35, v26
	v_mov_b32_e32 v36, v26
	v_mov_b32_e32 v37, v26
	v_mov_b32_e32 v38, v26
	v_mov_b32_e32 v39, v26
	v_mov_b32_e32 v40, v26
	v_mov_b32_e32 v41, v26
	v_mov_b32_e32 v118, v26
	v_mov_b32_e32 v119, v26
	v_mov_b32_e32 v120, v26
	v_mov_b32_e32 v121, v26
	v_mov_b32_e32 v122, v26
	v_mov_b32_e32 v123, v26
	v_mov_b32_e32 v124, v26
	v_mov_b32_e32 v125, v26
	v_mov_b32_e32 v130, v26
	v_mov_b32_e32 v131, v26
	v_mov_b32_e32 v132, v26
	v_mov_b32_e32 v133, v26
	v_mov_b32_e32 v134, v26
	v_mov_b32_e32 v135, v26
	v_mov_b32_e32 v136, v26
	v_mov_b32_e32 v137, v26
	v_mov_b32_e32 v42, v26
	v_mov_b32_e32 v43, v26
	v_mov_b32_e32 v44, v26
	v_mov_b32_e32 v45, v26
	v_mov_b32_e32 v46, v26
	v_mov_b32_e32 v47, v26
	v_mov_b32_e32 v48, v26
	v_mov_b32_e32 v49, v26
	v_mov_b32_e32 v98, v26
	v_mov_b32_e32 v99, v26
	v_mov_b32_e32 v100, v26
	v_mov_b32_e32 v101, v26
	v_mov_b32_e32 v126, v26
	v_mov_b32_e32 v127, v26
	v_mov_b32_e32 v128, v26
	v_mov_b32_e32 v129, v26
	v_mov_b32_e32 v138, v26
	v_mov_b32_e32 v139, v26
	v_mov_b32_e32 v140, v26
	v_mov_b32_e32 v141, v26
	v_mov_b32_e32 v142, v26
	v_mov_b32_e32 v143, v26
	v_mov_b32_e32 v144, v26
	v_mov_b32_e32 v145, v26
	v_mov_b32_e32 v146, v26
	v_mov_b32_e32 v147, v26
	v_mov_b32_e32 v148, v26
	v_mov_b32_e32 v149, v26
	v_mov_b32_e32 v150, v26
	v_mov_b32_e32 v151, v26
	v_mov_b32_e32 v152, v26
	v_mov_b32_e32 v153, v26
	v_mov_b32_e32 v102, v26
	v_mov_b32_e32 v103, v26
	v_mov_b32_e32 v104, v26
	v_mov_b32_e32 v105, v26
	v_mov_b32_e32 v106, v26
	v_mov_b32_e32 v107, v26
	v_mov_b32_e32 v108, v26
	v_mov_b32_e32 v109, v26
	v_mov_b32_e32 v110, v26
	v_mov_b32_e32 v111, v26
	v_mov_b32_e32 v112, v26
	v_mov_b32_e32 v113, v26
	v_mov_b32_e32 v114, v26
	v_mov_b32_e32 v115, v26
	v_mov_b32_e32 v116, v26
	v_mov_b32_e32 v117, v26
	v_mov_b32_e32 v58, v26
	v_mov_b32_e32 v59, v26
	v_mov_b32_e32 v60, v26
	v_mov_b32_e32 v61, v26
	v_mov_b32_e32 v66, v26
	v_mov_b32_e32 v67, v26
	v_mov_b32_e32 v68, v26
	v_mov_b32_e32 v69, v26
	v_mov_b32_e32 v82, v26
	v_mov_b32_e32 v83, v26
	v_mov_b32_e32 v84, v26
	v_mov_b32_e32 v85, v26
	v_mov_b32_e32 v86, v26
	v_mov_b32_e32 v87, v26
	v_mov_b32_e32 v88, v26
	v_mov_b32_e32 v89, v26
	v_mov_b32_e32 v182, v26
	v_mov_b32_e32 v183, v26
	v_mov_b32_e32 v184, v26
	v_mov_b32_e32 v185, v26
	v_mov_b32_e32 v186, v26
	v_mov_b32_e32 v187, v26
	v_mov_b32_e32 v188, v26
	v_mov_b32_e32 v189, v26
	v_mov_b32_e32 v190, v26
	v_mov_b32_e32 v191, v26
	v_mov_b32_e32 v192, v26
	v_mov_b32_e32 v193, v26
	v_mov_b32_e32 v174, v26
	v_mov_b32_e32 v175, v26
	v_mov_b32_e32 v176, v26
	v_mov_b32_e32 v177, v26
	v_mov_b32_e32 v162, v26
	v_mov_b32_e32 v163, v26
	v_mov_b32_e32 v164, v26
	v_mov_b32_e32 v165, v26
	v_mov_b32_e32 v166, v26
	v_mov_b32_e32 v167, v26
	v_mov_b32_e32 v168, v26
	v_mov_b32_e32 v169, v26
	v_mov_b32_e32 v170, v26
	v_mov_b32_e32 v171, v26
	v_mov_b32_e32 v172, v26
	v_mov_b32_e32 v173, v26
	v_mov_b32_e32 v62, v26
	v_mov_b32_e32 v63, v26
	v_mov_b32_e32 v64, v26
	v_mov_b32_e32 v65, v26
	s_andn2_b64 vcc, exec, s[2:3]
	s_cbranch_vccnz .LBB0_1261

; #define PG8_STAGE(bufoff, gbase, voff) do { _Pragma("unroll") for (int _i = 0; _i < 2; ++_i) \
;         __builtin_amdgcn_global_load_lds((const unsigned*)((const char*)(gbase) + (voff)[_i]), (PG8_LAS unsigned*)(lds + (bufoff) + ldsw + _i * 8192), 16, 0, 0); } while (0)
; #define PG8_LDA(dst, b, h) do { _Pragma("unroll") for (int m = 0; m < 4; ++m) _Pragma("unroll") for (int k = 0; k < 2; ++k) dst[m][k] = *(const PG8_LAS bf16x8*)(lds + PG8_SA(b, h) + aoff + m * 2048 + k * 1024); } while (0)
; #define PG8_LDB(dst, b, h) do { _Pragma("unroll") for (int n = 0; n < 2; ++n) _Pragma("unroll") for (int k = 0; k < 2; ++k) dst[n][k] = *(const PG8_LAS bf16x8*)(lds + PG8_SB(b, h) + boff + n * 2048 + k * 1024); } while (0)
; #define PG8_MMA(ai, bj, At, Bt) do { __builtin_amdgcn_s_setprio(1); _Pragma("unroll") for (int m = 0; m < 4; ++m) _Pragma("unroll") for (int n = 0; n < 2; ++n) _Pragma("unroll") for (int k = 0; k < 2; ++k) \
;         acc[ai][bj][m][n] = __builtin_amdgcn_mfma_f32_16x16x32_bf16(Bt[n][k], At[m][k], acc[ai][bj][m][n], 0, 0, 0); __builtin_amdgcn_s_setprio(0); } while (0)
; #define PG8_WAIT_V(n) asm volatile("s_waitcnt vmcnt(" #n ")" ::: "memory")
; #define PG8_WAIT_L(n) asm volatile("s_waitcnt lgkmcnt(" #n ")" ::: "memory")
; template <class Epi, class Sched, bool ALIGN_EPI = false, bool SP2 = false>
; __device__ __forceinline__ void gemm_phase(PG8_LAS unsigned char* lds, const Gemm g, const Sched& S, const Epi& E) {
;     ...
;             const bool last = (t == nt - 2);
;             const char* a1 = cA + (size_t)(t + 1) * kstep;
;             const char* a2 = last ? nA : cA + (size_t)(t + 2) * kstep; const char* b2 = last ? nB : cB + (size_t)(t + 2) * kstep;
;             const char* a3 = a2 + kstep; const char* b3 = b2 + kstep;
;             if (last && has_next) S.a_ready(nxt);
;             if constexpr (SP2) {
;             PG8_LDB(B0, 0, 0); PG8_LDB(B1, 0, 1); PG8_SCHED; PG8_LDA(At, 0, 0); PG8_STAGE(PG8_SA(1, 1), a1 + hstepA, voffA);
;             PG8_WAIT_V(8); PG8_WAIT_L(0); PG8_BAR; PG8_MMA(0, 0, At, B0); PG8_MMA(0, 1, At, B1); PG8_BAR; PG8_SCHED;
;             PG8_LDA(At, 0, 1); PG8_STAGE(PG8_SB(0, 0), b2, voffB); PG8_STAGE(PG8_SB(0, 1), b2 + hstepB, voffB); PG8_STAGE(PG8_SA(0, 0), a2, voffA);
;             PG8_WAIT_V(8); PG8_WAIT_L(0); PG8_BAR; PG8_MMA(1, 0, At, B0); PG8_MMA(1, 1, At, B1); PG8_BAR; PG8_SCHED;
.LBB0_1528:
	ds_read_b128 v[130:133], v182
	ds_read_b128 v[134:137], v182 offset:1024
	ds_read_b128 v[154:157], v182 offset:2048
	ds_read_b128 v[158:161], v182 offset:3072
	ds_read_b128 v[162:165], v183
	ds_read_b128 v[166:169], v183 offset:1024
	ds_read_b128 v[170:173], v183 offset:2048
	ds_read_b128 v[186:189], v183 offset:3072
	s_add_u32 s44, s42, 0xfffc0080
	s_addc_u32 s45, s43, -1
	s_cmp_eq_u32 s69, 12
	s_cselect_b32 s47, s31, s45
	s_cselect_b32 s46, s39, s44
	s_cselect_b32 s45, s29, s68
	s_cselect_b32 s44, s66, s67
	s_add_i32 m0, s41, 0xc000
	ds_read_b128 v[190:193], v184
	ds_read_b128 v[194:197], v184 offset:1024
	ds_read_b128 v[198:201], v184 offset:2048
	ds_read_b128 v[202:205], v184 offset:3072
	ds_read_b128 v[206:209], v184 offset:4096
	ds_read_b128 v[210:213], v184 offset:5120
	ds_read_b128 v[214:217], v184 offset:6144
	ds_read_b128 v[218:221], v184 offset:7168
	global_load_lds_dwordx4 v146, s[42:43]
	s_add_i32 m0, s41, 0xe000
	s_nop 0
	global_load_lds_dwordx4 v148, s[42:43]
	s_waitcnt vmcnt(8)
	s_waitcnt lgkmcnt(0)
	s_barrier
	s_setprio 1
	s_waitcnt lgkmcnt(0)
	v_mfma_f32_16x16x32_bf16 v[126:129], v[130:133], v[190:193], v[126:129]
	v_mfma_f32_16x16x32_bf16 v[94:97], v[154:157], v[190:193], v[94:97]
	v_mfma_f32_16x16x32_bf16 v[118:121], v[130:133], v[198:201], v[118:121]
	v_mfma_f32_16x16x32_bf16 v[86:89], v[154:157], v[198:201], v[86:89]
	v_mfma_f32_16x16x32_bf16 v[114:117], v[130:133], v[206:209], v[114:117]
	v_mfma_f32_16x16x32_bf16 v[82:85], v[154:157], v[206:209], v[82:85]
	v_mfma_f32_16x16x32_bf16 v[102:105], v[130:133], v[214:217], v[102:105]
	v_mfma_f32_16x16x32_bf16 v[70:73], v[154:157], v[214:217], v[70:73]
	v_mfma_f32_16x16x32_bf16 v[126:129], v[134:137], v[194:197], v[126:129]
	v_mfma_f32_16x16x32_bf16 v[94:97], v[158:161], v[194:197], v[94:97]
	v_mfma_f32_16x16x32_bf16 v[118:121], v[134:137], v[202:205], v[118:121]
	v_mfma_f32_16x16x32_bf16 v[86:89], v[158:161], v[202:205], v[86:89]
	v_mfma_f32_16x16x32_bf16 v[114:117], v[134:137], v[210:213], v[114:117]
	v_mfma_f32_16x16x32_bf16 v[82:85], v[158:161], v[210:213], v[82:85]
	v_mfma_f32_16x16x32_bf16 v[102:105], v[134:137], v[218:221], v[102:105]
	v_mfma_f32_16x16x32_bf16 v[70:73], v[158:161], v[218:221], v[70:73]
	s_setprio 0
	s_setprio 1
	v_mfma_f32_16x16x32_bf16 v[122:125], v[162:165], v[190:193], v[122:125]
	v_mfma_f32_16x16x32_bf16 v[90:93], v[170:173], v[190:193], v[90:93]
	v_mfma_f32_16x16x32_bf16 v[110:113], v[162:165], v[198:201], v[110:113]
	v_mfma_f32_16x16x32_bf16 v[78:81], v[170:173], v[198:201], v[78:81]
	v_mfma_f32_16x16x32_bf16 v[106:109], v[162:165], v[206:209], v[106:109]
	v_mfma_f32_16x16x32_bf16 v[74:77], v[170:173], v[206:209], v[74:77]
	v_mfma_f32_16x16x32_bf16 v[98:101], v[162:165], v[214:217], v[98:101]
	v_mfma_f32_16x16x32_bf16 v[66:69], v[170:173], v[214:217], v[66:69]
	v_mfma_f32_16x16x32_bf16 v[122:125], v[166:169], v[194:197], v[122:125]
	v_mfma_f32_16x16x32_bf16 v[90:93], v[186:189], v[194:197], v[90:93]
	v_mfma_f32_16x16x32_bf16 v[110:113], v[166:169], v[202:205], v[110:113]
	v_mfma_f32_16x16x32_bf16 v[78:81], v[186:189], v[202:205], v[78:81]
	v_mfma_f32_16x16x32_bf16 v[106:109], v[166:169], v[210:213], v[106:109]
	v_mfma_f32_16x16x32_bf16 v[74:77], v[186:189], v[210:213], v[74:77]
	v_mfma_f32_16x16x32_bf16 v[98:101], v[166:169], v[218:221], v[98:101]
	v_mfma_f32_16x16x32_bf16 v[66:69], v[186:189], v[218:221], v[66:69]
	s_setprio 0
	s_barrier
	s_add_i32 s70, s63, s51
	s_add_u32 s98, s44, 0x80
	s_addc_u32 s99, s45, 0
	s_mov_b32 m0, s70
	ds_read_b128 v[190:193], v184 offset:16384
	ds_read_b128 v[194:197], v184 offset:17408
	ds_read_b128 v[198:201], v184 offset:18432
	ds_read_b128 v[202:205], v184 offset:19456
	ds_read_b128 v[206:209], v184 offset:20480
	ds_read_b128 v[210:213], v184 offset:21504
	ds_read_b128 v[214:217], v184 offset:22528
	ds_read_b128 v[218:221], v184 offset:23552
	global_load_lds_dwordx4 v140, s[44:45]
	s_add_i32 m0, s70, 0x2000
	s_add_u32 s70, s44, 0x40000
	s_addc_u32 s71, s45, 0
	s_add_i32 s72, s64, s51
	global_load_lds_dwordx4 v144, s[44:45]
	s_mov_b32 m0, s72
	v_lshl_add_u64 v[226:227], s[46:47], 0, v[142:143]
	global_load_lds_dwordx4 v140, s[70:71]
	s_add_i32 m0, s72, 0x2000
	s_nop 0
	global_load_lds_dwordx4 v144, s[70:71]
	s_add_u32 s100, s46, 0x80
	s_addc_u32 s101, s47, 0
	s_mov_b32 m0, s41
	s_nop 0
	global_load_lds_dwordx4 v138, s[46:47]
	s_mov_b32 m0, s52
	s_nop 0
	global_load_lds_dwordx4 v142, s[46:47]
	s_waitcnt vmcnt(8)
	s_waitcnt lgkmcnt(0)
	s_barrier
	s_setprio 1
	s_waitcnt lgkmcnt(0)
	v_mfma_f32_16x16x32_bf16 v[62:65], v[130:133], v[190:193], v[62:65]
	v_mfma_f32_16x16x32_bf16 v[30:33], v[154:157], v[190:193], v[30:33]
	v_mfma_f32_16x16x32_bf16 v[54:57], v[130:133], v[198:201], v[54:57]
	v_mfma_f32_16x16x32_bf16 v[22:25], v[154:157], v[198:201], v[22:25]
	v_mfma_f32_16x16x32_bf16 v[50:53], v[130:133], v[206:209], v[50:53]
	v_mfma_f32_16x16x32_bf16 v[18:21], v[154:157], v[206:209], v[18:21]
	v_mfma_f32_16x16x32_bf16 v[38:41], v[130:133], v[214:217], v[38:41]
	v_mfma_f32_16x16x32_bf16 v[6:9], v[154:157], v[214:217], v[6:9]
	v_mfma_f32_16x16x32_bf16 v[62:65], v[134:137], v[194:197], v[62:65]
	v_mfma_f32_16x16x32_bf16 v[30:33], v[158:161], v[194:197], v[30:33]
	v_mfma_f32_16x16x32_bf16 v[54:57], v[134:137], v[202:205], v[54:57]
	v_mfma_f32_16x16x32_bf16 v[22:25], v[158:161], v[202:205], v[22:25]
	v_mfma_f32_16x16x32_bf16 v[50:53], v[134:137], v[210:213], v[50:53]
	v_mfma_f32_16x16x32_bf16 v[18:21], v[158:161], v[210:213], v[18:21]
	v_mfma_f32_16x16x32_bf16 v[38:41], v[134:137], v[218:221], v[38:41]
	v_mfma_f32_16x16x32_bf16 v[6:9], v[158:161], v[218:221], v[6:9]
	s_setprio 0
	s_setprio 1
	v_mfma_f32_16x16x32_bf16 v[58:61], v[162:165], v[190:193], v[58:61]
	v_mfma_f32_16x16x32_bf16 v[26:29], v[170:173], v[190:193], v[26:29]
	v_mfma_f32_16x16x32_bf16 v[46:49], v[162:165], v[198:201], v[46:49]
	v_mfma_f32_16x16x32_bf16 v[14:17], v[170:173], v[198:201], v[14:17]
	v_mfma_f32_16x16x32_bf16 v[42:45], v[162:165], v[206:209], v[42:45]
	v_mfma_f32_16x16x32_bf16 v[10:13], v[170:173], v[206:209], v[10:13]
	v_mfma_f32_16x16x32_bf16 v[34:37], v[162:165], v[214:217], v[34:37]
	v_mfma_f32_16x16x32_bf16 v[2:5], v[170:173], v[214:217], v[2:5]
	v_mfma_f32_16x16x32_bf16 v[58:61], v[166:169], v[194:197], v[58:61]
	v_mfma_f32_16x16x32_bf16 v[26:29], v[186:189], v[194:197], v[26:29]
	v_mfma_f32_16x16x32_bf16 v[46:49], v[166:169], v[202:205], v[46:49]
	v_mfma_f32_16x16x32_bf16 v[14:17], v[186:189], v[202:205], v[14:17]
	v_mfma_f32_16x16x32_bf16 v[42:45], v[166:169], v[210:213], v[42:45]
	v_mfma_f32_16x16x32_bf16 v[10:13], v[186:189], v[210:213], v[10:13]
	v_mfma_f32_16x16x32_bf16 v[34:37], v[166:169], v[218:221], v[34:37]
	v_mfma_f32_16x16x32_bf16 v[2:5], v[186:189], v[218:221], v[2:5]
	s_setprio 0
	s_barrier
; #define PG8_STAGE(bufoff, gbase, voff) do { _Pragma("unroll") for (int _i = 0; _i < 2; ++_i) \
;         __builtin_amdgcn_global_load_lds((const unsigned*)((const char*)(gbase) + (voff)[_i]), (PG8_LAS unsigned*)(lds + (bufoff) + ldsw + _i * 8192), 16, 0, 0); } while (0)
; #define PG8_LDA(dst, b, h) do { _Pragma("unroll") for (int m = 0; m < 4; ++m) _Pragma("unroll") for (int k = 0; k < 2; ++k) dst[m][k] = *(const PG8_LAS bf16x8*)(lds + PG8_SA(b, h) + aoff + m * 2048 + k * 1024); } while (0)
; #define PG8_LDB(dst, b, h) do { _Pragma("unroll") for (int n = 0; n < 2; ++n) _Pragma("unroll") for (int k = 0; k < 2; ++k) dst[n][k] = *(const PG8_LAS bf16x8*)(lds + PG8_SB(b, h) + boff + n * 2048 + k * 1024); } while (0)
; #define PG8_MMA(ai, bj, At, Bt) do { __builtin_amdgcn_s_setprio(1); _Pragma("unroll") for (int m = 0; m < 4; ++m) _Pragma("unroll") for (int n = 0; n < 2; ++n) _Pragma("unroll") for (int k = 0; k < 2; ++k) \
;         acc[ai][bj][m][n] = __builtin_amdgcn_mfma_f32_16x16x32_bf16(Bt[n][k], At[m][k], acc[ai][bj][m][n], 0, 0, 0); __builtin_amdgcn_s_setprio(0); } while (0)
; #define PG8_WAIT_V(n) asm volatile("s_waitcnt vmcnt(" #n ")" ::: "memory")
; #define PG8_WAIT_L(n) asm volatile("s_waitcnt lgkmcnt(" #n ")" ::: "memory")
; #define PG8_BAR __builtin_amdgcn_s_barrier()
; #define PG8_SCHED __builtin_amdgcn_sched_barrier(0)
; template <class Epi, class Sched, bool ALIGN_EPI = false, bool SP2 = false>
; __device__ __forceinline__ void gemm_phase(PG8_LAS unsigned char* lds, const Gemm g, const Sched& S, const Epi& E) {
;     ...
;             PG8_LDB(B0, 1, 0); PG8_LDB(B1, 1, 1); PG8_SCHED; PG8_LDA(At, 1, 0); PG8_STAGE(PG8_SA(0, 1), a2 + hstepA, voffA);
;             PG8_WAIT_V(8); PG8_WAIT_L(0); PG8_BAR; PG8_MMA(0, 0, At, B0); PG8_MMA(0, 1, At, B1); PG8_BAR; PG8_SCHED;
;             PG8_LDA(At, 1, 1); PG8_STAGE(PG8_SB(1, 0), b3, voffB); PG8_STAGE(PG8_SB(1, 1), b3 + hstepB, voffB); PG8_STAGE(PG8_SA(1, 0), a3, voffA);
;             PG8_WAIT_V(8); PG8_WAIT_L(0); PG8_BAR; PG8_MMA(1, 0, At, B0); PG8_MMA(1, 1, At, B1); PG8_BAR; PG8_SCHED;
	s_add_i32 s70, 0, 0x18000
	s_add_i32 s71, 0, 0x1c000
	v_add_u32_e32 v158, s70, v176
	v_add_u32_e32 v185, s71, v176
	ds_read_b128 v[130:133], v158
	ds_read_b128 v[134:137], v158 offset:1024
	ds_read_b128 v[154:157], v158 offset:2048
	ds_read_b128 v[158:161], v158 offset:3072
	ds_read_b128 v[162:165], v185
	ds_read_b128 v[166:169], v185 offset:1024
	ds_read_b128 v[170:173], v185 offset:2048
	ds_read_b128 v[186:189], v185 offset:3072
	s_add_u32 s46, s46, 0x40000
	s_addc_u32 s47, s47, 0
	s_mov_b32 m0, s53
	ds_read_b128 v[190:193], v184 offset:32768
	ds_read_b128 v[194:197], v184 offset:33792
	ds_read_b128 v[198:201], v184 offset:34816
	ds_read_b128 v[202:205], v184 offset:35840
	ds_read_b128 v[206:209], v184 offset:36864
	ds_read_b128 v[210:213], v184 offset:37888
	ds_read_b128 v[214:217], v184 offset:38912
	ds_read_b128 v[218:221], v184 offset:39936
	global_load_lds_dwordx4 v138, s[46:47]
	s_mov_b32 m0, s54
	s_nop 0
	global_load_lds_dwordx4 v142, s[46:47]
	s_waitcnt vmcnt(8)
	s_waitcnt lgkmcnt(0)
	s_barrier
	s_setprio 1
	s_waitcnt lgkmcnt(0)
	v_mfma_f32_16x16x32_bf16 v[126:129], v[130:133], v[190:193], v[126:129]
	v_mfma_f32_16x16x32_bf16 v[94:97], v[154:157], v[190:193], v[94:97]
	v_mfma_f32_16x16x32_bf16 v[118:121], v[130:133], v[198:201], v[118:121]
	v_mfma_f32_16x16x32_bf16 v[86:89], v[154:157], v[198:201], v[86:89]
	v_mfma_f32_16x16x32_bf16 v[114:117], v[130:133], v[206:209], v[114:117]
	v_mfma_f32_16x16x32_bf16 v[82:85], v[154:157], v[206:209], v[82:85]
	v_mfma_f32_16x16x32_bf16 v[102:105], v[130:133], v[214:217], v[102:105]
	v_mfma_f32_16x16x32_bf16 v[70:73], v[154:157], v[214:217], v[70:73]
	v_mfma_f32_16x16x32_bf16 v[126:129], v[134:137], v[194:197], v[126:129]
	v_mfma_f32_16x16x32_bf16 v[94:97], v[158:161], v[194:197], v[94:97]
	v_mfma_f32_16x16x32_bf16 v[118:121], v[134:137], v[202:205], v[118:121]
	v_mfma_f32_16x16x32_bf16 v[86:89], v[158:161], v[202:205], v[86:89]
	v_mfma_f32_16x16x32_bf16 v[114:117], v[134:137], v[210:213], v[114:117]
	v_mfma_f32_16x16x32_bf16 v[82:85], v[158:161], v[210:213], v[82:85]
	v_mfma_f32_16x16x32_bf16 v[102:105], v[134:137], v[218:221], v[102:105]
	v_mfma_f32_16x16x32_bf16 v[70:73], v[158:161], v[218:221], v[70:73]
	s_setprio 0
	s_setprio 1
	v_mfma_f32_16x16x32_bf16 v[122:125], v[162:165], v[190:193], v[122:125]
	v_mfma_f32_16x16x32_bf16 v[90:93], v[170:173], v[190:193], v[90:93]
	v_mfma_f32_16x16x32_bf16 v[110:113], v[162:165], v[198:201], v[110:113]
	v_mfma_f32_16x16x32_bf16 v[78:81], v[170:173], v[198:201], v[78:81]
	v_mfma_f32_16x16x32_bf16 v[106:109], v[162:165], v[206:209], v[106:109]
	v_mfma_f32_16x16x32_bf16 v[74:77], v[170:173], v[206:209], v[74:77]
	v_mfma_f32_16x16x32_bf16 v[98:101], v[162:165], v[214:217], v[98:101]
	v_mfma_f32_16x16x32_bf16 v[66:69], v[170:173], v[214:217], v[66:69]
	v_mfma_f32_16x16x32_bf16 v[122:125], v[166:169], v[194:197], v[122:125]
	v_mfma_f32_16x16x32_bf16 v[90:93], v[186:189], v[194:197], v[90:93]
	v_mfma_f32_16x16x32_bf16 v[110:113], v[166:169], v[202:205], v[110:113]
	v_mfma_f32_16x16x32_bf16 v[78:81], v[186:189], v[202:205], v[78:81]
	v_mfma_f32_16x16x32_bf16 v[106:109], v[166:169], v[210:213], v[106:109]
	v_mfma_f32_16x16x32_bf16 v[74:77], v[186:189], v[210:213], v[74:77]
	v_mfma_f32_16x16x32_bf16 v[98:101], v[166:169], v[218:221], v[98:101]
	v_mfma_f32_16x16x32_bf16 v[66:69], v[186:189], v[218:221], v[66:69]
	s_setprio 0
	s_barrier
	s_add_i32 s46, s70, s51
	s_mov_b32 m0, s46
	ds_read_b128 v[190:193], v184 offset:49152
	ds_read_b128 v[194:197], v184 offset:50176
	ds_read_b128 v[198:201], v184 offset:51200
	ds_read_b128 v[202:205], v184 offset:52224
	ds_read_b128 v[206:209], v184 offset:53248
	ds_read_b128 v[210:213], v184 offset:54272
	ds_read_b128 v[214:217], v184 offset:55296
	ds_read_b128 v[218:221], v184 offset:56320
	global_load_lds_dwordx4 v140, s[98:99]
	s_add_i32 m0, s46, 0x2000
	s_add_u32 s44, s44, 0x40080
	s_addc_u32 s45, s45, 0
	s_add_i32 s46, s71, s51
	global_load_lds_dwordx4 v144, s[98:99]
	s_mov_b32 m0, s46
	s_nop 0
	global_load_lds_dwordx4 v140, s[44:45]
	s_add_i32 m0, s46, 0x2000
	s_nop 0
	global_load_lds_dwordx4 v144, s[44:45]
	s_mov_b32 m0, s59
	s_nop 0
	global_load_lds_dwordx4 v138, s[100:101]
	v_lshl_add_u64 v[174:175], v[226:227], 0, s[24:25]
	s_mov_b32 m0, s60
	s_nop 0
	global_load_lds_dwordx4 v142, s[100:101]
	s_waitcnt vmcnt(8)
	s_waitcnt lgkmcnt(0)
	s_barrier
	s_setprio 1
	s_waitcnt lgkmcnt(0)
	v_mfma_f32_16x16x32_bf16 v[62:65], v[130:133], v[190:193], v[62:65]
	v_mfma_f32_16x16x32_bf16 v[30:33], v[154:157], v[190:193], v[30:33]
	v_mfma_f32_16x16x32_bf16 v[54:57], v[130:133], v[198:201], v[54:57]
	v_mfma_f32_16x16x32_bf16 v[22:25], v[154:157], v[198:201], v[22:25]
	v_mfma_f32_16x16x32_bf16 v[50:53], v[130:133], v[206:209], v[50:53]
	v_mfma_f32_16x16x32_bf16 v[18:21], v[154:157], v[206:209], v[18:21]
	v_mfma_f32_16x16x32_bf16 v[38:41], v[130:133], v[214:217], v[38:41]
	v_mfma_f32_16x16x32_bf16 v[6:9], v[154:157], v[214:217], v[6:9]
	v_mfma_f32_16x16x32_bf16 v[62:65], v[134:137], v[194:197], v[62:65]
	v_mfma_f32_16x16x32_bf16 v[30:33], v[158:161], v[194:197], v[30:33]
	v_mfma_f32_16x16x32_bf16 v[54:57], v[134:137], v[202:205], v[54:57]
	v_mfma_f32_16x16x32_bf16 v[22:25], v[158:161], v[202:205], v[22:25]
	v_mfma_f32_16x16x32_bf16 v[50:53], v[134:137], v[210:213], v[50:53]
	v_mfma_f32_16x16x32_bf16 v[18:21], v[158:161], v[210:213], v[18:21]
	v_mfma_f32_16x16x32_bf16 v[38:41], v[134:137], v[218:221], v[38:41]
	v_mfma_f32_16x16x32_bf16 v[6:9], v[158:161], v[218:221], v[6:9]
	s_setprio 0
	s_setprio 1
	v_mfma_f32_16x16x32_bf16 v[58:61], v[162:165], v[190:193], v[58:61]
	v_mfma_f32_16x16x32_bf16 v[26:29], v[170:173], v[190:193], v[26:29]
	v_mfma_f32_16x16x32_bf16 v[46:49], v[162:165], v[198:201], v[46:49]
	v_mfma_f32_16x16x32_bf16 v[14:17], v[170:173], v[198:201], v[14:17]
	v_mfma_f32_16x16x32_bf16 v[42:45], v[162:165], v[206:209], v[42:45]
	v_mfma_f32_16x16x32_bf16 v[10:13], v[170:173], v[206:209], v[10:13]
	v_mfma_f32_16x16x32_bf16 v[34:37], v[162:165], v[214:217], v[34:37]
	v_mfma_f32_16x16x32_bf16 v[2:5], v[170:173], v[214:217], v[2:5]
	v_mfma_f32_16x16x32_bf16 v[58:61], v[166:169], v[194:197], v[58:61]
	v_mfma_f32_16x16x32_bf16 v[26:29], v[186:189], v[194:197], v[26:29]
	v_mfma_f32_16x16x32_bf16 v[46:49], v[166:169], v[202:205], v[46:49]
	v_mfma_f32_16x16x32_bf16 v[14:17], v[186:189], v[202:205], v[14:17]
	v_mfma_f32_16x16x32_bf16 v[42:45], v[166:169], v[210:213], v[42:45]
	v_mfma_f32_16x16x32_bf16 v[10:13], v[186:189], v[210:213], v[10:13]
	v_mfma_f32_16x16x32_bf16 v[34:37], v[166:169], v[218:221], v[34:37]
	v_mfma_f32_16x16x32_bf16 v[2:5], v[186:189], v[218:221], v[2:5]
	s_setprio 0
	s_barrier
	s_add_i32 s69, s69, 2
	s_add_u32 s42, s42, 0x100
	s_addc_u32 s43, s43, 0
	s_add_u32 s67, s67, 0x100
	s_addc_u32 s68, s68, 0
	s_cmp_gt_u32 s69, 13
	s_cbranch_scc0 .LBB0_1528
	s_and_b64 vcc, exec, s[26:27]
	s_cbranch_vccz .LBB0_1531
	s_barrier

; #define PG8_STAGE(bufoff, gbase, voff) do { _Pragma("unroll") for (int _i = 0; _i < 2; ++_i) \
;         __builtin_amdgcn_global_load_lds((const unsigned*)((const char*)(gbase) + (voff)[_i]), (PG8_LAS unsigned*)(lds + (bufoff) + ldsw + _i * 8192), 16, 0, 0); } while (0)
; #define PG8_LDA(dst, b, h) do { _Pragma("unroll") for (int m = 0; m < 4; ++m) _Pragma("unroll") for (int k = 0; k < 2; ++k) dst[m][k] = *(const PG8_LAS bf16x8*)(lds + PG8_SA(b, h) + aoff + m * 2048 + k * 1024); } while (0)
; #define PG8_LDB(dst, b, h) do { _Pragma("unroll") for (int n = 0; n < 2; ++n) _Pragma("unroll") for (int k = 0; k < 2; ++k) dst[n][k] = *(const PG8_LAS bf16x8*)(lds + PG8_SB(b, h) + boff + n * 2048 + k * 1024); } while (0)
; #define PG8_MMA(ai, bj, At, Bt) do { __builtin_amdgcn_s_setprio(1); _Pragma("unroll") for (int m = 0; m < 4; ++m) _Pragma("unroll") for (int n = 0; n < 2; ++n) _Pragma("unroll") for (int k = 0; k < 2; ++k) \
;         acc[ai][bj][m][n] = __builtin_amdgcn_mfma_f32_16x16x32_bf16(Bt[n][k], At[m][k], acc[ai][bj][m][n], 0, 0, 0); __builtin_amdgcn_s_setprio(0); } while (0)
; #define PG8_WAIT_V(n) asm volatile("s_waitcnt vmcnt(" #n ")" ::: "memory")
; #define PG8_WAIT_L(n) asm volatile("s_waitcnt lgkmcnt(" #n ")" ::: "memory")
; template <class Epi, class Sched, bool ALIGN_EPI = false, bool SP2 = false>
; __device__ __forceinline__ void gemm_phase(PG8_LAS unsigned char* lds, const Gemm g, const Sched& S, const Epi& E) {
;     ...
;             const bool last = (t == nt - 2);
;             const char* a1 = cA + (size_t)(t + 1) * kstep;
;             const char* a2 = last ? nA : cA + (size_t)(t + 2) * kstep; const char* b2 = last ? nB : cB + (size_t)(t + 2) * kstep;
;             const char* a3 = a2 + kstep; const char* b3 = b2 + kstep;
;             if (last && has_next) S.a_ready(nxt);
;             if constexpr (SP2) {
;             PG8_LDB(B0, 0, 0); PG8_LDB(B1, 0, 1); PG8_SCHED; PG8_LDA(At, 0, 0); PG8_STAGE(PG8_SA(1, 1), a1 + hstepA, voffA);
;             PG8_WAIT_V(8); PG8_WAIT_L(0); PG8_BAR; PG8_MMA(0, 0, At, B0); PG8_MMA(0, 1, At, B1); PG8_BAR; PG8_SCHED;
;             PG8_LDA(At, 0, 1); PG8_STAGE(PG8_SB(0, 0), b2, voffB); PG8_STAGE(PG8_SB(0, 1), b2 + hstepB, voffB); PG8_STAGE(PG8_SA(0, 0), a2, voffA);
;             PG8_WAIT_V(8); PG8_WAIT_L(0); PG8_BAR; PG8_MMA(1, 0, At, B0); PG8_MMA(1, 1, At, B1); PG8_BAR; PG8_SCHED;
.LBB0_1838:
	v_add_u32_e32 v24, s50, v22
	ds_read_b128 v[34:37], v24
	ds_read_b128 v[38:41], v24 offset:1024
	ds_read_b128 v[42:45], v24 offset:2048
	ds_read_b128 v[46:49], v24 offset:3072
	v_add_u32_e32 v24, s51, v22
	s_add_u32 s22, s14, s20
	ds_read_b128 v[50:53], v24
	ds_read_b128 v[54:57], v24 offset:1024
	ds_read_b128 v[66:69], v24 offset:2048
	ds_read_b128 v[70:73], v24 offset:3072
	s_addc_u32 s23, s15, s21
	s_add_u32 s22, s22, 0x100
	s_addc_u32 s23, s23, 0
	s_add_u32 s58, s55, s20
	s_addc_u32 s59, s56, s21
	s_cmpk_eq_i32 s20, 0x1500
	s_cselect_b32 s25, s19, s23
	s_cselect_b32 s24, s18, s22
	s_cselect_b32 s23, s1, s59
	s_cselect_b32 s22, s0, s58
	v_lshl_add_u64 v[24:25], v[18:19], 0, s[20:21]
	s_add_i32 m0, s42, 0xc000
	ds_read_b128 v[162:165], v23
	ds_read_b128 v[166:169], v23 offset:1024
	ds_read_b128 v[194:197], v23 offset:2048
	ds_read_b128 v[198:201], v23 offset:3072
	ds_read_b128 v[202:205], v23 offset:4096
	ds_read_b128 v[206:209], v23 offset:5120
	ds_read_b128 v[210:213], v23 offset:6144
	ds_read_b128 v[216:219], v23 offset:7168
	global_load_lds_dwordx4 v[24:25], off
	v_lshl_add_u64 v[24:25], v[20:21], 0, s[20:21]
	s_add_i32 m0, s42, 0xe000
	s_nop 0
	global_load_lds_dwordx4 v[24:25], off
	s_waitcnt vmcnt(8)
	s_waitcnt lgkmcnt(0)
	s_barrier
	s_setprio 1
	s_waitcnt lgkmcnt(0)
	v_mfma_f32_16x16x32_bf16 v[170:173], v[34:37], v[162:165], v[170:173]
	v_mfma_f32_16x16x32_bf16 v[174:177], v[42:45], v[162:165], v[174:177]
	v_mfma_f32_16x16x32_bf16 v[178:181], v[34:37], v[194:197], v[178:181]
	v_mfma_f32_16x16x32_bf16 v[182:185], v[42:45], v[194:197], v[182:185]
	v_mfma_f32_16x16x32_bf16 v[186:189], v[34:37], v[202:205], v[186:189]
	v_mfma_f32_16x16x32_bf16 v[190:193], v[42:45], v[202:205], v[190:193]
	v_mfma_f32_16x16x32_bf16 v[158:161], v[34:37], v[210:213], v[158:161]
	v_mfma_f32_16x16x32_bf16 v[154:157], v[42:45], v[210:213], v[154:157]
	v_mfma_f32_16x16x32_bf16 v[170:173], v[38:41], v[166:169], v[170:173]
	v_mfma_f32_16x16x32_bf16 v[174:177], v[46:49], v[166:169], v[174:177]
	v_mfma_f32_16x16x32_bf16 v[178:181], v[38:41], v[198:201], v[178:181]
	v_mfma_f32_16x16x32_bf16 v[182:185], v[46:49], v[198:201], v[182:185]
	v_mfma_f32_16x16x32_bf16 v[186:189], v[38:41], v[206:209], v[186:189]
	v_mfma_f32_16x16x32_bf16 v[190:193], v[46:49], v[206:209], v[190:193]
	v_mfma_f32_16x16x32_bf16 v[158:161], v[38:41], v[216:219], v[158:161]
	v_mfma_f32_16x16x32_bf16 v[154:157], v[46:49], v[216:219], v[154:157]
	s_setprio 0
	s_setprio 1
	v_mfma_f32_16x16x32_bf16 v[62:65], v[50:53], v[162:165], v[62:65]
	v_mfma_f32_16x16x32_bf16 v[58:61], v[66:69], v[162:165], v[58:61]
	v_mfma_f32_16x16x32_bf16 v[74:77], v[50:53], v[194:197], v[74:77]
	v_mfma_f32_16x16x32_bf16 v[78:81], v[66:69], v[194:197], v[78:81]
	v_mfma_f32_16x16x32_bf16 v[90:93], v[50:53], v[202:205], v[90:93]
	v_mfma_f32_16x16x32_bf16 v[94:97], v[66:69], v[202:205], v[94:97]
	v_mfma_f32_16x16x32_bf16 v[106:109], v[50:53], v[210:213], v[106:109]
	v_mfma_f32_16x16x32_bf16 v[110:113], v[66:69], v[210:213], v[110:113]
	v_mfma_f32_16x16x32_bf16 v[62:65], v[54:57], v[166:169], v[62:65]
	v_mfma_f32_16x16x32_bf16 v[58:61], v[70:73], v[166:169], v[58:61]
	v_mfma_f32_16x16x32_bf16 v[74:77], v[54:57], v[198:201], v[74:77]
	v_mfma_f32_16x16x32_bf16 v[78:81], v[70:73], v[198:201], v[78:81]
	v_mfma_f32_16x16x32_bf16 v[90:93], v[54:57], v[206:209], v[90:93]
	v_mfma_f32_16x16x32_bf16 v[94:97], v[70:73], v[206:209], v[94:97]
	v_mfma_f32_16x16x32_bf16 v[106:109], v[54:57], v[216:219], v[106:109]
	v_mfma_f32_16x16x32_bf16 v[110:113], v[70:73], v[216:219], v[110:113]
	s_setprio 0
	s_barrier
	s_add_i32 s58, s50, s41
	s_add_u32 s98, s22, 0x80
	s_addc_u32 s99, s23, 0
	s_mov_b32 m0, s58
	ds_read_b128 v[162:165], v23 offset:16384
	ds_read_b128 v[166:169], v23 offset:17408
	ds_read_b128 v[194:197], v23 offset:18432
	ds_read_b128 v[198:201], v23 offset:19456
	ds_read_b128 v[202:205], v23 offset:20480
	ds_read_b128 v[206:209], v23 offset:21504
	ds_read_b128 v[210:213], v23 offset:22528
	ds_read_b128 v[216:219], v23 offset:23552
	global_load_lds_dwordx4 v4, s[22:23]
	s_add_i32 m0, s58, 0x2000
	s_add_u32 s58, s22, 0xb0000
	s_addc_u32 s59, s23, 0
	s_add_i32 s60, s51, s41
	global_load_lds_dwordx4 v8, s[22:23]
	s_mov_b32 m0, s60
	s_add_u32 s100, s24, 0x80
	s_addc_u32 s101, s25, 0
	global_load_lds_dwordx4 v4, s[58:59]
	s_add_i32 m0, s60, 0x2000
	s_nop 0
	global_load_lds_dwordx4 v8, s[58:59]
	s_mov_b32 m0, s42
	s_nop 0
	global_load_lds_dwordx4 v2, s[24:25]
	s_mov_b32 m0, s43
	s_nop 0
	global_load_lds_dwordx4 v6, s[24:25]
	s_waitcnt vmcnt(8)
	s_waitcnt lgkmcnt(0)
	s_barrier
; #define PG8_STAGE(bufoff, gbase, voff) do { _Pragma("unroll") for (int _i = 0; _i < 2; ++_i) \
;         __builtin_amdgcn_global_load_lds((const unsigned*)((const char*)(gbase) + (voff)[_i]), (PG8_LAS unsigned*)(lds + (bufoff) + ldsw + _i * 8192), 16, 0, 0); } while (0)
; #define PG8_LDA(dst, b, h) do { _Pragma("unroll") for (int m = 0; m < 4; ++m) _Pragma("unroll") for (int k = 0; k < 2; ++k) dst[m][k] = *(const PG8_LAS bf16x8*)(lds + PG8_SA(b, h) + aoff + m * 2048 + k * 1024); } while (0)
; #define PG8_LDB(dst, b, h) do { _Pragma("unroll") for (int n = 0; n < 2; ++n) _Pragma("unroll") for (int k = 0; k < 2; ++k) dst[n][k] = *(const PG8_LAS bf16x8*)(lds + PG8_SB(b, h) + boff + n * 2048 + k * 1024); } while (0)
; #define PG8_MMA(ai, bj, At, Bt) do { __builtin_amdgcn_s_setprio(1); _Pragma("unroll") for (int m = 0; m < 4; ++m) _Pragma("unroll") for (int n = 0; n < 2; ++n) _Pragma("unroll") for (int k = 0; k < 2; ++k) \
;         acc[ai][bj][m][n] = __builtin_amdgcn_mfma_f32_16x16x32_bf16(Bt[n][k], At[m][k], acc[ai][bj][m][n], 0, 0, 0); __builtin_amdgcn_s_setprio(0); } while (0)
; #define PG8_WAIT_V(n) asm volatile("s_waitcnt vmcnt(" #n ")" ::: "memory")
; #define PG8_WAIT_L(n) asm volatile("s_waitcnt lgkmcnt(" #n ")" ::: "memory")
; #define PG8_BAR __builtin_amdgcn_s_barrier()
; #define PG8_SCHED __builtin_amdgcn_sched_barrier(0)
; template <class Epi, class Sched, bool ALIGN_EPI = false, bool SP2 = false>
; __device__ __forceinline__ void gemm_phase(PG8_LAS unsigned char* lds, const Gemm g, const Sched& S, const Epi& E) {
;     ...
;             PG8_WAIT_V(8); PG8_WAIT_L(0); PG8_BAR; PG8_MMA(1, 0, At, B0); PG8_MMA(1, 1, At, B1); PG8_BAR; PG8_SCHED;
;             PG8_LDB(B0, 1, 0); PG8_LDB(B1, 1, 1); PG8_SCHED; PG8_LDA(At, 1, 0); PG8_STAGE(PG8_SA(0, 1), a2 + hstepA, voffA);
;             PG8_WAIT_V(8); PG8_WAIT_L(0); PG8_BAR; PG8_MMA(0, 0, At, B0); PG8_MMA(0, 1, At, B1); PG8_BAR; PG8_SCHED;
	s_setprio 1
	s_waitcnt lgkmcnt(0)
	v_mfma_f32_16x16x32_bf16 v[150:153], v[34:37], v[162:165], v[150:153]
	v_mfma_f32_16x16x32_bf16 v[146:149], v[42:45], v[162:165], v[146:149]
	v_mfma_f32_16x16x32_bf16 v[142:145], v[34:37], v[194:197], v[142:145]
	v_mfma_f32_16x16x32_bf16 v[138:141], v[42:45], v[194:197], v[138:141]
	v_mfma_f32_16x16x32_bf16 v[134:137], v[34:37], v[202:205], v[134:137]
	v_mfma_f32_16x16x32_bf16 v[130:133], v[42:45], v[202:205], v[130:133]
	v_mfma_f32_16x16x32_bf16 v[34:37], v[34:37], v[210:213], v[98:101]
	v_mfma_f32_16x16x32_bf16 v[150:153], v[38:41], v[166:169], v[150:153]
	v_mfma_f32_16x16x32_bf16 v[146:149], v[46:49], v[166:169], v[146:149]
	v_mfma_f32_16x16x32_bf16 v[142:145], v[38:41], v[198:201], v[142:145]
	v_mfma_f32_16x16x32_bf16 v[138:141], v[46:49], v[198:201], v[138:141]
	v_mfma_f32_16x16x32_bf16 v[134:137], v[38:41], v[206:209], v[134:137]
	v_mfma_f32_16x16x32_bf16 v[130:133], v[46:49], v[206:209], v[130:133]
	v_mfma_f32_16x16x32_bf16 v[34:37], v[38:41], v[216:219], v[34:37]
	v_mfma_f32_16x16x32_bf16 v[38:41], v[42:45], v[210:213], v[82:85]
	v_mfma_f32_16x16x32_bf16 v[38:41], v[46:49], v[216:219], v[38:41]
	s_setprio 0
	s_setprio 1
	v_mfma_f32_16x16x32_bf16 v[82:85], v[50:53], v[194:197], v[122:125]
	v_mfma_f32_16x16x32_bf16 v[122:125], v[54:57], v[198:201], v[82:85]
	v_mfma_f32_16x16x32_bf16 v[82:85], v[66:69], v[194:197], v[126:129]
	v_mfma_f32_16x16x32_bf16 v[126:129], v[70:73], v[198:201], v[82:85]
	v_mfma_f32_16x16x32_bf16 v[82:85], v[50:53], v[202:205], v[102:105]
	v_mfma_f32_16x16x32_bf16 v[102:105], v[54:57], v[206:209], v[82:85]
	v_mfma_f32_16x16x32_bf16 v[82:85], v[66:69], v[202:205], v[86:89]
	v_mfma_f32_16x16x32_bf16 v[30:33], v[50:53], v[210:213], v[30:33]
	v_mfma_f32_16x16x32_bf16 v[24:27], v[66:69], v[210:213], v[26:29]
	v_mfma_f32_16x16x32_bf16 v[42:45], v[50:53], v[162:165], v[114:117]
	v_mfma_f32_16x16x32_bf16 v[46:49], v[66:69], v[162:165], v[118:121]
	v_mfma_f32_16x16x32_bf16 v[86:89], v[70:73], v[206:209], v[82:85]
	v_mfma_f32_16x16x32_bf16 v[30:33], v[54:57], v[216:219], v[30:33]
	v_mfma_f32_16x16x32_bf16 v[24:27], v[70:73], v[216:219], v[24:27]
	v_mfma_f32_16x16x32_bf16 v[42:45], v[54:57], v[166:169], v[42:45]
	v_mfma_f32_16x16x32_bf16 v[46:49], v[70:73], v[166:169], v[46:49]
	s_setprio 0
	s_barrier
	s_add_i32 s58, 0, 0x18000
	v_add_u32_e32 v28, s58, v22
	s_add_i32 s59, 0, 0x1c000
	ds_read_b128 v[50:53], v28
	ds_read_b128 v[54:57], v28 offset:1024
	ds_read_b128 v[66:69], v28 offset:2048
	ds_read_b128 v[70:73], v28 offset:3072
	v_add_u32_e32 v28, s59, v22
	ds_read_b128 v[162:165], v28
	ds_read_b128 v[166:169], v28 offset:1024
	ds_read_b128 v[194:197], v28 offset:2048
	ds_read_b128 v[198:201], v28 offset:3072
	s_add_u32 s24, s24, 0xb0000
	s_addc_u32 s25, s25, 0
	s_mov_b32 m0, s45
	ds_read_b128 v[82:85], v23 offset:32768
	ds_read_b128 v[98:101], v23 offset:33792
	ds_read_b128 v[114:117], v23 offset:34816
	ds_read_b128 v[118:121], v23 offset:35840
	ds_read_b128 v[202:205], v23 offset:36864
	ds_read_b128 v[206:209], v23 offset:37888
	ds_read_b128 v[210:213], v23 offset:38912
	ds_read_b128 v[216:219], v23 offset:39936
	global_load_lds_dwordx4 v2, s[24:25]
	s_mov_b32 m0, s46
	s_nop 0
	global_load_lds_dwordx4 v6, s[24:25]
	s_waitcnt vmcnt(8)
	s_waitcnt lgkmcnt(0)
	s_barrier
	s_setprio 1
	s_waitcnt lgkmcnt(0)
	v_mfma_f32_16x16x32_bf16 v[170:173], v[50:53], v[82:85], v[170:173]
	v_mfma_f32_16x16x32_bf16 v[174:177], v[66:69], v[82:85], v[174:177]
	v_mfma_f32_16x16x32_bf16 v[178:181], v[50:53], v[114:117], v[178:181]
	v_mfma_f32_16x16x32_bf16 v[182:185], v[66:69], v[114:117], v[182:185]
	v_mfma_f32_16x16x32_bf16 v[186:189], v[50:53], v[202:205], v[186:189]
	v_mfma_f32_16x16x32_bf16 v[190:193], v[66:69], v[202:205], v[190:193]
	v_mfma_f32_16x16x32_bf16 v[158:161], v[50:53], v[210:213], v[158:161]
	v_mfma_f32_16x16x32_bf16 v[154:157], v[66:69], v[210:213], v[154:157]
	v_mfma_f32_16x16x32_bf16 v[170:173], v[54:57], v[98:101], v[170:173]
	v_mfma_f32_16x16x32_bf16 v[174:177], v[70:73], v[98:101], v[174:177]
	v_mfma_f32_16x16x32_bf16 v[178:181], v[54:57], v[118:121], v[178:181]
	v_mfma_f32_16x16x32_bf16 v[182:185], v[70:73], v[118:121], v[182:185]
	v_mfma_f32_16x16x32_bf16 v[186:189], v[54:57], v[206:209], v[186:189]
	v_mfma_f32_16x16x32_bf16 v[190:193], v[70:73], v[206:209], v[190:193]
	v_mfma_f32_16x16x32_bf16 v[158:161], v[54:57], v[216:219], v[158:161]
	v_mfma_f32_16x16x32_bf16 v[154:157], v[70:73], v[216:219], v[154:157]
	s_setprio 0
	s_setprio 1
	v_mfma_f32_16x16x32_bf16 v[62:65], v[162:165], v[82:85], v[62:65]
	v_mfma_f32_16x16x32_bf16 v[58:61], v[194:197], v[82:85], v[58:61]
	v_mfma_f32_16x16x32_bf16 v[82:85], v[162:165], v[202:205], v[90:93]
	v_mfma_f32_16x16x32_bf16 v[90:93], v[166:169], v[206:209], v[82:85]
	v_mfma_f32_16x16x32_bf16 v[82:85], v[194:197], v[202:205], v[94:97]
	v_mfma_f32_16x16x32_bf16 v[94:97], v[198:201], v[206:209], v[82:85]
	v_mfma_f32_16x16x32_bf16 v[82:85], v[162:165], v[210:213], v[106:109]
	v_mfma_f32_16x16x32_bf16 v[74:77], v[162:165], v[114:117], v[74:77]
	v_mfma_f32_16x16x32_bf16 v[78:81], v[194:197], v[114:117], v[78:81]
	v_mfma_f32_16x16x32_bf16 v[106:109], v[166:169], v[216:219], v[82:85]
	v_mfma_f32_16x16x32_bf16 v[82:85], v[194:197], v[210:213], v[110:113]
	v_mfma_f32_16x16x32_bf16 v[62:65], v[166:169], v[98:101], v[62:65]
	v_mfma_f32_16x16x32_bf16 v[58:61], v[198:201], v[98:101], v[58:61]
	v_mfma_f32_16x16x32_bf16 v[74:77], v[166:169], v[118:121], v[74:77]
	v_mfma_f32_16x16x32_bf16 v[78:81], v[198:201], v[118:121], v[78:81]
	v_mfma_f32_16x16x32_bf16 v[110:113], v[198:201], v[216:219], v[82:85]
	s_setprio 0
	s_barrier
; #define PG8_STAGE(bufoff, gbase, voff) do { _Pragma("unroll") for (int _i = 0; _i < 2; ++_i) \
;         __builtin_amdgcn_global_load_lds((const unsigned*)((const char*)(gbase) + (voff)[_i]), (PG8_LAS unsigned*)(lds + (bufoff) + ldsw + _i * 8192), 16, 0, 0); } while (0)
; #define PG8_LDA(dst, b, h) do { _Pragma("unroll") for (int m = 0; m < 4; ++m) _Pragma("unroll") for (int k = 0; k < 2; ++k) dst[m][k] = *(const PG8_LAS bf16x8*)(lds + PG8_SA(b, h) + aoff + m * 2048 + k * 1024); } while (0)
; #define PG8_MMA(ai, bj, At, Bt) do { __builtin_amdgcn_s_setprio(1); _Pragma("unroll") for (int m = 0; m < 4; ++m) _Pragma("unroll") for (int n = 0; n < 2; ++n) _Pragma("unroll") for (int k = 0; k < 2; ++k) \
;         acc[ai][bj][m][n] = __builtin_amdgcn_mfma_f32_16x16x32_bf16(Bt[n][k], At[m][k], acc[ai][bj][m][n], 0, 0, 0); __builtin_amdgcn_s_setprio(0); } while (0)
; #define PG8_WAIT_V(n) asm volatile("s_waitcnt vmcnt(" #n ")" ::: "memory")
; #define PG8_WAIT_L(n) asm volatile("s_waitcnt lgkmcnt(" #n ")" ::: "memory")
; #define PG8_BAR __builtin_amdgcn_s_barrier()
; #define PG8_SCHED __builtin_amdgcn_sched_barrier(0)
; template <class Epi, class Sched, bool ALIGN_EPI = false, bool SP2 = false>
; __device__ __forceinline__ void gemm_phase(PG8_LAS unsigned char* lds, const Gemm g, const Sched& S, const Epi& E) {
;     ...
;             PG8_LDA(At, 1, 1); PG8_STAGE(PG8_SB(1, 0), b3, voffB); PG8_STAGE(PG8_SB(1, 1), b3 + hstepB, voffB); PG8_STAGE(PG8_SA(1, 0), a3, voffA);
;             PG8_WAIT_V(8); PG8_WAIT_L(0); PG8_BAR; PG8_MMA(1, 0, At, B0); PG8_MMA(1, 1, At, B1); PG8_BAR; PG8_SCHED;
;     ...
; #pragma unroll
;         for (int a = 0; a < 2; ++a)
; #pragma unroll
;             for (int b = 0; b < 2; ++b)
; #pragma unroll
;                 for (int m = 0; m < 4; ++m)
; #pragma unroll
;                     for (int n = 0; n < 2; ++n) acc[a][b][m][n] = (f32x4){0.f, 0.f, 0.f, 0.f};
;         cur = nxt; cA = nA; cB = nB; ++ui;
	s_add_i32 s24, s58, s41
	s_mov_b32 m0, s24
	ds_read_b128 v[118:121], v23 offset:49152
	ds_read_b128 v[202:205], v23 offset:50176
	ds_read_b128 v[206:209], v23 offset:51200
	ds_read_b128 v[210:213], v23 offset:52224
	ds_read_b128 v[216:219], v23 offset:53248
	ds_read_b128 v[220:223], v23 offset:54272
	ds_read_b128 v[224:227], v23 offset:55296
	ds_read_b128 v[228:231], v23 offset:56320
	global_load_lds_dwordx4 v4, s[98:99]
	s_add_i32 m0, s24, 0x2000
	s_add_u32 s22, s22, 0xb0080
	s_addc_u32 s23, s23, 0
	s_add_i32 s24, s59, s41
	global_load_lds_dwordx4 v8, s[98:99]
	s_mov_b32 m0, s24
	s_nop 0
	global_load_lds_dwordx4 v4, s[22:23]
	s_add_i32 m0, s24, 0x2000
	s_nop 0
	global_load_lds_dwordx4 v8, s[22:23]
	s_mov_b32 m0, s48
	s_nop 0
	global_load_lds_dwordx4 v2, s[100:101]
	s_mov_b32 m0, s49
	s_nop 0
	global_load_lds_dwordx4 v6, s[100:101]
	s_waitcnt vmcnt(8)
	s_waitcnt lgkmcnt(0)
	s_barrier
	s_setprio 1
	s_waitcnt lgkmcnt(0)
	v_mfma_f32_16x16x32_bf16 v[82:85], v[50:53], v[118:121], v[150:153]
	v_mfma_f32_16x16x32_bf16 v[150:153], v[54:57], v[202:205], v[82:85]
	v_mfma_f32_16x16x32_bf16 v[82:85], v[66:69], v[118:121], v[146:149]
	v_mfma_f32_16x16x32_bf16 v[146:149], v[70:73], v[202:205], v[82:85]
	v_mfma_f32_16x16x32_bf16 v[82:85], v[50:53], v[206:209], v[142:145]
	v_mfma_f32_16x16x32_bf16 v[142:145], v[54:57], v[210:213], v[82:85]
	v_mfma_f32_16x16x32_bf16 v[82:85], v[66:69], v[206:209], v[138:141]
	v_mfma_f32_16x16x32_bf16 v[138:141], v[70:73], v[210:213], v[82:85]
	v_mfma_f32_16x16x32_bf16 v[82:85], v[50:53], v[216:219], v[134:137]
	v_mfma_f32_16x16x32_bf16 v[34:37], v[50:53], v[224:227], v[34:37]
	v_mfma_f32_16x16x32_bf16 v[134:137], v[54:57], v[220:223], v[82:85]
	v_mfma_f32_16x16x32_bf16 v[82:85], v[66:69], v[216:219], v[130:133]
	v_mfma_f32_16x16x32_bf16 v[98:101], v[54:57], v[228:231], v[34:37]
	v_mfma_f32_16x16x32_bf16 v[34:37], v[66:69], v[224:227], v[38:41]
	v_mfma_f32_16x16x32_bf16 v[130:133], v[70:73], v[220:223], v[82:85]
	v_mfma_f32_16x16x32_bf16 v[82:85], v[70:73], v[228:231], v[34:37]
	s_setprio 0
	s_setprio 1
	v_mfma_f32_16x16x32_bf16 v[34:37], v[162:165], v[118:121], v[42:45]
	v_mfma_f32_16x16x32_bf16 v[114:117], v[166:169], v[202:205], v[34:37]
	v_mfma_f32_16x16x32_bf16 v[34:37], v[194:197], v[118:121], v[46:49]
	v_mfma_f32_16x16x32_bf16 v[118:121], v[198:201], v[202:205], v[34:37]
	v_mfma_f32_16x16x32_bf16 v[34:37], v[162:165], v[206:209], v[122:125]
	v_mfma_f32_16x16x32_bf16 v[122:125], v[166:169], v[210:213], v[34:37]
	v_mfma_f32_16x16x32_bf16 v[34:37], v[194:197], v[206:209], v[126:129]
	v_mfma_f32_16x16x32_bf16 v[126:129], v[198:201], v[210:213], v[34:37]
	v_mfma_f32_16x16x32_bf16 v[34:37], v[162:165], v[216:219], v[102:105]
	v_mfma_f32_16x16x32_bf16 v[102:105], v[166:169], v[220:223], v[34:37]
	v_mfma_f32_16x16x32_bf16 v[34:37], v[194:197], v[216:219], v[86:89]
	v_mfma_f32_16x16x32_bf16 v[28:31], v[162:165], v[224:227], v[30:33]
	v_mfma_f32_16x16x32_bf16 v[24:27], v[194:197], v[224:227], v[24:27]
	v_mfma_f32_16x16x32_bf16 v[86:89], v[198:201], v[220:223], v[34:37]
	v_mfma_f32_16x16x32_bf16 v[30:33], v[166:169], v[228:231], v[28:31]
	v_mfma_f32_16x16x32_bf16 v[26:29], v[198:201], v[228:231], v[24:27]
	s_setprio 0
	s_barrier
	s_add_i32 s57, s57, 2
	s_add_u32 s20, s20, 0x100
	s_addc_u32 s21, s21, 0
	s_cmp_gt_u32 s57, 41
	s_cbranch_scc0 .LBB0_1838
	s_add_u32 s20, s55, 0xffffff00
	s_addc_u32 s21, s56, -1
	s_and_b64 vcc, exec, s[4:5]
	s_cbranch_vccnz .LBB0_1825
	v_mov_b32_e32 v26, 0
	s_mov_b32 s12, s52
	s_mov_b32 s27, s53
	s_mov_b64 s[14:15], s[18:19]
	s_mov_b32 s47, s54
	v_mov_b32_e32 v27, v26
	v_mov_b32_e32 v28, v26
	v_mov_b32_e32 v29, v26
	v_mov_b32_e32 v30, v26
	v_mov_b32_e32 v31, v26
	v_mov_b32_e32 v32, v26
	v_mov_b32_e32 v33, v26
	v_mov_b32_e32 v86, v26
	v_mov_b32_e32 v87, v26
	v_mov_b32_e32 v88, v26
	v_mov_b32_e32 v89, v26
	v_mov_b32_e32 v102, v26
	v_mov_b32_e32 v103, v26
	v_mov_b32_e32 v104, v26
	v_mov_b32_e32 v105, v26
	v_mov_b32_e32 v126, v26
	v_mov_b32_e32 v127, v26
	v_mov_b32_e32 v128, v26
	v_mov_b32_e32 v129, v26
	v_mov_b32_e32 v122, v26
	v_mov_b32_e32 v123, v26
	v_mov_b32_e32 v124, v26
	v_mov_b32_e32 v125, v26
	v_mov_b32_e32 v118, v26
	v_mov_b32_e32 v119, v26
	v_mov_b32_e32 v120, v26
	v_mov_b32_e32 v121, v26
	v_mov_b32_e32 v114, v26
	v_mov_b32_e32 v115, v26
	v_mov_b32_e32 v116, v26
	v_mov_b32_e32 v117, v26
	v_mov_b32_e32 v82, v26
	v_mov_b32_e32 v83, v26
	v_mov_b32_e32 v84, v26
	v_mov_b32_e32 v85, v26
	v_mov_b32_e32 v98, v26
	v_mov_b32_e32 v99, v26
	v_mov_b32_e32 v100, v26
	v_mov_b32_e32 v101, v26
	v_mov_b32_e32 v130, v26
	v_mov_b32_e32 v131, v26
	v_mov_b32_e32 v132, v26
	v_mov_b32_e32 v133, v26
	v_mov_b32_e32 v134, v26
	v_mov_b32_e32 v135, v26
	v_mov_b32_e32 v136, v26
	v_mov_b32_e32 v137, v26
	v_mov_b32_e32 v138, v26
	v_mov_b32_e32 v139, v26
	v_mov_b32_e32 v140, v26
	v_mov_b32_e32 v141, v26
	v_mov_b32_e32 v142, v26
	v_mov_b32_e32 v143, v26
	v_mov_b32_e32 v144, v26
	v_mov_b32_e32 v145, v26
	v_mov_b32_e32 v146, v26
	v_mov_b32_e32 v147, v26
	v_mov_b32_e32 v148, v26
	v_mov_b32_e32 v149, v26
	v_mov_b32_e32 v150, v26
	v_mov_b32_e32 v151, v26
	v_mov_b32_e32 v152, v26
	v_mov_b32_e32 v153, v26
	v_mov_b32_e32 v110, v26
	v_mov_b32_e32 v111, v26
	v_mov_b32_e32 v112, v26
	v_mov_b32_e32 v113, v26
	v_mov_b32_e32 v106, v26
	v_mov_b32_e32 v107, v26
	v_mov_b32_e32 v108, v26
	v_mov_b32_e32 v109, v26
	v_mov_b32_e32 v94, v26
	v_mov_b32_e32 v95, v26
	v_mov_b32_e32 v96, v26
	v_mov_b32_e32 v97, v26
	v_mov_b32_e32 v90, v26
	v_mov_b32_e32 v91, v26
	v_mov_b32_e32 v92, v26
	v_mov_b32_e32 v93, v26
	v_mov_b32_e32 v78, v26
	v_mov_b32_e32 v79, v26
	v_mov_b32_e32 v80, v26
	v_mov_b32_e32 v81, v26
	v_mov_b32_e32 v74, v26
	v_mov_b32_e32 v75, v26
	v_mov_b32_e32 v76, v26
	v_mov_b32_e32 v77, v26
	v_mov_b32_e32 v58, v26
	v_mov_b32_e32 v59, v26
	v_mov_b32_e32 v60, v26
	v_mov_b32_e32 v61, v26
	v_mov_b32_e32 v62, v26
	v_mov_b32_e32 v63, v26
	v_mov_b32_e32 v64, v26
	v_mov_b32_e32 v65, v26
	v_mov_b32_e32 v154, v26
	v_mov_b32_e32 v155, v26
	v_mov_b32_e32 v156, v26
	v_mov_b32_e32 v157, v26
	v_mov_b32_e32 v158, v26
	v_mov_b32_e32 v159, v26
	v_mov_b32_e32 v160, v26
	v_mov_b32_e32 v161, v26
	v_mov_b32_e32 v190, v26
	v_mov_b32_e32 v191, v26
	v_mov_b32_e32 v192, v26
	v_mov_b32_e32 v193, v26
	v_mov_b32_e32 v186, v26
	v_mov_b32_e32 v187, v26
	v_mov_b32_e32 v188, v26
	v_mov_b32_e32 v189, v26
	v_mov_b32_e32 v182, v26
	v_mov_b32_e32 v183, v26
	v_mov_b32_e32 v184, v26
	v_mov_b32_e32 v185, v26
	v_mov_b32_e32 v178, v26
	v_mov_b32_e32 v179, v26
	v_mov_b32_e32 v180, v26
	v_mov_b32_e32 v181, v26
	v_mov_b32_e32 v174, v26
	v_mov_b32_e32 v175, v26
	v_mov_b32_e32 v176, v26
	v_mov_b32_e32 v177, v26
	v_mov_b32_e32 v170, v26
	v_mov_b32_e32 v171, v26
	v_mov_b32_e32 v172, v26
	v_mov_b32_e32 v173, v26
	s_andn2_b64 vcc, exec, s[2:3]
	s_cbranch_vccnz .LBB0_1826

; #define PG8_STAGE(bufoff, gbase, voff) do { _Pragma("unroll") for (int _i = 0; _i < 2; ++_i) \
;         __builtin_amdgcn_global_load_lds((const unsigned*)((const char*)(gbase) + (voff)[_i]), (PG8_LAS unsigned*)(lds + (bufoff) + ldsw + _i * 8192), 16, 0, 0); } while (0)
; #define PG8_LDA(dst, b, h) do { _Pragma("unroll") for (int m = 0; m < 4; ++m) _Pragma("unroll") for (int k = 0; k < 2; ++k) dst[m][k] = *(const PG8_LAS bf16x8*)(lds + PG8_SA(b, h) + aoff + m * 2048 + k * 1024); } while (0)
; #define PG8_LDB(dst, b, h) do { _Pragma("unroll") for (int n = 0; n < 2; ++n) _Pragma("unroll") for (int k = 0; k < 2; ++k) dst[n][k] = *(const PG8_LAS bf16x8*)(lds + PG8_SB(b, h) + boff + n * 2048 + k * 1024); } while (0)
; #define PG8_MMA(ai, bj, At, Bt) do { __builtin_amdgcn_s_setprio(1); _Pragma("unroll") for (int m = 0; m < 4; ++m) _Pragma("unroll") for (int n = 0; n < 2; ++n) _Pragma("unroll") for (int k = 0; k < 2; ++k) \
;         acc[ai][bj][m][n] = __builtin_amdgcn_mfma_f32_16x16x32_bf16(Bt[n][k], At[m][k], acc[ai][bj][m][n], 0, 0, 0); __builtin_amdgcn_s_setprio(0); } while (0)
; #define PG8_WAIT_V(n) asm volatile("s_waitcnt vmcnt(" #n ")" ::: "memory")
; #define PG8_WAIT_L(n) asm volatile("s_waitcnt lgkmcnt(" #n ")" ::: "memory")
; template <class Epi, class Sched, bool ALIGN_EPI = false, bool SP2 = false>
; __device__ __forceinline__ void gemm_phase(PG8_LAS unsigned char* lds, const Gemm g, const Sched& S, const Epi& E) {
;     ...
;             const bool last = (t == nt - 2);
;             const char* a1 = cA + (size_t)(t + 1) * kstep;
;             const char* a2 = last ? nA : cA + (size_t)(t + 2) * kstep; const char* b2 = last ? nB : cB + (size_t)(t + 2) * kstep;
;             const char* a3 = a2 + kstep; const char* b3 = b2 + kstep;
;             if (last && has_next) S.a_ready(nxt);
;             if constexpr (SP2) {
;             PG8_LDB(B0, 0, 0); PG8_LDB(B1, 0, 1); PG8_SCHED; PG8_LDA(At, 0, 0); PG8_STAGE(PG8_SA(1, 1), a1 + hstepA, voffA);
;             PG8_WAIT_V(8); PG8_WAIT_L(0); PG8_BAR; PG8_MMA(0, 0, At, B0); PG8_MMA(0, 1, At, B1); PG8_BAR; PG8_SCHED;
;             PG8_LDA(At, 0, 1); PG8_STAGE(PG8_SB(0, 0), b2, voffB); PG8_STAGE(PG8_SB(0, 1), b2 + hstepB, voffB); PG8_STAGE(PG8_SA(0, 0), a2, voffA);
;             PG8_WAIT_V(8); PG8_WAIT_L(0); PG8_BAR; PG8_MMA(1, 0, At, B0); PG8_MMA(1, 1, At, B1); PG8_BAR; PG8_SCHED;
.LBB0_1897:
	ds_read_b128 v[130:133], v162
	ds_read_b128 v[134:137], v162 offset:1024
	ds_read_b128 v[138:141], v162 offset:2048
	ds_read_b128 v[142:145], v162 offset:3072
	ds_read_b128 v[156:159], v163
	ds_read_b128 v[166:169], v163 offset:1024
	ds_read_b128 v[170:173], v163 offset:2048
	ds_read_b128 v[174:177], v163 offset:3072
	s_add_u32 s22, s20, 0x100
	s_addc_u32 s23, s21, 0
	s_cmp_eq_u32 s68, 4
	s_cselect_b32 s27, s17, s23
	s_cselect_b32 s26, s16, s22
	s_cselect_b32 s25, s19, s67
	s_cselect_b32 s24, s18, s66
	v_lshl_add_u64 v[210:211], s[20:21], 0, v[152:153]
	s_add_i32 m0, s42, 0xc000
	ds_read_b128 v[178:181], v164
	ds_read_b128 v[182:185], v164 offset:1024
	ds_read_b128 v[186:189], v164 offset:2048
	ds_read_b128 v[190:193], v164 offset:3072
	ds_read_b128 v[194:197], v164 offset:4096
	ds_read_b128 v[198:201], v164 offset:5120
	ds_read_b128 v[202:205], v164 offset:6144
	ds_read_b128 v[206:209], v164 offset:7168
	global_load_lds_dwordx4 v[210:211], off
	v_lshl_add_u64 v[210:211], s[20:21], 0, v[154:155]
	s_add_i32 m0, s42, 0xe000
	s_nop 0
	global_load_lds_dwordx4 v[210:211], off
	s_waitcnt vmcnt(8)
	s_waitcnt lgkmcnt(0)
	s_barrier
	s_setprio 1
	s_waitcnt lgkmcnt(0)
	v_mfma_f32_16x16x32_bf16 v[126:129], v[130:133], v[178:181], v[126:129]
	v_mfma_f32_16x16x32_bf16 v[122:125], v[138:141], v[178:181], v[122:125]
	v_mfma_f32_16x16x32_bf16 v[118:121], v[130:133], v[186:189], v[118:121]
	v_mfma_f32_16x16x32_bf16 v[114:117], v[138:141], v[186:189], v[114:117]
	v_mfma_f32_16x16x32_bf16 v[102:105], v[130:133], v[194:197], v[102:105]
	v_mfma_f32_16x16x32_bf16 v[90:93], v[138:141], v[194:197], v[90:93]
	v_mfma_f32_16x16x32_bf16 v[82:85], v[130:133], v[202:205], v[82:85]
	v_mfma_f32_16x16x32_bf16 v[74:77], v[138:141], v[202:205], v[74:77]
	v_mfma_f32_16x16x32_bf16 v[126:129], v[134:137], v[182:185], v[126:129]
	v_mfma_f32_16x16x32_bf16 v[122:125], v[142:145], v[182:185], v[122:125]
	v_mfma_f32_16x16x32_bf16 v[118:121], v[134:137], v[190:193], v[118:121]
	v_mfma_f32_16x16x32_bf16 v[114:117], v[142:145], v[190:193], v[114:117]
	v_mfma_f32_16x16x32_bf16 v[102:105], v[134:137], v[198:201], v[102:105]
	v_mfma_f32_16x16x32_bf16 v[90:93], v[142:145], v[198:201], v[90:93]
	v_mfma_f32_16x16x32_bf16 v[82:85], v[134:137], v[206:209], v[82:85]
	v_mfma_f32_16x16x32_bf16 v[74:77], v[142:145], v[206:209], v[74:77]
	s_setprio 0
	s_setprio 1
	v_mfma_f32_16x16x32_bf16 v[110:113], v[156:159], v[178:181], v[110:113]
	v_mfma_f32_16x16x32_bf16 v[106:109], v[170:173], v[178:181], v[106:109]
	v_mfma_f32_16x16x32_bf16 v[98:101], v[156:159], v[186:189], v[98:101]
	v_mfma_f32_16x16x32_bf16 v[94:97], v[170:173], v[186:189], v[94:97]
	v_mfma_f32_16x16x32_bf16 v[86:89], v[156:159], v[194:197], v[86:89]
	v_mfma_f32_16x16x32_bf16 v[78:81], v[170:173], v[194:197], v[78:81]
	v_mfma_f32_16x16x32_bf16 v[70:73], v[156:159], v[202:205], v[70:73]
	v_mfma_f32_16x16x32_bf16 v[66:69], v[170:173], v[202:205], v[66:69]
	v_mfma_f32_16x16x32_bf16 v[110:113], v[166:169], v[182:185], v[110:113]
	v_mfma_f32_16x16x32_bf16 v[106:109], v[174:177], v[182:185], v[106:109]
	v_mfma_f32_16x16x32_bf16 v[98:101], v[166:169], v[190:193], v[98:101]
	v_mfma_f32_16x16x32_bf16 v[94:97], v[174:177], v[190:193], v[94:97]
	v_mfma_f32_16x16x32_bf16 v[86:89], v[166:169], v[198:201], v[86:89]
	v_mfma_f32_16x16x32_bf16 v[78:81], v[174:177], v[198:201], v[78:81]
	v_mfma_f32_16x16x32_bf16 v[70:73], v[166:169], v[206:209], v[70:73]
	v_mfma_f32_16x16x32_bf16 v[66:69], v[174:177], v[206:209], v[66:69]
	s_setprio 0
	s_barrier
	s_add_i32 s20, s54, s40
	s_add_u32 s98, s24, 0x80
	s_addc_u32 s99, s25, 0
	s_mov_b32 m0, s20
	ds_read_b128 v[178:181], v164 offset:16384
	ds_read_b128 v[182:185], v164 offset:17408
	ds_read_b128 v[186:189], v164 offset:18432
	ds_read_b128 v[190:193], v164 offset:19456
	ds_read_b128 v[194:197], v164 offset:20480
	ds_read_b128 v[198:201], v164 offset:21504
	ds_read_b128 v[202:205], v164 offset:22528
	ds_read_b128 v[206:209], v164 offset:23552
	global_load_lds_dwordx4 v148, s[24:25]
	s_add_i32 m0, s20, 0x2000
	s_add_u32 s20, s24, 0xb0000
	s_addc_u32 s21, s25, 0
	s_add_i32 s69, s55, s40
	global_load_lds_dwordx4 v146, s[24:25]
	s_mov_b32 m0, s69
	s_nop 0
	global_load_lds_dwordx4 v148, s[20:21]
	s_add_i32 m0, s69, 0x2000
	s_nop 0
	global_load_lds_dwordx4 v146, s[20:21]
	s_add_u32 s100, s26, 0x80
	s_addc_u32 s101, s27, 0
	s_mov_b32 m0, s42
	s_nop 0
	global_load_lds_dwordx4 v148, s[26:27]
	s_mov_b32 m0, s43
	s_nop 0
	global_load_lds_dwordx4 v146, s[26:27]
	s_waitcnt vmcnt(8)
	s_waitcnt lgkmcnt(0)
	s_barrier
; #define PG8_STAGE(bufoff, gbase, voff) do { _Pragma("unroll") for (int _i = 0; _i < 2; ++_i) \
;         __builtin_amdgcn_global_load_lds((const unsigned*)((const char*)(gbase) + (voff)[_i]), (PG8_LAS unsigned*)(lds + (bufoff) + ldsw + _i * 8192), 16, 0, 0); } while (0)
; #define PG8_LDA(dst, b, h) do { _Pragma("unroll") for (int m = 0; m < 4; ++m) _Pragma("unroll") for (int k = 0; k < 2; ++k) dst[m][k] = *(const PG8_LAS bf16x8*)(lds + PG8_SA(b, h) + aoff + m * 2048 + k * 1024); } while (0)
; #define PG8_LDB(dst, b, h) do { _Pragma("unroll") for (int n = 0; n < 2; ++n) _Pragma("unroll") for (int k = 0; k < 2; ++k) dst[n][k] = *(const PG8_LAS bf16x8*)(lds + PG8_SB(b, h) + boff + n * 2048 + k * 1024); } while (0)
; #define PG8_MMA(ai, bj, At, Bt) do { __builtin_amdgcn_s_setprio(1); _Pragma("unroll") for (int m = 0; m < 4; ++m) _Pragma("unroll") for (int n = 0; n < 2; ++n) _Pragma("unroll") for (int k = 0; k < 2; ++k) \
;         acc[ai][bj][m][n] = __builtin_amdgcn_mfma_f32_16x16x32_bf16(Bt[n][k], At[m][k], acc[ai][bj][m][n], 0, 0, 0); __builtin_amdgcn_s_setprio(0); } while (0)
; #define PG8_WAIT_V(n) asm volatile("s_waitcnt vmcnt(" #n ")" ::: "memory")
; #define PG8_WAIT_L(n) asm volatile("s_waitcnt lgkmcnt(" #n ")" ::: "memory")
; #define PG8_BAR __builtin_amdgcn_s_barrier()
; #define PG8_SCHED __builtin_amdgcn_sched_barrier(0)
; template <class Epi, class Sched, bool ALIGN_EPI = false, bool SP2 = false>
; __device__ __forceinline__ void gemm_phase(PG8_LAS unsigned char* lds, const Gemm g, const Sched& S, const Epi& E) {
;     ...
;             PG8_WAIT_V(8); PG8_WAIT_L(0); PG8_BAR; PG8_MMA(1, 0, At, B0); PG8_MMA(1, 1, At, B1); PG8_BAR; PG8_SCHED;
;             PG8_LDB(B0, 1, 0); PG8_LDB(B1, 1, 1); PG8_SCHED; PG8_LDA(At, 1, 0); PG8_STAGE(PG8_SA(0, 1), a2 + hstepA, voffA);
;             PG8_WAIT_V(8); PG8_WAIT_L(0); PG8_BAR; PG8_MMA(0, 0, At, B0); PG8_MMA(0, 1, At, B1); PG8_BAR; PG8_SCHED;
	s_setprio 1
	s_waitcnt lgkmcnt(0)
	v_mfma_f32_16x16x32_bf16 v[62:65], v[130:133], v[178:181], v[62:65]
	v_mfma_f32_16x16x32_bf16 v[58:61], v[138:141], v[178:181], v[58:61]
	v_mfma_f32_16x16x32_bf16 v[54:57], v[130:133], v[186:189], v[54:57]
	v_mfma_f32_16x16x32_bf16 v[50:53], v[138:141], v[186:189], v[50:53]
	v_mfma_f32_16x16x32_bf16 v[46:49], v[130:133], v[194:197], v[46:49]
	v_mfma_f32_16x16x32_bf16 v[38:41], v[138:141], v[194:197], v[38:41]
	v_mfma_f32_16x16x32_bf16 v[18:21], v[130:133], v[202:205], v[18:21]
	v_mfma_f32_16x16x32_bf16 v[10:13], v[138:141], v[202:205], v[10:13]
	v_mfma_f32_16x16x32_bf16 v[62:65], v[134:137], v[182:185], v[62:65]
	v_mfma_f32_16x16x32_bf16 v[58:61], v[142:145], v[182:185], v[58:61]
	v_mfma_f32_16x16x32_bf16 v[54:57], v[134:137], v[190:193], v[54:57]
	v_mfma_f32_16x16x32_bf16 v[50:53], v[142:145], v[190:193], v[50:53]
	v_mfma_f32_16x16x32_bf16 v[46:49], v[134:137], v[198:201], v[46:49]
	v_mfma_f32_16x16x32_bf16 v[38:41], v[142:145], v[198:201], v[38:41]
	v_mfma_f32_16x16x32_bf16 v[18:21], v[134:137], v[206:209], v[18:21]
	v_mfma_f32_16x16x32_bf16 v[10:13], v[142:145], v[206:209], v[10:13]
	s_setprio 0
	s_setprio 1
	v_mfma_f32_16x16x32_bf16 v[42:45], v[156:159], v[178:181], v[42:45]
	v_mfma_f32_16x16x32_bf16 v[34:37], v[170:173], v[178:181], v[34:37]
	v_mfma_f32_16x16x32_bf16 v[30:33], v[156:159], v[186:189], v[30:33]
	v_mfma_f32_16x16x32_bf16 v[26:29], v[170:173], v[186:189], v[26:29]
	v_mfma_f32_16x16x32_bf16 v[22:25], v[156:159], v[194:197], v[22:25]
	v_mfma_f32_16x16x32_bf16 v[14:17], v[170:173], v[194:197], v[14:17]
	v_mfma_f32_16x16x32_bf16 v[6:9], v[156:159], v[202:205], v[6:9]
	v_mfma_f32_16x16x32_bf16 v[2:5], v[170:173], v[202:205], v[2:5]
	v_mfma_f32_16x16x32_bf16 v[42:45], v[166:169], v[182:185], v[42:45]
	v_mfma_f32_16x16x32_bf16 v[34:37], v[174:177], v[182:185], v[34:37]
	v_mfma_f32_16x16x32_bf16 v[30:33], v[166:169], v[190:193], v[30:33]
	v_mfma_f32_16x16x32_bf16 v[26:29], v[174:177], v[190:193], v[26:29]
	v_mfma_f32_16x16x32_bf16 v[22:25], v[166:169], v[198:201], v[22:25]
	v_mfma_f32_16x16x32_bf16 v[14:17], v[174:177], v[198:201], v[14:17]
	v_mfma_f32_16x16x32_bf16 v[6:9], v[166:169], v[206:209], v[6:9]
	v_mfma_f32_16x16x32_bf16 v[2:5], v[174:177], v[206:209], v[2:5]
	s_setprio 0
	s_barrier
	s_add_i32 s69, 0, 0x18000
	s_add_i32 s70, 0, 0x1c000
	v_add_u32_e32 v142, s69, v1
	v_add_u32_e32 v174, s70, v1
	ds_read_b128 v[130:133], v142
	ds_read_b128 v[134:137], v142 offset:1024
	ds_read_b128 v[138:141], v142 offset:2048
	ds_read_b128 v[142:145], v142 offset:3072
	ds_read_b128 v[156:159], v174
	ds_read_b128 v[166:169], v174 offset:1024
	ds_read_b128 v[170:173], v174 offset:2048
	ds_read_b128 v[174:177], v174 offset:3072
	s_add_u32 s20, s26, 0xb0000
	s_addc_u32 s21, s27, 0
	s_mov_b32 m0, s44
	ds_read_b128 v[178:181], v164 offset:32768
	ds_read_b128 v[182:185], v164 offset:33792
	ds_read_b128 v[186:189], v164 offset:34816
	ds_read_b128 v[190:193], v164 offset:35840
	ds_read_b128 v[194:197], v164 offset:36864
	ds_read_b128 v[198:201], v164 offset:37888
	ds_read_b128 v[202:205], v164 offset:38912
	ds_read_b128 v[206:209], v164 offset:39936
	global_load_lds_dwordx4 v148, s[20:21]
	s_mov_b32 m0, s45
	s_nop 0
	global_load_lds_dwordx4 v146, s[20:21]
	s_waitcnt vmcnt(8)
	s_waitcnt lgkmcnt(0)
	s_barrier
	s_setprio 1
	s_waitcnt lgkmcnt(0)
	v_mfma_f32_16x16x32_bf16 v[126:129], v[130:133], v[178:181], v[126:129]
	v_mfma_f32_16x16x32_bf16 v[122:125], v[138:141], v[178:181], v[122:125]
	v_mfma_f32_16x16x32_bf16 v[118:121], v[130:133], v[186:189], v[118:121]
	v_mfma_f32_16x16x32_bf16 v[114:117], v[138:141], v[186:189], v[114:117]
	v_mfma_f32_16x16x32_bf16 v[102:105], v[130:133], v[194:197], v[102:105]
	v_mfma_f32_16x16x32_bf16 v[90:93], v[138:141], v[194:197], v[90:93]
	v_mfma_f32_16x16x32_bf16 v[82:85], v[130:133], v[202:205], v[82:85]
	v_mfma_f32_16x16x32_bf16 v[74:77], v[138:141], v[202:205], v[74:77]
	v_mfma_f32_16x16x32_bf16 v[126:129], v[134:137], v[182:185], v[126:129]
	v_mfma_f32_16x16x32_bf16 v[122:125], v[142:145], v[182:185], v[122:125]
	v_mfma_f32_16x16x32_bf16 v[118:121], v[134:137], v[190:193], v[118:121]
	v_mfma_f32_16x16x32_bf16 v[114:117], v[142:145], v[190:193], v[114:117]
	v_mfma_f32_16x16x32_bf16 v[102:105], v[134:137], v[198:201], v[102:105]
	v_mfma_f32_16x16x32_bf16 v[90:93], v[142:145], v[198:201], v[90:93]
	v_mfma_f32_16x16x32_bf16 v[82:85], v[134:137], v[206:209], v[82:85]
	v_mfma_f32_16x16x32_bf16 v[74:77], v[142:145], v[206:209], v[74:77]
	s_setprio 0
	s_setprio 1
	v_mfma_f32_16x16x32_bf16 v[110:113], v[156:159], v[178:181], v[110:113]
	v_mfma_f32_16x16x32_bf16 v[106:109], v[170:173], v[178:181], v[106:109]
	v_mfma_f32_16x16x32_bf16 v[98:101], v[156:159], v[186:189], v[98:101]
	v_mfma_f32_16x16x32_bf16 v[94:97], v[170:173], v[186:189], v[94:97]
	v_mfma_f32_16x16x32_bf16 v[86:89], v[156:159], v[194:197], v[86:89]
	v_mfma_f32_16x16x32_bf16 v[78:81], v[170:173], v[194:197], v[78:81]
	v_mfma_f32_16x16x32_bf16 v[70:73], v[156:159], v[202:205], v[70:73]
	v_mfma_f32_16x16x32_bf16 v[66:69], v[170:173], v[202:205], v[66:69]
	v_mfma_f32_16x16x32_bf16 v[110:113], v[166:169], v[182:185], v[110:113]
	v_mfma_f32_16x16x32_bf16 v[106:109], v[174:177], v[182:185], v[106:109]
	v_mfma_f32_16x16x32_bf16 v[98:101], v[166:169], v[190:193], v[98:101]
	v_mfma_f32_16x16x32_bf16 v[94:97], v[174:177], v[190:193], v[94:97]
	v_mfma_f32_16x16x32_bf16 v[86:89], v[166:169], v[198:201], v[86:89]
	v_mfma_f32_16x16x32_bf16 v[78:81], v[174:177], v[198:201], v[78:81]
	v_mfma_f32_16x16x32_bf16 v[70:73], v[166:169], v[206:209], v[70:73]
	v_mfma_f32_16x16x32_bf16 v[66:69], v[174:177], v[206:209], v[66:69]
	s_setprio 0
	s_barrier
; #define PG8_STAGE(bufoff, gbase, voff) do { _Pragma("unroll") for (int _i = 0; _i < 2; ++_i) \
;         __builtin_amdgcn_global_load_lds((const unsigned*)((const char*)(gbase) + (voff)[_i]), (PG8_LAS unsigned*)(lds + (bufoff) + ldsw + _i * 8192), 16, 0, 0); } while (0)
; #define PG8_LDA(dst, b, h) do { _Pragma("unroll") for (int m = 0; m < 4; ++m) _Pragma("unroll") for (int k = 0; k < 2; ++k) dst[m][k] = *(const PG8_LAS bf16x8*)(lds + PG8_SA(b, h) + aoff + m * 2048 + k * 1024); } while (0)
; #define PG8_MMA(ai, bj, At, Bt) do { __builtin_amdgcn_s_setprio(1); _Pragma("unroll") for (int m = 0; m < 4; ++m) _Pragma("unroll") for (int n = 0; n < 2; ++n) _Pragma("unroll") for (int k = 0; k < 2; ++k) \
;         acc[ai][bj][m][n] = __builtin_amdgcn_mfma_f32_16x16x32_bf16(Bt[n][k], At[m][k], acc[ai][bj][m][n], 0, 0, 0); __builtin_amdgcn_s_setprio(0); } while (0)
; #define PG8_WAIT_V(n) asm volatile("s_waitcnt vmcnt(" #n ")" ::: "memory")
; #define PG8_WAIT_L(n) asm volatile("s_waitcnt lgkmcnt(" #n ")" ::: "memory")
; #define PG8_BAR __builtin_amdgcn_s_barrier()
; #define PG8_SCHED __builtin_amdgcn_sched_barrier(0)
; template <class Epi, class Sched, bool ALIGN_EPI = false, bool SP2 = false>
; __device__ __forceinline__ void gemm_phase(PG8_LAS unsigned char* lds, const Gemm g, const Sched& S, const Epi& E) {
;     ...
;             PG8_LDA(At, 1, 1); PG8_STAGE(PG8_SB(1, 0), b3, voffB); PG8_STAGE(PG8_SB(1, 1), b3 + hstepB, voffB); PG8_STAGE(PG8_SA(1, 0), a3, voffA);
;             PG8_WAIT_V(8); PG8_WAIT_L(0); PG8_BAR; PG8_MMA(1, 0, At, B0); PG8_MMA(1, 1, At, B1); PG8_BAR; PG8_SCHED;
	s_add_i32 s20, s69, s40
	s_mov_b32 m0, s20
	ds_read_b128 v[178:181], v164 offset:49152
	ds_read_b128 v[182:185], v164 offset:50176
	ds_read_b128 v[186:189], v164 offset:51200
	ds_read_b128 v[190:193], v164 offset:52224
	ds_read_b128 v[194:197], v164 offset:53248
	ds_read_b128 v[198:201], v164 offset:54272
	ds_read_b128 v[202:205], v164 offset:55296
	ds_read_b128 v[206:209], v164 offset:56320
	global_load_lds_dwordx4 v148, s[98:99]
	s_add_i32 m0, s20, 0x2000
	s_add_u32 s20, s24, 0xb0080
	s_addc_u32 s21, s25, 0
	s_add_i32 s24, s70, s40
	global_load_lds_dwordx4 v146, s[98:99]
	s_mov_b32 m0, s24
	s_nop 0
	global_load_lds_dwordx4 v148, s[20:21]
	s_add_i32 m0, s24, 0x2000
	s_nop 0
	global_load_lds_dwordx4 v146, s[20:21]
	s_mov_b32 m0, s51
	s_nop 0
	global_load_lds_dwordx4 v148, s[100:101]
	s_mov_b32 m0, s52
	s_nop 0
	global_load_lds_dwordx4 v146, s[100:101]
	s_waitcnt vmcnt(8)
	s_waitcnt lgkmcnt(0)
	s_barrier
	s_setprio 1
	s_waitcnt lgkmcnt(0)
	v_mfma_f32_16x16x32_bf16 v[62:65], v[130:133], v[178:181], v[62:65]
	v_mfma_f32_16x16x32_bf16 v[58:61], v[138:141], v[178:181], v[58:61]
	v_mfma_f32_16x16x32_bf16 v[54:57], v[130:133], v[186:189], v[54:57]
	v_mfma_f32_16x16x32_bf16 v[50:53], v[138:141], v[186:189], v[50:53]
	v_mfma_f32_16x16x32_bf16 v[46:49], v[130:133], v[194:197], v[46:49]
	v_mfma_f32_16x16x32_bf16 v[38:41], v[138:141], v[194:197], v[38:41]
	v_mfma_f32_16x16x32_bf16 v[18:21], v[130:133], v[202:205], v[18:21]
	v_mfma_f32_16x16x32_bf16 v[10:13], v[138:141], v[202:205], v[10:13]
	v_mfma_f32_16x16x32_bf16 v[62:65], v[134:137], v[182:185], v[62:65]
	v_mfma_f32_16x16x32_bf16 v[58:61], v[142:145], v[182:185], v[58:61]
	v_mfma_f32_16x16x32_bf16 v[54:57], v[134:137], v[190:193], v[54:57]
	v_mfma_f32_16x16x32_bf16 v[50:53], v[142:145], v[190:193], v[50:53]
	v_mfma_f32_16x16x32_bf16 v[46:49], v[134:137], v[198:201], v[46:49]
	v_mfma_f32_16x16x32_bf16 v[38:41], v[142:145], v[198:201], v[38:41]
	v_mfma_f32_16x16x32_bf16 v[18:21], v[134:137], v[206:209], v[18:21]
	v_mfma_f32_16x16x32_bf16 v[10:13], v[142:145], v[206:209], v[10:13]
	s_setprio 0
	s_setprio 1
	v_mfma_f32_16x16x32_bf16 v[42:45], v[156:159], v[178:181], v[42:45]
	v_mfma_f32_16x16x32_bf16 v[34:37], v[170:173], v[178:181], v[34:37]
	v_mfma_f32_16x16x32_bf16 v[30:33], v[156:159], v[186:189], v[30:33]
	v_mfma_f32_16x16x32_bf16 v[26:29], v[170:173], v[186:189], v[26:29]
	v_mfma_f32_16x16x32_bf16 v[22:25], v[156:159], v[194:197], v[22:25]
	v_mfma_f32_16x16x32_bf16 v[14:17], v[170:173], v[194:197], v[14:17]
	v_mfma_f32_16x16x32_bf16 v[6:9], v[156:159], v[202:205], v[6:9]
	v_mfma_f32_16x16x32_bf16 v[2:5], v[170:173], v[202:205], v[2:5]
	v_mfma_f32_16x16x32_bf16 v[42:45], v[166:169], v[182:185], v[42:45]
	v_mfma_f32_16x16x32_bf16 v[34:37], v[174:177], v[182:185], v[34:37]
	v_mfma_f32_16x16x32_bf16 v[30:33], v[166:169], v[190:193], v[30:33]
	v_mfma_f32_16x16x32_bf16 v[26:29], v[174:177], v[190:193], v[26:29]
	v_mfma_f32_16x16x32_bf16 v[22:25], v[166:169], v[198:201], v[22:25]
	v_mfma_f32_16x16x32_bf16 v[14:17], v[174:177], v[198:201], v[14:17]
	v_mfma_f32_16x16x32_bf16 v[6:9], v[166:169], v[206:209], v[6:9]
	v_mfma_f32_16x16x32_bf16 v[2:5], v[174:177], v[206:209], v[2:5]
	s_setprio 0
	s_barrier
	s_add_i32 s68, s68, 2
	s_add_u32 s66, s66, 0x100
	s_addc_u32 s67, s67, 0
	s_cmp_gt_u32 s68, 5
	s_mov_b64 s[20:21], s[22:23]
	s_cbranch_scc0 .LBB0_1897
	s_and_b64 vcc, exec, s[10:11]
	s_cbranch_vccz .LBB0_1900
	s_barrier

; #define PG8_STAGE(bufoff, gbase, voff) do { _Pragma("unroll") for (int _i = 0; _i < 2; ++_i) \
;         __builtin_amdgcn_global_load_lds((const unsigned*)((const char*)(gbase) + (voff)[_i]), (PG8_LAS unsigned*)(lds + (bufoff) + ldsw + _i * 8192), 16, 0, 0); } while (0)
; #define PG8_LDA(dst, b, h) do { _Pragma("unroll") for (int m = 0; m < 4; ++m) _Pragma("unroll") for (int k = 0; k < 2; ++k) dst[m][k] = *(const PG8_LAS bf16x8*)(lds + PG8_SA(b, h) + aoff + m * 2048 + k * 1024); } while (0)
; #define PG8_LDB(dst, b, h) do { _Pragma("unroll") for (int n = 0; n < 2; ++n) _Pragma("unroll") for (int k = 0; k < 2; ++k) dst[n][k] = *(const PG8_LAS bf16x8*)(lds + PG8_SB(b, h) + boff + n * 2048 + k * 1024); } while (0)
; #define PG8_MMA(ai, bj, At, Bt) do { __builtin_amdgcn_s_setprio(1); _Pragma("unroll") for (int m = 0; m < 4; ++m) _Pragma("unroll") for (int n = 0; n < 2; ++n) _Pragma("unroll") for (int k = 0; k < 2; ++k) \
;         acc[ai][bj][m][n] = __builtin_amdgcn_mfma_f32_16x16x32_bf16(Bt[n][k], At[m][k], acc[ai][bj][m][n], 0, 0, 0); __builtin_amdgcn_s_setprio(0); } while (0)
; #define PG8_WAIT_V(n) asm volatile("s_waitcnt vmcnt(" #n ")" ::: "memory")
; #define PG8_WAIT_L(n) asm volatile("s_waitcnt lgkmcnt(" #n ")" ::: "memory")
; template <class Epi, class Sched, bool ALIGN_EPI = false, bool SP2 = false>
; __device__ __forceinline__ void gemm_phase(PG8_LAS unsigned char* lds, const Gemm g, const Sched& S, const Epi& E) {
;     ...
;             const bool last = (t == nt - 2);
;             const char* a1 = cA + (size_t)(t + 1) * kstep;
;             const char* a2 = last ? nA : cA + (size_t)(t + 2) * kstep; const char* b2 = last ? nB : cB + (size_t)(t + 2) * kstep;
;             const char* a3 = a2 + kstep; const char* b3 = b2 + kstep;
;             if (last && has_next) S.a_ready(nxt);
;             if constexpr (SP2) {
;             PG8_LDB(B0, 0, 0); PG8_LDB(B1, 0, 1); PG8_SCHED; PG8_LDA(At, 0, 0); PG8_STAGE(PG8_SA(1, 1), a1 + hstepA, voffA);
;             PG8_WAIT_V(8); PG8_WAIT_L(0); PG8_BAR; PG8_MMA(0, 0, At, B0); PG8_MMA(0, 1, At, B1); PG8_BAR; PG8_SCHED;
;             PG8_LDA(At, 0, 1); PG8_STAGE(PG8_SB(0, 0), b2, voffB); PG8_STAGE(PG8_SB(0, 1), b2 + hstepB, voffB); PG8_STAGE(PG8_SA(0, 0), a2, voffA);
;             PG8_WAIT_V(8); PG8_WAIT_L(0); PG8_BAR; PG8_MMA(1, 0, At, B0); PG8_MMA(1, 1, At, B1); PG8_BAR; PG8_SCHED;
.LBB0_2153:
	ds_read_b128 v[148:151], v156
	ds_read_b128 v[160:163], v156 offset:1024
	ds_read_b128 v[164:167], v156 offset:2048
	ds_read_b128 v[168:171], v156 offset:3072
	ds_read_b128 v[172:175], v157
	ds_read_b128 v[176:179], v157 offset:1024
	ds_read_b128 v[180:183], v157 offset:2048
	ds_read_b128 v[184:187], v157 offset:3072
	s_add_u32 s36, s34, 0xfffc0080
	s_addc_u32 s37, s35, -1
	s_cmp_eq_u32 s59, 12
	s_cselect_b32 s39, s5, s37
	s_cselect_b32 s38, s25, s36
	s_cselect_b32 s37, s23, s58
	s_cselect_b32 s36, s31, s57
	s_add_i32 m0, s44, 0xc000
	ds_read_b128 v[188:191], v158
	ds_read_b128 v[192:195], v158 offset:1024
	ds_read_b128 v[196:199], v158 offset:2048
	ds_read_b128 v[200:203], v158 offset:3072
	ds_read_b128 v[204:207], v158 offset:4096
	ds_read_b128 v[208:211], v158 offset:5120
	ds_read_b128 v[212:215], v158 offset:6144
	ds_read_b128 v[216:219], v158 offset:7168
	global_load_lds_dwordx4 v140, s[34:35]
	s_add_i32 m0, s44, 0xe000
	s_nop 0
	global_load_lds_dwordx4 v142, s[34:35]
	s_waitcnt vmcnt(8)
	s_waitcnt lgkmcnt(0)
	s_barrier
	s_setprio 1
	s_waitcnt lgkmcnt(0)
	v_mfma_f32_16x16x32_bf16 v[126:129], v[148:151], v[188:191], v[126:129]
	v_mfma_f32_16x16x32_bf16 v[122:125], v[164:167], v[188:191], v[122:125]
	v_mfma_f32_16x16x32_bf16 v[110:113], v[148:151], v[196:199], v[110:113]
	v_mfma_f32_16x16x32_bf16 v[106:109], v[164:167], v[196:199], v[106:109]
	v_mfma_f32_16x16x32_bf16 v[94:97], v[148:151], v[204:207], v[94:97]
	v_mfma_f32_16x16x32_bf16 v[90:93], v[164:167], v[204:207], v[90:93]
	v_mfma_f32_16x16x32_bf16 v[78:81], v[148:151], v[212:215], v[78:81]
	v_mfma_f32_16x16x32_bf16 v[74:77], v[164:167], v[212:215], v[74:77]
	v_mfma_f32_16x16x32_bf16 v[126:129], v[160:163], v[192:195], v[126:129]
	v_mfma_f32_16x16x32_bf16 v[122:125], v[168:171], v[192:195], v[122:125]
	v_mfma_f32_16x16x32_bf16 v[110:113], v[160:163], v[200:203], v[110:113]
	v_mfma_f32_16x16x32_bf16 v[106:109], v[168:171], v[200:203], v[106:109]
	v_mfma_f32_16x16x32_bf16 v[94:97], v[160:163], v[208:211], v[94:97]
	v_mfma_f32_16x16x32_bf16 v[90:93], v[168:171], v[208:211], v[90:93]
	v_mfma_f32_16x16x32_bf16 v[78:81], v[160:163], v[216:219], v[78:81]
	v_mfma_f32_16x16x32_bf16 v[74:77], v[168:171], v[216:219], v[74:77]
	s_setprio 0
	s_setprio 1
	v_mfma_f32_16x16x32_bf16 v[118:121], v[172:175], v[188:191], v[118:121]
	v_mfma_f32_16x16x32_bf16 v[114:117], v[180:183], v[188:191], v[114:117]
	v_mfma_f32_16x16x32_bf16 v[102:105], v[172:175], v[196:199], v[102:105]
	v_mfma_f32_16x16x32_bf16 v[98:101], v[180:183], v[196:199], v[98:101]
	v_mfma_f32_16x16x32_bf16 v[86:89], v[172:175], v[204:207], v[86:89]
	v_mfma_f32_16x16x32_bf16 v[82:85], v[180:183], v[204:207], v[82:85]
	v_mfma_f32_16x16x32_bf16 v[70:73], v[172:175], v[212:215], v[70:73]
	v_mfma_f32_16x16x32_bf16 v[66:69], v[180:183], v[212:215], v[66:69]
	v_mfma_f32_16x16x32_bf16 v[118:121], v[176:179], v[192:195], v[118:121]
	v_mfma_f32_16x16x32_bf16 v[114:117], v[184:187], v[192:195], v[114:117]
	v_mfma_f32_16x16x32_bf16 v[102:105], v[176:179], v[200:203], v[102:105]
	v_mfma_f32_16x16x32_bf16 v[98:101], v[184:187], v[200:203], v[98:101]
	v_mfma_f32_16x16x32_bf16 v[86:89], v[176:179], v[208:211], v[86:89]
	v_mfma_f32_16x16x32_bf16 v[82:85], v[184:187], v[208:211], v[82:85]
	v_mfma_f32_16x16x32_bf16 v[70:73], v[176:179], v[216:219], v[70:73]
	v_mfma_f32_16x16x32_bf16 v[66:69], v[184:187], v[216:219], v[66:69]
	s_setprio 0
	s_barrier
	s_add_i32 s60, s54, s43
	s_add_u32 s98, s36, 0x80
	s_addc_u32 s99, s37, 0
	s_mov_b32 m0, s60
	ds_read_b128 v[188:191], v158 offset:16384
	ds_read_b128 v[192:195], v158 offset:17408
	ds_read_b128 v[196:199], v158 offset:18432
	ds_read_b128 v[200:203], v158 offset:19456
	ds_read_b128 v[204:207], v158 offset:20480
	ds_read_b128 v[208:211], v158 offset:21504
	ds_read_b128 v[212:215], v158 offset:22528
	ds_read_b128 v[216:219], v158 offset:23552
	global_load_lds_dwordx4 v132, s[36:37]
	s_add_i32 m0, s60, 0x2000
	s_add_u32 s60, s36, 0x40000
	s_addc_u32 s61, s37, 0
	s_add_i32 s62, s55, s43
	global_load_lds_dwordx4 v136, s[36:37]
	s_mov_b32 m0, s62
	s_nop 0
	global_load_lds_dwordx4 v132, s[60:61]
	s_add_i32 m0, s62, 0x2000
	s_nop 0
	global_load_lds_dwordx4 v136, s[60:61]
	s_add_u32 s100, s38, 0x80
	s_addc_u32 s101, s39, 0
	s_mov_b32 m0, s44
	s_nop 0
	global_load_lds_dwordx4 v130, s[38:39]
	s_mov_b32 m0, s45
	s_nop 0
	global_load_lds_dwordx4 v134, s[38:39]
	s_waitcnt vmcnt(8)
	s_waitcnt lgkmcnt(0)
	s_barrier
	s_setprio 1
	s_waitcnt lgkmcnt(0)
	v_mfma_f32_16x16x32_bf16 v[62:65], v[148:151], v[188:191], v[62:65]
	v_mfma_f32_16x16x32_bf16 v[58:61], v[164:167], v[188:191], v[58:61]
	v_mfma_f32_16x16x32_bf16 v[46:49], v[148:151], v[196:199], v[46:49]
	v_mfma_f32_16x16x32_bf16 v[42:45], v[164:167], v[196:199], v[42:45]
	v_mfma_f32_16x16x32_bf16 v[30:33], v[148:151], v[204:207], v[30:33]
	v_mfma_f32_16x16x32_bf16 v[26:29], v[164:167], v[204:207], v[26:29]
	v_mfma_f32_16x16x32_bf16 v[14:17], v[148:151], v[212:215], v[14:17]
	v_mfma_f32_16x16x32_bf16 v[10:13], v[164:167], v[212:215], v[10:13]
	v_mfma_f32_16x16x32_bf16 v[62:65], v[160:163], v[192:195], v[62:65]
	v_mfma_f32_16x16x32_bf16 v[58:61], v[168:171], v[192:195], v[58:61]
	v_mfma_f32_16x16x32_bf16 v[46:49], v[160:163], v[200:203], v[46:49]
	v_mfma_f32_16x16x32_bf16 v[42:45], v[168:171], v[200:203], v[42:45]
	v_mfma_f32_16x16x32_bf16 v[30:33], v[160:163], v[208:211], v[30:33]
	v_mfma_f32_16x16x32_bf16 v[26:29], v[168:171], v[208:211], v[26:29]
	v_mfma_f32_16x16x32_bf16 v[14:17], v[160:163], v[216:219], v[14:17]
	v_mfma_f32_16x16x32_bf16 v[10:13], v[168:171], v[216:219], v[10:13]
	s_setprio 0
	s_setprio 1
	v_mfma_f32_16x16x32_bf16 v[54:57], v[172:175], v[188:191], v[54:57]
	v_mfma_f32_16x16x32_bf16 v[50:53], v[180:183], v[188:191], v[50:53]
	v_mfma_f32_16x16x32_bf16 v[38:41], v[172:175], v[196:199], v[38:41]
	v_mfma_f32_16x16x32_bf16 v[34:37], v[180:183], v[196:199], v[34:37]
	v_mfma_f32_16x16x32_bf16 v[22:25], v[172:175], v[204:207], v[22:25]
	v_mfma_f32_16x16x32_bf16 v[18:21], v[180:183], v[204:207], v[18:21]
	v_mfma_f32_16x16x32_bf16 v[6:9], v[172:175], v[212:215], v[6:9]
	v_mfma_f32_16x16x32_bf16 v[2:5], v[180:183], v[212:215], v[2:5]
	v_mfma_f32_16x16x32_bf16 v[54:57], v[176:179], v[192:195], v[54:57]
	v_mfma_f32_16x16x32_bf16 v[50:53], v[184:187], v[192:195], v[50:53]
	v_mfma_f32_16x16x32_bf16 v[38:41], v[176:179], v[200:203], v[38:41]
	v_mfma_f32_16x16x32_bf16 v[34:37], v[184:187], v[200:203], v[34:37]
	v_mfma_f32_16x16x32_bf16 v[22:25], v[176:179], v[208:211], v[22:25]
	v_mfma_f32_16x16x32_bf16 v[18:21], v[184:187], v[208:211], v[18:21]
	v_mfma_f32_16x16x32_bf16 v[6:9], v[176:179], v[216:219], v[6:9]
	v_mfma_f32_16x16x32_bf16 v[2:5], v[184:187], v[216:219], v[2:5]
	s_setprio 0
	s_barrier
; #define PG8_STAGE(bufoff, gbase, voff) do { _Pragma("unroll") for (int _i = 0; _i < 2; ++_i) \
;         __builtin_amdgcn_global_load_lds((const unsigned*)((const char*)(gbase) + (voff)[_i]), (PG8_LAS unsigned*)(lds + (bufoff) + ldsw + _i * 8192), 16, 0, 0); } while (0)
; #define PG8_LDA(dst, b, h) do { _Pragma("unroll") for (int m = 0; m < 4; ++m) _Pragma("unroll") for (int k = 0; k < 2; ++k) dst[m][k] = *(const PG8_LAS bf16x8*)(lds + PG8_SA(b, h) + aoff + m * 2048 + k * 1024); } while (0)
; #define PG8_LDB(dst, b, h) do { _Pragma("unroll") for (int n = 0; n < 2; ++n) _Pragma("unroll") for (int k = 0; k < 2; ++k) dst[n][k] = *(const PG8_LAS bf16x8*)(lds + PG8_SB(b, h) + boff + n * 2048 + k * 1024); } while (0)
; #define PG8_MMA(ai, bj, At, Bt) do { __builtin_amdgcn_s_setprio(1); _Pragma("unroll") for (int m = 0; m < 4; ++m) _Pragma("unroll") for (int n = 0; n < 2; ++n) _Pragma("unroll") for (int k = 0; k < 2; ++k) \
;         acc[ai][bj][m][n] = __builtin_amdgcn_mfma_f32_16x16x32_bf16(Bt[n][k], At[m][k], acc[ai][bj][m][n], 0, 0, 0); __builtin_amdgcn_s_setprio(0); } while (0)
; #define PG8_WAIT_V(n) asm volatile("s_waitcnt vmcnt(" #n ")" ::: "memory")
; #define PG8_WAIT_L(n) asm volatile("s_waitcnt lgkmcnt(" #n ")" ::: "memory")
; #define PG8_BAR __builtin_amdgcn_s_barrier()
; #define PG8_SCHED __builtin_amdgcn_sched_barrier(0)
; template <class Epi, class Sched, bool ALIGN_EPI = false, bool SP2 = false>
; __device__ __forceinline__ void gemm_phase(PG8_LAS unsigned char* lds, const Gemm g, const Sched& S, const Epi& E) {
;     ...
;             PG8_LDB(B0, 1, 0); PG8_LDB(B1, 1, 1); PG8_SCHED; PG8_LDA(At, 1, 0); PG8_STAGE(PG8_SA(0, 1), a2 + hstepA, voffA);
;             PG8_WAIT_V(8); PG8_WAIT_L(0); PG8_BAR; PG8_MMA(0, 0, At, B0); PG8_MMA(0, 1, At, B1); PG8_BAR; PG8_SCHED;
;             PG8_LDA(At, 1, 1); PG8_STAGE(PG8_SB(1, 0), b3, voffB); PG8_STAGE(PG8_SB(1, 1), b3 + hstepB, voffB); PG8_STAGE(PG8_SA(1, 0), a3, voffA);
;             PG8_WAIT_V(8); PG8_WAIT_L(0); PG8_BAR; PG8_MMA(1, 0, At, B0); PG8_MMA(1, 1, At, B1); PG8_BAR; PG8_SCHED;
	s_add_i32 s60, 0, 0x18000
	v_add_u32_e32 v138, s60, v154
	s_add_i32 s61, 0, 0x1c000
	ds_read_b128 v[148:151], v138
	ds_read_b128 v[160:163], v138 offset:1024
	ds_read_b128 v[164:167], v138 offset:2048
	ds_read_b128 v[168:171], v138 offset:3072
	v_add_u32_e32 v138, s61, v154
	ds_read_b128 v[172:175], v138
	ds_read_b128 v[176:179], v138 offset:1024
	ds_read_b128 v[180:183], v138 offset:2048
	ds_read_b128 v[184:187], v138 offset:3072
	s_add_u32 s38, s38, 0x40000
	s_addc_u32 s39, s39, 0
	s_mov_b32 m0, s46
	ds_read_b128 v[188:191], v158 offset:32768
	ds_read_b128 v[192:195], v158 offset:33792
	ds_read_b128 v[196:199], v158 offset:34816
	ds_read_b128 v[200:203], v158 offset:35840
	ds_read_b128 v[204:207], v158 offset:36864
	ds_read_b128 v[208:211], v158 offset:37888
	ds_read_b128 v[212:215], v158 offset:38912
	ds_read_b128 v[216:219], v158 offset:39936
	global_load_lds_dwordx4 v130, s[38:39]
	s_mov_b32 m0, s47
	s_nop 0
	global_load_lds_dwordx4 v134, s[38:39]
	s_waitcnt vmcnt(8)
	s_waitcnt lgkmcnt(0)
	s_barrier
	s_setprio 1
	s_waitcnt lgkmcnt(0)
	v_mfma_f32_16x16x32_bf16 v[126:129], v[148:151], v[188:191], v[126:129]
	v_mfma_f32_16x16x32_bf16 v[122:125], v[164:167], v[188:191], v[122:125]
	v_mfma_f32_16x16x32_bf16 v[110:113], v[148:151], v[196:199], v[110:113]
	v_mfma_f32_16x16x32_bf16 v[106:109], v[164:167], v[196:199], v[106:109]
	v_mfma_f32_16x16x32_bf16 v[94:97], v[148:151], v[204:207], v[94:97]
	v_mfma_f32_16x16x32_bf16 v[90:93], v[164:167], v[204:207], v[90:93]
	v_mfma_f32_16x16x32_bf16 v[78:81], v[148:151], v[212:215], v[78:81]
	v_mfma_f32_16x16x32_bf16 v[74:77], v[164:167], v[212:215], v[74:77]
	v_mfma_f32_16x16x32_bf16 v[126:129], v[160:163], v[192:195], v[126:129]
	v_mfma_f32_16x16x32_bf16 v[122:125], v[168:171], v[192:195], v[122:125]
	v_mfma_f32_16x16x32_bf16 v[110:113], v[160:163], v[200:203], v[110:113]
	v_mfma_f32_16x16x32_bf16 v[106:109], v[168:171], v[200:203], v[106:109]
	v_mfma_f32_16x16x32_bf16 v[94:97], v[160:163], v[208:211], v[94:97]
	v_mfma_f32_16x16x32_bf16 v[90:93], v[168:171], v[208:211], v[90:93]
	v_mfma_f32_16x16x32_bf16 v[78:81], v[160:163], v[216:219], v[78:81]
	v_mfma_f32_16x16x32_bf16 v[74:77], v[168:171], v[216:219], v[74:77]
	s_setprio 0
	s_setprio 1
	v_mfma_f32_16x16x32_bf16 v[118:121], v[172:175], v[188:191], v[118:121]
	v_mfma_f32_16x16x32_bf16 v[114:117], v[180:183], v[188:191], v[114:117]
	v_mfma_f32_16x16x32_bf16 v[102:105], v[172:175], v[196:199], v[102:105]
	v_mfma_f32_16x16x32_bf16 v[98:101], v[180:183], v[196:199], v[98:101]
	v_mfma_f32_16x16x32_bf16 v[86:89], v[172:175], v[204:207], v[86:89]
	v_mfma_f32_16x16x32_bf16 v[82:85], v[180:183], v[204:207], v[82:85]
	v_mfma_f32_16x16x32_bf16 v[70:73], v[172:175], v[212:215], v[70:73]
	v_mfma_f32_16x16x32_bf16 v[66:69], v[180:183], v[212:215], v[66:69]
	v_mfma_f32_16x16x32_bf16 v[118:121], v[176:179], v[192:195], v[118:121]
	v_mfma_f32_16x16x32_bf16 v[114:117], v[184:187], v[192:195], v[114:117]
	v_mfma_f32_16x16x32_bf16 v[102:105], v[176:179], v[200:203], v[102:105]
	v_mfma_f32_16x16x32_bf16 v[98:101], v[184:187], v[200:203], v[98:101]
	v_mfma_f32_16x16x32_bf16 v[86:89], v[176:179], v[208:211], v[86:89]
	v_mfma_f32_16x16x32_bf16 v[82:85], v[184:187], v[208:211], v[82:85]
	v_mfma_f32_16x16x32_bf16 v[70:73], v[176:179], v[216:219], v[70:73]
	v_mfma_f32_16x16x32_bf16 v[66:69], v[184:187], v[216:219], v[66:69]
	s_setprio 0
	s_barrier
	s_add_i32 s38, s60, s43
	s_mov_b32 m0, s38
	ds_read_b128 v[188:191], v158 offset:49152
	ds_read_b128 v[192:195], v158 offset:50176
	ds_read_b128 v[196:199], v158 offset:51200
	ds_read_b128 v[200:203], v158 offset:52224
	ds_read_b128 v[204:207], v158 offset:53248
	ds_read_b128 v[208:211], v158 offset:54272
	ds_read_b128 v[212:215], v158 offset:55296
	ds_read_b128 v[216:219], v158 offset:56320
	global_load_lds_dwordx4 v132, s[98:99]
	s_add_i32 m0, s38, 0x2000
	s_add_u32 s36, s36, 0x40080
	s_addc_u32 s37, s37, 0
	s_add_i32 s38, s61, s43
	global_load_lds_dwordx4 v136, s[98:99]
	s_mov_b32 m0, s38
	s_nop 0
	global_load_lds_dwordx4 v132, s[36:37]
	s_add_i32 m0, s38, 0x2000
	s_nop 0
	global_load_lds_dwordx4 v136, s[36:37]
	s_mov_b32 m0, s49
	s_nop 0
	global_load_lds_dwordx4 v130, s[100:101]
	s_mov_b32 m0, s50
	s_nop 0
	global_load_lds_dwordx4 v134, s[100:101]
	s_waitcnt vmcnt(8)
	s_waitcnt lgkmcnt(0)
	s_barrier
	s_setprio 1
	s_waitcnt lgkmcnt(0)
	v_mfma_f32_16x16x32_bf16 v[62:65], v[148:151], v[188:191], v[62:65]
	v_mfma_f32_16x16x32_bf16 v[58:61], v[164:167], v[188:191], v[58:61]
	v_mfma_f32_16x16x32_bf16 v[46:49], v[148:151], v[196:199], v[46:49]
	v_mfma_f32_16x16x32_bf16 v[42:45], v[164:167], v[196:199], v[42:45]
	v_mfma_f32_16x16x32_bf16 v[30:33], v[148:151], v[204:207], v[30:33]
	v_mfma_f32_16x16x32_bf16 v[26:29], v[164:167], v[204:207], v[26:29]
	v_mfma_f32_16x16x32_bf16 v[14:17], v[148:151], v[212:215], v[14:17]
	v_mfma_f32_16x16x32_bf16 v[10:13], v[164:167], v[212:215], v[10:13]
	v_mfma_f32_16x16x32_bf16 v[62:65], v[160:163], v[192:195], v[62:65]
	v_mfma_f32_16x16x32_bf16 v[58:61], v[168:171], v[192:195], v[58:61]
	v_mfma_f32_16x16x32_bf16 v[46:49], v[160:163], v[200:203], v[46:49]
	v_mfma_f32_16x16x32_bf16 v[42:45], v[168:171], v[200:203], v[42:45]
	v_mfma_f32_16x16x32_bf16 v[30:33], v[160:163], v[208:211], v[30:33]
	v_mfma_f32_16x16x32_bf16 v[26:29], v[168:171], v[208:211], v[26:29]
	v_mfma_f32_16x16x32_bf16 v[14:17], v[160:163], v[216:219], v[14:17]
	v_mfma_f32_16x16x32_bf16 v[10:13], v[168:171], v[216:219], v[10:13]
	s_setprio 0
	s_setprio 1
	v_mfma_f32_16x16x32_bf16 v[54:57], v[172:175], v[188:191], v[54:57]
	v_mfma_f32_16x16x32_bf16 v[50:53], v[180:183], v[188:191], v[50:53]
	v_mfma_f32_16x16x32_bf16 v[38:41], v[172:175], v[196:199], v[38:41]
	v_mfma_f32_16x16x32_bf16 v[34:37], v[180:183], v[196:199], v[34:37]
	v_mfma_f32_16x16x32_bf16 v[22:25], v[172:175], v[204:207], v[22:25]
	v_mfma_f32_16x16x32_bf16 v[18:21], v[180:183], v[204:207], v[18:21]
	v_mfma_f32_16x16x32_bf16 v[6:9], v[172:175], v[212:215], v[6:9]
	v_mfma_f32_16x16x32_bf16 v[2:5], v[180:183], v[212:215], v[2:5]
	v_mfma_f32_16x16x32_bf16 v[54:57], v[176:179], v[192:195], v[54:57]
	v_mfma_f32_16x16x32_bf16 v[50:53], v[184:187], v[192:195], v[50:53]
	v_mfma_f32_16x16x32_bf16 v[38:41], v[176:179], v[200:203], v[38:41]
	v_mfma_f32_16x16x32_bf16 v[34:37], v[184:187], v[200:203], v[34:37]
	v_mfma_f32_16x16x32_bf16 v[22:25], v[176:179], v[208:211], v[22:25]
	v_mfma_f32_16x16x32_bf16 v[18:21], v[184:187], v[208:211], v[18:21]
	v_mfma_f32_16x16x32_bf16 v[6:9], v[176:179], v[216:219], v[6:9]
	v_mfma_f32_16x16x32_bf16 v[2:5], v[184:187], v[216:219], v[2:5]
	s_setprio 0
	s_barrier
	s_add_i32 s59, s59, 2
	s_add_u32 s34, s34, 0x100
	s_addc_u32 s35, s35, 0
	s_add_u32 s57, s57, 0x100
	s_addc_u32 s58, s58, 0
	s_cmp_gt_u32 s59, 13
	s_cbranch_scc0 .LBB0_2153
	s_and_b64 vcc, exec, s[14:15]
	s_cbranch_vccz .LBB0_2156
	s_barrier

; #define PG8_STAGE(bufoff, gbase, voff) do { _Pragma("unroll") for (int _i = 0; _i < 2; ++_i) \
;         __builtin_amdgcn_global_load_lds((const unsigned*)((const char*)(gbase) + (voff)[_i]), (PG8_LAS unsigned*)(lds + (bufoff) + ldsw + _i * 8192), 16, 0, 0); } while (0)
; #define PG8_LDA(dst, b, h) do { _Pragma("unroll") for (int m = 0; m < 4; ++m) _Pragma("unroll") for (int k = 0; k < 2; ++k) dst[m][k] = *(const PG8_LAS bf16x8*)(lds + PG8_SA(b, h) + aoff + m * 2048 + k * 1024); } while (0)
; #define PG8_LDB(dst, b, h) do { _Pragma("unroll") for (int n = 0; n < 2; ++n) _Pragma("unroll") for (int k = 0; k < 2; ++k) dst[n][k] = *(const PG8_LAS bf16x8*)(lds + PG8_SB(b, h) + boff + n * 2048 + k * 1024); } while (0)
; #define PG8_MMA(ai, bj, At, Bt) do { __builtin_amdgcn_s_setprio(1); _Pragma("unroll") for (int m = 0; m < 4; ++m) _Pragma("unroll") for (int n = 0; n < 2; ++n) _Pragma("unroll") for (int k = 0; k < 2; ++k) \
;         acc[ai][bj][m][n] = __builtin_amdgcn_mfma_f32_16x16x32_bf16(Bt[n][k], At[m][k], acc[ai][bj][m][n], 0, 0, 0); __builtin_amdgcn_s_setprio(0); } while (0)
; #define PG8_WAIT_V(n) asm volatile("s_waitcnt vmcnt(" #n ")" ::: "memory")
; #define PG8_WAIT_L(n) asm volatile("s_waitcnt lgkmcnt(" #n ")" ::: "memory")
; template <class Epi, class Sched, bool ALIGN_EPI = false, bool SP2 = false>
; __device__ __forceinline__ void gemm_phase(PG8_LAS unsigned char* lds, const Gemm g, const Sched& S, const Epi& E) {
;     ...
;             const bool last = (t == nt - 2);
;             const char* a1 = cA + (size_t)(t + 1) * kstep;
;             const char* a2 = last ? nA : cA + (size_t)(t + 2) * kstep; const char* b2 = last ? nB : cB + (size_t)(t + 2) * kstep;
;             const char* a3 = a2 + kstep; const char* b3 = b2 + kstep;
;             if (last && has_next) S.a_ready(nxt);
;             if constexpr (SP2) {
;             PG8_LDB(B0, 0, 0); PG8_LDB(B1, 0, 1); PG8_SCHED; PG8_LDA(At, 0, 0); PG8_STAGE(PG8_SA(1, 1), a1 + hstepA, voffA);
;             PG8_WAIT_V(8); PG8_WAIT_L(0); PG8_BAR; PG8_MMA(0, 0, At, B0); PG8_MMA(0, 1, At, B1); PG8_BAR; PG8_SCHED;
;             PG8_LDA(At, 0, 1); PG8_STAGE(PG8_SB(0, 0), b2, voffB); PG8_STAGE(PG8_SB(0, 1), b2 + hstepB, voffB); PG8_STAGE(PG8_SA(0, 0), a2, voffA);
;             PG8_WAIT_V(8); PG8_WAIT_L(0); PG8_BAR; PG8_MMA(1, 0, At, B0); PG8_MMA(1, 1, At, B1); PG8_BAR; PG8_SCHED;
.LBB0_2500:
	v_add_u32_e32 v24, s53, v22
	ds_read_b128 v[34:37], v24
	ds_read_b128 v[38:41], v24 offset:1024
	ds_read_b128 v[42:45], v24 offset:2048
	ds_read_b128 v[46:49], v24 offset:3072
	v_add_u32_e32 v24, s54, v22
	s_add_u32 s30, s0, s28
	ds_read_b128 v[50:53], v24
	ds_read_b128 v[54:57], v24 offset:1024
	ds_read_b128 v[66:69], v24 offset:2048
	ds_read_b128 v[70:73], v24 offset:3072
	s_addc_u32 s31, s1, s29
	s_add_u32 s30, s30, 0x100
	s_addc_u32 s31, s31, 0
	s_add_u32 s61, s56, s28
	s_addc_u32 s62, s57, s29
	s_cmpk_eq_i32 s28, 0x700
	s_cselect_b32 s35, s23, s31
	s_cselect_b32 s34, s58, s30
	s_cselect_b32 s31, s21, s62
	s_cselect_b32 s30, s59, s61
	v_lshl_add_u64 v[24:25], v[18:19], 0, s[28:29]
	s_add_i32 m0, s45, 0xc000
	ds_read_b128 v[162:165], v23
	ds_read_b128 v[166:169], v23 offset:1024
	ds_read_b128 v[194:197], v23 offset:2048
	ds_read_b128 v[198:201], v23 offset:3072
	ds_read_b128 v[202:205], v23 offset:4096
	ds_read_b128 v[206:209], v23 offset:5120
	ds_read_b128 v[210:213], v23 offset:6144
	ds_read_b128 v[216:219], v23 offset:7168
	global_load_lds_dwordx4 v[24:25], off
	v_lshl_add_u64 v[24:25], v[20:21], 0, s[28:29]
	s_add_i32 m0, s45, 0xe000
	s_nop 0
	global_load_lds_dwordx4 v[24:25], off
	s_waitcnt vmcnt(8)
	s_waitcnt lgkmcnt(0)
	s_barrier
	s_setprio 1
	s_waitcnt lgkmcnt(0)
	v_mfma_f32_16x16x32_bf16 v[170:173], v[34:37], v[162:165], v[170:173]
	v_mfma_f32_16x16x32_bf16 v[174:177], v[42:45], v[162:165], v[174:177]
	v_mfma_f32_16x16x32_bf16 v[178:181], v[34:37], v[194:197], v[178:181]
	v_mfma_f32_16x16x32_bf16 v[182:185], v[42:45], v[194:197], v[182:185]
	v_mfma_f32_16x16x32_bf16 v[186:189], v[34:37], v[202:205], v[186:189]
	v_mfma_f32_16x16x32_bf16 v[190:193], v[42:45], v[202:205], v[190:193]
	v_mfma_f32_16x16x32_bf16 v[158:161], v[34:37], v[210:213], v[158:161]
	v_mfma_f32_16x16x32_bf16 v[154:157], v[42:45], v[210:213], v[154:157]
	v_mfma_f32_16x16x32_bf16 v[170:173], v[38:41], v[166:169], v[170:173]
	v_mfma_f32_16x16x32_bf16 v[174:177], v[46:49], v[166:169], v[174:177]
	v_mfma_f32_16x16x32_bf16 v[178:181], v[38:41], v[198:201], v[178:181]
	v_mfma_f32_16x16x32_bf16 v[182:185], v[46:49], v[198:201], v[182:185]
	v_mfma_f32_16x16x32_bf16 v[186:189], v[38:41], v[206:209], v[186:189]
	v_mfma_f32_16x16x32_bf16 v[190:193], v[46:49], v[206:209], v[190:193]
	v_mfma_f32_16x16x32_bf16 v[158:161], v[38:41], v[216:219], v[158:161]
	v_mfma_f32_16x16x32_bf16 v[154:157], v[46:49], v[216:219], v[154:157]
	s_setprio 0
	s_setprio 1
	v_mfma_f32_16x16x32_bf16 v[62:65], v[50:53], v[162:165], v[62:65]
	v_mfma_f32_16x16x32_bf16 v[58:61], v[66:69], v[162:165], v[58:61]
	v_mfma_f32_16x16x32_bf16 v[74:77], v[50:53], v[194:197], v[74:77]
	v_mfma_f32_16x16x32_bf16 v[78:81], v[66:69], v[194:197], v[78:81]
	v_mfma_f32_16x16x32_bf16 v[94:97], v[50:53], v[202:205], v[94:97]
	v_mfma_f32_16x16x32_bf16 v[98:101], v[66:69], v[202:205], v[98:101]
	v_mfma_f32_16x16x32_bf16 v[106:109], v[50:53], v[210:213], v[106:109]
	v_mfma_f32_16x16x32_bf16 v[110:113], v[66:69], v[210:213], v[110:113]
	v_mfma_f32_16x16x32_bf16 v[62:65], v[54:57], v[166:169], v[62:65]
	v_mfma_f32_16x16x32_bf16 v[58:61], v[70:73], v[166:169], v[58:61]
	v_mfma_f32_16x16x32_bf16 v[74:77], v[54:57], v[198:201], v[74:77]
	v_mfma_f32_16x16x32_bf16 v[78:81], v[70:73], v[198:201], v[78:81]
	v_mfma_f32_16x16x32_bf16 v[94:97], v[54:57], v[206:209], v[94:97]
	v_mfma_f32_16x16x32_bf16 v[98:101], v[70:73], v[206:209], v[98:101]
	v_mfma_f32_16x16x32_bf16 v[106:109], v[54:57], v[216:219], v[106:109]
	v_mfma_f32_16x16x32_bf16 v[110:113], v[70:73], v[216:219], v[110:113]
	s_setprio 0
	s_barrier
	s_add_i32 s61, s53, s44
	s_add_u32 s98, s30, 0x80
	s_addc_u32 s99, s31, 0
	s_mov_b32 m0, s61
	ds_read_b128 v[162:165], v23 offset:16384
	ds_read_b128 v[166:169], v23 offset:17408
	ds_read_b128 v[194:197], v23 offset:18432
	ds_read_b128 v[198:201], v23 offset:19456
	ds_read_b128 v[202:205], v23 offset:20480
	ds_read_b128 v[206:209], v23 offset:21504
	ds_read_b128 v[210:213], v23 offset:22528
	ds_read_b128 v[216:219], v23 offset:23552
	global_load_lds_dwordx4 v4, s[30:31]
	s_add_i32 m0, s61, 0x2000
	s_add_u32 s62, s30, 0x40000
	s_addc_u32 s63, s31, 0
	s_add_i32 s61, s54, s44
	global_load_lds_dwordx4 v8, s[30:31]
	s_mov_b32 m0, s61
	s_add_u32 s100, s34, 0x80
	s_addc_u32 s101, s35, 0
	global_load_lds_dwordx4 v4, s[62:63]
	s_add_i32 m0, s61, 0x2000
	s_nop 0
	global_load_lds_dwordx4 v8, s[62:63]
	s_mov_b32 m0, s45
	s_nop 0
	global_load_lds_dwordx4 v2, s[34:35]
	s_mov_b32 m0, s46
	s_nop 0
	global_load_lds_dwordx4 v6, s[34:35]
	s_waitcnt vmcnt(8)
	s_waitcnt lgkmcnt(0)
	s_barrier
; #define PG8_STAGE(bufoff, gbase, voff) do { _Pragma("unroll") for (int _i = 0; _i < 2; ++_i) \
;         __builtin_amdgcn_global_load_lds((const unsigned*)((const char*)(gbase) + (voff)[_i]), (PG8_LAS unsigned*)(lds + (bufoff) + ldsw + _i * 8192), 16, 0, 0); } while (0)
; #define PG8_LDA(dst, b, h) do { _Pragma("unroll") for (int m = 0; m < 4; ++m) _Pragma("unroll") for (int k = 0; k < 2; ++k) dst[m][k] = *(const PG8_LAS bf16x8*)(lds + PG8_SA(b, h) + aoff + m * 2048 + k * 1024); } while (0)
; #define PG8_LDB(dst, b, h) do { _Pragma("unroll") for (int n = 0; n < 2; ++n) _Pragma("unroll") for (int k = 0; k < 2; ++k) dst[n][k] = *(const PG8_LAS bf16x8*)(lds + PG8_SB(b, h) + boff + n * 2048 + k * 1024); } while (0)
; #define PG8_MMA(ai, bj, At, Bt) do { __builtin_amdgcn_s_setprio(1); _Pragma("unroll") for (int m = 0; m < 4; ++m) _Pragma("unroll") for (int n = 0; n < 2; ++n) _Pragma("unroll") for (int k = 0; k < 2; ++k) \
;         acc[ai][bj][m][n] = __builtin_amdgcn_mfma_f32_16x16x32_bf16(Bt[n][k], At[m][k], acc[ai][bj][m][n], 0, 0, 0); __builtin_amdgcn_s_setprio(0); } while (0)
; #define PG8_WAIT_V(n) asm volatile("s_waitcnt vmcnt(" #n ")" ::: "memory")
; #define PG8_WAIT_L(n) asm volatile("s_waitcnt lgkmcnt(" #n ")" ::: "memory")
; #define PG8_BAR __builtin_amdgcn_s_barrier()
; #define PG8_SCHED __builtin_amdgcn_sched_barrier(0)
; template <class Epi, class Sched, bool ALIGN_EPI = false, bool SP2 = false>
; __device__ __forceinline__ void gemm_phase(PG8_LAS unsigned char* lds, const Gemm g, const Sched& S, const Epi& E) {
;     ...
;             PG8_WAIT_V(8); PG8_WAIT_L(0); PG8_BAR; PG8_MMA(1, 0, At, B0); PG8_MMA(1, 1, At, B1); PG8_BAR; PG8_SCHED;
;             PG8_LDB(B0, 1, 0); PG8_LDB(B1, 1, 1); PG8_SCHED; PG8_LDA(At, 1, 0); PG8_STAGE(PG8_SA(0, 1), a2 + hstepA, voffA);
;             PG8_WAIT_V(8); PG8_WAIT_L(0); PG8_BAR; PG8_MMA(0, 0, At, B0); PG8_MMA(0, 1, At, B1); PG8_BAR; PG8_SCHED;
	s_setprio 1
	s_waitcnt lgkmcnt(0)
	v_mfma_f32_16x16x32_bf16 v[150:153], v[34:37], v[162:165], v[150:153]
	v_mfma_f32_16x16x32_bf16 v[146:149], v[42:45], v[162:165], v[146:149]
	v_mfma_f32_16x16x32_bf16 v[142:145], v[34:37], v[194:197], v[142:145]
	v_mfma_f32_16x16x32_bf16 v[138:141], v[42:45], v[194:197], v[138:141]
	v_mfma_f32_16x16x32_bf16 v[134:137], v[34:37], v[202:205], v[134:137]
	v_mfma_f32_16x16x32_bf16 v[130:133], v[42:45], v[202:205], v[130:133]
	v_mfma_f32_16x16x32_bf16 v[34:37], v[34:37], v[210:213], v[90:93]
	v_mfma_f32_16x16x32_bf16 v[150:153], v[38:41], v[166:169], v[150:153]
	v_mfma_f32_16x16x32_bf16 v[146:149], v[46:49], v[166:169], v[146:149]
	v_mfma_f32_16x16x32_bf16 v[142:145], v[38:41], v[198:201], v[142:145]
	v_mfma_f32_16x16x32_bf16 v[138:141], v[46:49], v[198:201], v[138:141]
	v_mfma_f32_16x16x32_bf16 v[134:137], v[38:41], v[206:209], v[134:137]
	v_mfma_f32_16x16x32_bf16 v[130:133], v[46:49], v[206:209], v[130:133]
	v_mfma_f32_16x16x32_bf16 v[34:37], v[38:41], v[216:219], v[34:37]
	v_mfma_f32_16x16x32_bf16 v[38:41], v[42:45], v[210:213], v[82:85]
	v_mfma_f32_16x16x32_bf16 v[38:41], v[46:49], v[216:219], v[38:41]
	s_setprio 0
	s_setprio 1
	v_mfma_f32_16x16x32_bf16 v[82:85], v[50:53], v[194:197], v[122:125]
	v_mfma_f32_16x16x32_bf16 v[122:125], v[54:57], v[198:201], v[82:85]
	v_mfma_f32_16x16x32_bf16 v[82:85], v[66:69], v[194:197], v[126:129]
	v_mfma_f32_16x16x32_bf16 v[126:129], v[70:73], v[198:201], v[82:85]
	v_mfma_f32_16x16x32_bf16 v[82:85], v[50:53], v[202:205], v[102:105]
	v_mfma_f32_16x16x32_bf16 v[102:105], v[54:57], v[206:209], v[82:85]
	v_mfma_f32_16x16x32_bf16 v[82:85], v[66:69], v[202:205], v[86:89]
	v_mfma_f32_16x16x32_bf16 v[30:33], v[50:53], v[210:213], v[30:33]
	v_mfma_f32_16x16x32_bf16 v[24:27], v[66:69], v[210:213], v[26:29]
	v_mfma_f32_16x16x32_bf16 v[42:45], v[50:53], v[162:165], v[114:117]
	v_mfma_f32_16x16x32_bf16 v[46:49], v[66:69], v[162:165], v[118:121]
	v_mfma_f32_16x16x32_bf16 v[86:89], v[70:73], v[206:209], v[82:85]
	v_mfma_f32_16x16x32_bf16 v[30:33], v[54:57], v[216:219], v[30:33]
	v_mfma_f32_16x16x32_bf16 v[24:27], v[70:73], v[216:219], v[24:27]
	v_mfma_f32_16x16x32_bf16 v[42:45], v[54:57], v[166:169], v[42:45]
	v_mfma_f32_16x16x32_bf16 v[46:49], v[70:73], v[166:169], v[46:49]
	s_setprio 0
	s_barrier
	s_add_i32 s61, 0, 0x18000
	v_add_u32_e32 v28, s61, v22
	s_add_i32 s62, 0, 0x1c000
	ds_read_b128 v[50:53], v28
	ds_read_b128 v[54:57], v28 offset:1024
	ds_read_b128 v[66:69], v28 offset:2048
	ds_read_b128 v[70:73], v28 offset:3072
	v_add_u32_e32 v28, s62, v22
	ds_read_b128 v[162:165], v28
	ds_read_b128 v[166:169], v28 offset:1024
	ds_read_b128 v[194:197], v28 offset:2048
	ds_read_b128 v[198:201], v28 offset:3072
	s_add_u32 s34, s34, 0x40000
	s_addc_u32 s35, s35, 0
	s_mov_b32 m0, s48
	ds_read_b128 v[82:85], v23 offset:32768
	ds_read_b128 v[90:93], v23 offset:33792
	ds_read_b128 v[114:117], v23 offset:34816
	ds_read_b128 v[118:121], v23 offset:35840
	ds_read_b128 v[202:205], v23 offset:36864
	ds_read_b128 v[206:209], v23 offset:37888
	ds_read_b128 v[210:213], v23 offset:38912
	ds_read_b128 v[216:219], v23 offset:39936
	global_load_lds_dwordx4 v2, s[34:35]
	s_mov_b32 m0, s49
	s_nop 0
	global_load_lds_dwordx4 v6, s[34:35]
	s_waitcnt vmcnt(8)
	s_waitcnt lgkmcnt(0)
	s_barrier
	s_setprio 1
	s_waitcnt lgkmcnt(0)
	v_mfma_f32_16x16x32_bf16 v[170:173], v[50:53], v[82:85], v[170:173]
	v_mfma_f32_16x16x32_bf16 v[174:177], v[66:69], v[82:85], v[174:177]
	v_mfma_f32_16x16x32_bf16 v[178:181], v[50:53], v[114:117], v[178:181]
	v_mfma_f32_16x16x32_bf16 v[182:185], v[66:69], v[114:117], v[182:185]
	v_mfma_f32_16x16x32_bf16 v[186:189], v[50:53], v[202:205], v[186:189]
	v_mfma_f32_16x16x32_bf16 v[190:193], v[66:69], v[202:205], v[190:193]
	v_mfma_f32_16x16x32_bf16 v[158:161], v[50:53], v[210:213], v[158:161]
	v_mfma_f32_16x16x32_bf16 v[154:157], v[66:69], v[210:213], v[154:157]
	v_mfma_f32_16x16x32_bf16 v[170:173], v[54:57], v[90:93], v[170:173]
	v_mfma_f32_16x16x32_bf16 v[174:177], v[70:73], v[90:93], v[174:177]
	v_mfma_f32_16x16x32_bf16 v[178:181], v[54:57], v[118:121], v[178:181]
	v_mfma_f32_16x16x32_bf16 v[182:185], v[70:73], v[118:121], v[182:185]
	v_mfma_f32_16x16x32_bf16 v[186:189], v[54:57], v[206:209], v[186:189]
	v_mfma_f32_16x16x32_bf16 v[190:193], v[70:73], v[206:209], v[190:193]
	v_mfma_f32_16x16x32_bf16 v[158:161], v[54:57], v[216:219], v[158:161]
	v_mfma_f32_16x16x32_bf16 v[154:157], v[70:73], v[216:219], v[154:157]
	s_setprio 0
	s_setprio 1
	v_mfma_f32_16x16x32_bf16 v[62:65], v[162:165], v[82:85], v[62:65]
	v_mfma_f32_16x16x32_bf16 v[58:61], v[194:197], v[82:85], v[58:61]
	v_mfma_f32_16x16x32_bf16 v[82:85], v[162:165], v[202:205], v[94:97]
	v_mfma_f32_16x16x32_bf16 v[94:97], v[166:169], v[206:209], v[82:85]
	v_mfma_f32_16x16x32_bf16 v[82:85], v[194:197], v[202:205], v[98:101]
	v_mfma_f32_16x16x32_bf16 v[98:101], v[198:201], v[206:209], v[82:85]
	v_mfma_f32_16x16x32_bf16 v[82:85], v[162:165], v[210:213], v[106:109]
	v_mfma_f32_16x16x32_bf16 v[74:77], v[162:165], v[114:117], v[74:77]
	v_mfma_f32_16x16x32_bf16 v[78:81], v[194:197], v[114:117], v[78:81]
	v_mfma_f32_16x16x32_bf16 v[106:109], v[166:169], v[216:219], v[82:85]
	v_mfma_f32_16x16x32_bf16 v[82:85], v[194:197], v[210:213], v[110:113]
	v_mfma_f32_16x16x32_bf16 v[62:65], v[166:169], v[90:93], v[62:65]
	v_mfma_f32_16x16x32_bf16 v[58:61], v[198:201], v[90:93], v[58:61]
	v_mfma_f32_16x16x32_bf16 v[74:77], v[166:169], v[118:121], v[74:77]
	v_mfma_f32_16x16x32_bf16 v[78:81], v[198:201], v[118:121], v[78:81]
	v_mfma_f32_16x16x32_bf16 v[110:113], v[198:201], v[216:219], v[82:85]
	s_setprio 0
	s_barrier
; #define PG8_STAGE(bufoff, gbase, voff) do { _Pragma("unroll") for (int _i = 0; _i < 2; ++_i) \
;         __builtin_amdgcn_global_load_lds((const unsigned*)((const char*)(gbase) + (voff)[_i]), (PG8_LAS unsigned*)(lds + (bufoff) + ldsw + _i * 8192), 16, 0, 0); } while (0)
; #define PG8_LDA(dst, b, h) do { _Pragma("unroll") for (int m = 0; m < 4; ++m) _Pragma("unroll") for (int k = 0; k < 2; ++k) dst[m][k] = *(const PG8_LAS bf16x8*)(lds + PG8_SA(b, h) + aoff + m * 2048 + k * 1024); } while (0)
; #define PG8_MMA(ai, bj, At, Bt) do { __builtin_amdgcn_s_setprio(1); _Pragma("unroll") for (int m = 0; m < 4; ++m) _Pragma("unroll") for (int n = 0; n < 2; ++n) _Pragma("unroll") for (int k = 0; k < 2; ++k) \
;         acc[ai][bj][m][n] = __builtin_amdgcn_mfma_f32_16x16x32_bf16(Bt[n][k], At[m][k], acc[ai][bj][m][n], 0, 0, 0); __builtin_amdgcn_s_setprio(0); } while (0)
; #define PG8_WAIT_V(n) asm volatile("s_waitcnt vmcnt(" #n ")" ::: "memory")
; #define PG8_WAIT_L(n) asm volatile("s_waitcnt lgkmcnt(" #n ")" ::: "memory")
; #define PG8_BAR __builtin_amdgcn_s_barrier()
; #define PG8_SCHED __builtin_amdgcn_sched_barrier(0)
; template <class Epi, class Sched, bool ALIGN_EPI = false, bool SP2 = false>
; __device__ __forceinline__ void gemm_phase(PG8_LAS unsigned char* lds, const Gemm g, const Sched& S, const Epi& E) {
;     ...
;             PG8_LDA(At, 1, 1); PG8_STAGE(PG8_SB(1, 0), b3, voffB); PG8_STAGE(PG8_SB(1, 1), b3 + hstepB, voffB); PG8_STAGE(PG8_SA(1, 0), a3, voffA);
;             PG8_WAIT_V(8); PG8_WAIT_L(0); PG8_BAR; PG8_MMA(1, 0, At, B0); PG8_MMA(1, 1, At, B1); PG8_BAR; PG8_SCHED;
;     ...
; #pragma unroll
;         for (int a = 0; a < 2; ++a)
; #pragma unroll
;             for (int b = 0; b < 2; ++b)
; #pragma unroll
;                 for (int m = 0; m < 4; ++m)
; #pragma unroll
;                     for (int n = 0; n < 2; ++n) acc[a][b][m][n] = (f32x4){0.f, 0.f, 0.f, 0.f};
;         cur = nxt; cA = nA; cB = nB; ++ui;
	s_add_i32 s34, s61, s44
	s_mov_b32 m0, s34
	ds_read_b128 v[118:121], v23 offset:49152
	ds_read_b128 v[202:205], v23 offset:50176
	ds_read_b128 v[206:209], v23 offset:51200
	ds_read_b128 v[210:213], v23 offset:52224
	ds_read_b128 v[216:219], v23 offset:53248
	ds_read_b128 v[220:223], v23 offset:54272
	ds_read_b128 v[224:227], v23 offset:55296
	ds_read_b128 v[228:231], v23 offset:56320
	global_load_lds_dwordx4 v4, s[98:99]
	s_add_i32 m0, s34, 0x2000
	s_add_u32 s30, s30, 0x40080
	s_addc_u32 s31, s31, 0
	s_add_i32 s34, s62, s44
	global_load_lds_dwordx4 v8, s[98:99]
	s_mov_b32 m0, s34
	s_nop 0
	global_load_lds_dwordx4 v4, s[30:31]
	s_add_i32 m0, s34, 0x2000
	s_nop 0
	global_load_lds_dwordx4 v8, s[30:31]
	s_mov_b32 m0, s51
	s_nop 0
	global_load_lds_dwordx4 v2, s[100:101]
	s_mov_b32 m0, s52
	s_nop 0
	global_load_lds_dwordx4 v6, s[100:101]
	s_waitcnt vmcnt(8)
	s_waitcnt lgkmcnt(0)
	s_barrier
	s_setprio 1
	s_waitcnt lgkmcnt(0)
	v_mfma_f32_16x16x32_bf16 v[82:85], v[50:53], v[118:121], v[150:153]
	v_mfma_f32_16x16x32_bf16 v[150:153], v[54:57], v[202:205], v[82:85]
	v_mfma_f32_16x16x32_bf16 v[82:85], v[66:69], v[118:121], v[146:149]
	v_mfma_f32_16x16x32_bf16 v[146:149], v[70:73], v[202:205], v[82:85]
	v_mfma_f32_16x16x32_bf16 v[82:85], v[50:53], v[206:209], v[142:145]
	v_mfma_f32_16x16x32_bf16 v[142:145], v[54:57], v[210:213], v[82:85]
	v_mfma_f32_16x16x32_bf16 v[82:85], v[66:69], v[206:209], v[138:141]
	v_mfma_f32_16x16x32_bf16 v[138:141], v[70:73], v[210:213], v[82:85]
	v_mfma_f32_16x16x32_bf16 v[82:85], v[50:53], v[216:219], v[134:137]
	v_mfma_f32_16x16x32_bf16 v[34:37], v[50:53], v[224:227], v[34:37]
	v_mfma_f32_16x16x32_bf16 v[134:137], v[54:57], v[220:223], v[82:85]
	v_mfma_f32_16x16x32_bf16 v[82:85], v[66:69], v[216:219], v[130:133]
	v_mfma_f32_16x16x32_bf16 v[90:93], v[54:57], v[228:231], v[34:37]
	v_mfma_f32_16x16x32_bf16 v[34:37], v[66:69], v[224:227], v[38:41]
	v_mfma_f32_16x16x32_bf16 v[130:133], v[70:73], v[220:223], v[82:85]
	v_mfma_f32_16x16x32_bf16 v[82:85], v[70:73], v[228:231], v[34:37]
	s_setprio 0
	s_setprio 1
	v_mfma_f32_16x16x32_bf16 v[34:37], v[162:165], v[118:121], v[42:45]
	v_mfma_f32_16x16x32_bf16 v[114:117], v[166:169], v[202:205], v[34:37]
	v_mfma_f32_16x16x32_bf16 v[34:37], v[194:197], v[118:121], v[46:49]
	v_mfma_f32_16x16x32_bf16 v[118:121], v[198:201], v[202:205], v[34:37]
	v_mfma_f32_16x16x32_bf16 v[34:37], v[162:165], v[206:209], v[122:125]
	v_mfma_f32_16x16x32_bf16 v[122:125], v[166:169], v[210:213], v[34:37]
	v_mfma_f32_16x16x32_bf16 v[34:37], v[194:197], v[206:209], v[126:129]
	v_mfma_f32_16x16x32_bf16 v[126:129], v[198:201], v[210:213], v[34:37]
	v_mfma_f32_16x16x32_bf16 v[34:37], v[162:165], v[216:219], v[102:105]
	v_mfma_f32_16x16x32_bf16 v[102:105], v[166:169], v[220:223], v[34:37]
	v_mfma_f32_16x16x32_bf16 v[34:37], v[194:197], v[216:219], v[86:89]
	v_mfma_f32_16x16x32_bf16 v[28:31], v[162:165], v[224:227], v[30:33]
	v_mfma_f32_16x16x32_bf16 v[24:27], v[194:197], v[224:227], v[24:27]
	v_mfma_f32_16x16x32_bf16 v[86:89], v[198:201], v[220:223], v[34:37]
	v_mfma_f32_16x16x32_bf16 v[30:33], v[166:169], v[228:231], v[28:31]
	v_mfma_f32_16x16x32_bf16 v[26:29], v[198:201], v[228:231], v[24:27]
	s_setprio 0
	s_barrier
	s_add_i32 s60, s60, 2
	s_add_u32 s28, s28, 0x100
	s_addc_u32 s29, s29, 0
	s_cmp_gt_u32 s60, 13
	s_cbranch_scc0 .LBB0_2500
	s_add_u32 s28, s56, 0xffffff00
	s_addc_u32 s29, s57, -1
	s_andn2_b64 vcc, exec, s[4:5]
	s_cbranch_vccnz .LBB0_2491
	v_mov_b32_e32 v26, 0
	s_mov_b32 s16, s20
	s_mov_b32 s14, s22
	s_mov_b64 s[0:1], s[26:27]
	s_mov_b32 s50, s55
	v_mov_b32_e32 v27, v26
	v_mov_b32_e32 v28, v26
	v_mov_b32_e32 v29, v26
	v_mov_b32_e32 v30, v26
	v_mov_b32_e32 v31, v26
	v_mov_b32_e32 v32, v26
	v_mov_b32_e32 v33, v26
	v_mov_b32_e32 v86, v26
	v_mov_b32_e32 v87, v26
	v_mov_b32_e32 v88, v26
	v_mov_b32_e32 v89, v26
	v_mov_b32_e32 v102, v26
	v_mov_b32_e32 v103, v26
	v_mov_b32_e32 v104, v26
	v_mov_b32_e32 v105, v26
	v_mov_b32_e32 v126, v26
	v_mov_b32_e32 v127, v26
	v_mov_b32_e32 v128, v26
	v_mov_b32_e32 v129, v26
	v_mov_b32_e32 v122, v26
	v_mov_b32_e32 v123, v26
	v_mov_b32_e32 v124, v26
	v_mov_b32_e32 v125, v26
	v_mov_b32_e32 v118, v26
	v_mov_b32_e32 v119, v26
	v_mov_b32_e32 v120, v26
	v_mov_b32_e32 v121, v26
	v_mov_b32_e32 v114, v26
	v_mov_b32_e32 v115, v26
	v_mov_b32_e32 v116, v26
	v_mov_b32_e32 v117, v26
	v_mov_b32_e32 v82, v26
	v_mov_b32_e32 v83, v26
	v_mov_b32_e32 v84, v26
	v_mov_b32_e32 v85, v26
	v_mov_b32_e32 v90, v26
	v_mov_b32_e32 v91, v26
	v_mov_b32_e32 v92, v26
	v_mov_b32_e32 v93, v26
	v_mov_b32_e32 v130, v26
	v_mov_b32_e32 v131, v26
	v_mov_b32_e32 v132, v26
	v_mov_b32_e32 v133, v26
	v_mov_b32_e32 v134, v26
	v_mov_b32_e32 v135, v26
	v_mov_b32_e32 v136, v26
	v_mov_b32_e32 v137, v26
	v_mov_b32_e32 v138, v26
	v_mov_b32_e32 v139, v26
	v_mov_b32_e32 v140, v26
	v_mov_b32_e32 v141, v26
	v_mov_b32_e32 v142, v26
	v_mov_b32_e32 v143, v26
	v_mov_b32_e32 v144, v26
	v_mov_b32_e32 v145, v26
	v_mov_b32_e32 v146, v26
	v_mov_b32_e32 v147, v26
	v_mov_b32_e32 v148, v26
	v_mov_b32_e32 v149, v26
	v_mov_b32_e32 v150, v26
	v_mov_b32_e32 v151, v26
	v_mov_b32_e32 v152, v26
	v_mov_b32_e32 v153, v26
	v_mov_b32_e32 v110, v26
	v_mov_b32_e32 v111, v26
	v_mov_b32_e32 v112, v26
	v_mov_b32_e32 v113, v26
	v_mov_b32_e32 v106, v26
	v_mov_b32_e32 v107, v26
	v_mov_b32_e32 v108, v26
	v_mov_b32_e32 v109, v26
	v_mov_b32_e32 v98, v26
	v_mov_b32_e32 v99, v26
	v_mov_b32_e32 v100, v26
	v_mov_b32_e32 v101, v26
	v_mov_b32_e32 v94, v26
	v_mov_b32_e32 v95, v26
	v_mov_b32_e32 v96, v26
	v_mov_b32_e32 v97, v26
	v_mov_b32_e32 v78, v26
	v_mov_b32_e32 v79, v26
	v_mov_b32_e32 v80, v26
	v_mov_b32_e32 v81, v26
	v_mov_b32_e32 v74, v26
	v_mov_b32_e32 v75, v26
	v_mov_b32_e32 v76, v26
	v_mov_b32_e32 v77, v26
	v_mov_b32_e32 v58, v26
	v_mov_b32_e32 v59, v26
	v_mov_b32_e32 v60, v26
	v_mov_b32_e32 v61, v26
	v_mov_b32_e32 v62, v26
	v_mov_b32_e32 v63, v26
	v_mov_b32_e32 v64, v26
	v_mov_b32_e32 v65, v26
	v_mov_b32_e32 v154, v26
	v_mov_b32_e32 v155, v26
	v_mov_b32_e32 v156, v26
	v_mov_b32_e32 v157, v26
	v_mov_b32_e32 v158, v26
	v_mov_b32_e32 v159, v26
	v_mov_b32_e32 v160, v26
	v_mov_b32_e32 v161, v26
	v_mov_b32_e32 v190, v26
	v_mov_b32_e32 v191, v26
	v_mov_b32_e32 v192, v26
	v_mov_b32_e32 v193, v26
	v_mov_b32_e32 v186, v26
	v_mov_b32_e32 v187, v26
	v_mov_b32_e32 v188, v26
	v_mov_b32_e32 v189, v26
	v_mov_b32_e32 v182, v26
	v_mov_b32_e32 v183, v26
	v_mov_b32_e32 v184, v26
	v_mov_b32_e32 v185, v26
	v_mov_b32_e32 v178, v26
	v_mov_b32_e32 v179, v26
	v_mov_b32_e32 v180, v26
	v_mov_b32_e32 v181, v26
	v_mov_b32_e32 v174, v26
	v_mov_b32_e32 v175, v26
	v_mov_b32_e32 v176, v26
	v_mov_b32_e32 v177, v26
	v_mov_b32_e32 v170, v26
	v_mov_b32_e32 v171, v26
	v_mov_b32_e32 v172, v26
	v_mov_b32_e32 v173, v26
	s_andn2_b64 vcc, exec, s[2:3]
	s_cbranch_vccnz .LBB0_2492

; #define PG8_STAGE(bufoff, gbase, voff) do { _Pragma("unroll") for (int _i = 0; _i < 2; ++_i) \
;         __builtin_amdgcn_global_load_lds((const unsigned*)((const char*)(gbase) + (voff)[_i]), (PG8_LAS unsigned*)(lds + (bufoff) + ldsw + _i * 8192), 16, 0, 0); } while (0)
; #define PG8_LDA(dst, b, h) do { _Pragma("unroll") for (int m = 0; m < 4; ++m) _Pragma("unroll") for (int k = 0; k < 2; ++k) dst[m][k] = *(const PG8_LAS bf16x8*)(lds + PG8_SA(b, h) + aoff + m * 2048 + k * 1024); } while (0)
; #define PG8_LDB(dst, b, h) do { _Pragma("unroll") for (int n = 0; n < 2; ++n) _Pragma("unroll") for (int k = 0; k < 2; ++k) dst[n][k] = *(const PG8_LAS bf16x8*)(lds + PG8_SB(b, h) + boff + n * 2048 + k * 1024); } while (0)
; #define PG8_MMA(ai, bj, At, Bt) do { __builtin_amdgcn_s_setprio(1); _Pragma("unroll") for (int m = 0; m < 4; ++m) _Pragma("unroll") for (int n = 0; n < 2; ++n) _Pragma("unroll") for (int k = 0; k < 2; ++k) \
;         acc[ai][bj][m][n] = __builtin_amdgcn_mfma_f32_16x16x32_bf16(Bt[n][k], At[m][k], acc[ai][bj][m][n], 0, 0, 0); __builtin_amdgcn_s_setprio(0); } while (0)
; #define PG8_WAIT_V(n) asm volatile("s_waitcnt vmcnt(" #n ")" ::: "memory")
; #define PG8_WAIT_L(n) asm volatile("s_waitcnt lgkmcnt(" #n ")" ::: "memory")
; template <class Epi, class Sched, bool ALIGN_EPI = false, bool SP2 = false>
; __device__ __forceinline__ void gemm_phase(PG8_LAS unsigned char* lds, const Gemm g, const Sched& S, const Epi& E) {
;     ...
;             const bool last = (t == nt - 2);
;             const char* a1 = cA + (size_t)(t + 1) * kstep;
;             const char* a2 = last ? nA : cA + (size_t)(t + 2) * kstep; const char* b2 = last ? nB : cB + (size_t)(t + 2) * kstep;
;             const char* a3 = a2 + kstep; const char* b3 = b2 + kstep;
;             if (last && has_next) S.a_ready(nxt);
;             if constexpr (SP2) {
;             PG8_LDB(B0, 0, 0); PG8_LDB(B1, 0, 1); PG8_SCHED; PG8_LDA(At, 0, 0); PG8_STAGE(PG8_SA(1, 1), a1 + hstepA, voffA);
;             PG8_WAIT_V(8); PG8_WAIT_L(0); PG8_BAR; PG8_MMA(0, 0, At, B0); PG8_MMA(0, 1, At, B1); PG8_BAR; PG8_SCHED;
;             PG8_LDA(At, 0, 1); PG8_STAGE(PG8_SB(0, 0), b2, voffB); PG8_STAGE(PG8_SB(0, 1), b2 + hstepB, voffB); PG8_STAGE(PG8_SA(0, 0), a2, voffA);
;             PG8_WAIT_V(8); PG8_WAIT_L(0); PG8_BAR; PG8_MMA(1, 0, At, B0); PG8_MMA(1, 1, At, B1); PG8_BAR; PG8_SCHED;
.LBB0_2613:
	ds_read_b128 v[130:133], v182
	ds_read_b128 v[134:137], v182 offset:1024
	ds_read_b128 v[154:157], v182 offset:2048
	ds_read_b128 v[158:161], v182 offset:3072
	ds_read_b128 v[162:165], v183
	ds_read_b128 v[166:169], v183 offset:1024
	ds_read_b128 v[170:173], v183 offset:2048
	ds_read_b128 v[186:189], v183 offset:3072
	s_add_u32 s44, s42, 0xfffc0080
	s_addc_u32 s45, s43, -1
	s_cmp_eq_u32 s70, 12
	s_cselect_b32 s47, s31, s45
	s_cselect_b32 s46, s39, s44
	s_cselect_b32 s45, s29, s69
	s_cselect_b32 s44, s67, s68
	s_add_i32 m0, s41, 0xc000
	ds_read_b128 v[190:193], v184
	ds_read_b128 v[194:197], v184 offset:1024
	ds_read_b128 v[198:201], v184 offset:2048
	ds_read_b128 v[202:205], v184 offset:3072
	ds_read_b128 v[206:209], v184 offset:4096
	ds_read_b128 v[210:213], v184 offset:5120
	ds_read_b128 v[214:217], v184 offset:6144
	ds_read_b128 v[218:221], v184 offset:7168
	global_load_lds_dwordx4 v146, s[42:43]
	s_add_i32 m0, s41, 0xe000
	s_nop 0
	global_load_lds_dwordx4 v148, s[42:43]
	s_waitcnt vmcnt(8)
	s_waitcnt lgkmcnt(0)
	s_barrier
	s_setprio 1
	s_waitcnt lgkmcnt(0)
	v_mfma_f32_16x16x32_bf16 v[126:129], v[130:133], v[190:193], v[126:129]
	v_mfma_f32_16x16x32_bf16 v[94:97], v[154:157], v[190:193], v[94:97]
	v_mfma_f32_16x16x32_bf16 v[118:121], v[130:133], v[198:201], v[118:121]
	v_mfma_f32_16x16x32_bf16 v[86:89], v[154:157], v[198:201], v[86:89]
	v_mfma_f32_16x16x32_bf16 v[114:117], v[130:133], v[206:209], v[114:117]
	v_mfma_f32_16x16x32_bf16 v[82:85], v[154:157], v[206:209], v[82:85]
	v_mfma_f32_16x16x32_bf16 v[102:105], v[130:133], v[214:217], v[102:105]
	v_mfma_f32_16x16x32_bf16 v[70:73], v[154:157], v[214:217], v[70:73]
	v_mfma_f32_16x16x32_bf16 v[126:129], v[134:137], v[194:197], v[126:129]
	v_mfma_f32_16x16x32_bf16 v[94:97], v[158:161], v[194:197], v[94:97]
	v_mfma_f32_16x16x32_bf16 v[118:121], v[134:137], v[202:205], v[118:121]
	v_mfma_f32_16x16x32_bf16 v[86:89], v[158:161], v[202:205], v[86:89]
	v_mfma_f32_16x16x32_bf16 v[114:117], v[134:137], v[210:213], v[114:117]
	v_mfma_f32_16x16x32_bf16 v[82:85], v[158:161], v[210:213], v[82:85]
	v_mfma_f32_16x16x32_bf16 v[102:105], v[134:137], v[218:221], v[102:105]
	v_mfma_f32_16x16x32_bf16 v[70:73], v[158:161], v[218:221], v[70:73]
	s_setprio 0
	s_setprio 1
	v_mfma_f32_16x16x32_bf16 v[122:125], v[162:165], v[190:193], v[122:125]
	v_mfma_f32_16x16x32_bf16 v[90:93], v[170:173], v[190:193], v[90:93]
	v_mfma_f32_16x16x32_bf16 v[110:113], v[162:165], v[198:201], v[110:113]
	v_mfma_f32_16x16x32_bf16 v[78:81], v[170:173], v[198:201], v[78:81]
	v_mfma_f32_16x16x32_bf16 v[106:109], v[162:165], v[206:209], v[106:109]
	v_mfma_f32_16x16x32_bf16 v[74:77], v[170:173], v[206:209], v[74:77]
	v_mfma_f32_16x16x32_bf16 v[98:101], v[162:165], v[214:217], v[98:101]
	v_mfma_f32_16x16x32_bf16 v[66:69], v[170:173], v[214:217], v[66:69]
	v_mfma_f32_16x16x32_bf16 v[122:125], v[166:169], v[194:197], v[122:125]
	v_mfma_f32_16x16x32_bf16 v[90:93], v[186:189], v[194:197], v[90:93]
	v_mfma_f32_16x16x32_bf16 v[110:113], v[166:169], v[202:205], v[110:113]
	v_mfma_f32_16x16x32_bf16 v[78:81], v[186:189], v[202:205], v[78:81]
	v_mfma_f32_16x16x32_bf16 v[106:109], v[166:169], v[210:213], v[106:109]
	v_mfma_f32_16x16x32_bf16 v[74:77], v[186:189], v[210:213], v[74:77]
	v_mfma_f32_16x16x32_bf16 v[98:101], v[166:169], v[218:221], v[98:101]
	v_mfma_f32_16x16x32_bf16 v[66:69], v[186:189], v[218:221], v[66:69]
	s_setprio 0
	s_barrier
	s_add_i32 s71, s64, s51
	s_add_u32 s98, s44, 0x80
	s_addc_u32 s99, s45, 0
	s_mov_b32 m0, s71
	ds_read_b128 v[190:193], v184 offset:16384
	ds_read_b128 v[194:197], v184 offset:17408
	ds_read_b128 v[198:201], v184 offset:18432
	ds_read_b128 v[202:205], v184 offset:19456
	ds_read_b128 v[206:209], v184 offset:20480
	ds_read_b128 v[210:213], v184 offset:21504
	ds_read_b128 v[214:217], v184 offset:22528
	ds_read_b128 v[218:221], v184 offset:23552
	global_load_lds_dwordx4 v140, s[44:45]
	s_add_i32 m0, s71, 0x2000
	s_add_u32 s72, s44, 0x40000
	s_addc_u32 s73, s45, 0
	s_add_i32 s71, s65, s51
	global_load_lds_dwordx4 v144, s[44:45]
	s_mov_b32 m0, s71
	v_lshl_add_u64 v[226:227], s[46:47], 0, v[142:143]
	global_load_lds_dwordx4 v140, s[72:73]
	s_add_i32 m0, s71, 0x2000
	s_nop 0
	global_load_lds_dwordx4 v144, s[72:73]
	s_add_u32 s100, s46, 0x80
	s_addc_u32 s101, s47, 0
	s_mov_b32 m0, s41
	s_nop 0
	global_load_lds_dwordx4 v138, s[46:47]
	s_mov_b32 m0, s52
	s_nop 0
	global_load_lds_dwordx4 v142, s[46:47]
	s_waitcnt vmcnt(8)
	s_waitcnt lgkmcnt(0)
	s_barrier
	s_setprio 1
	s_waitcnt lgkmcnt(0)
	v_mfma_f32_16x16x32_bf16 v[62:65], v[130:133], v[190:193], v[62:65]
	v_mfma_f32_16x16x32_bf16 v[30:33], v[154:157], v[190:193], v[30:33]
	v_mfma_f32_16x16x32_bf16 v[54:57], v[130:133], v[198:201], v[54:57]
	v_mfma_f32_16x16x32_bf16 v[22:25], v[154:157], v[198:201], v[22:25]
	v_mfma_f32_16x16x32_bf16 v[50:53], v[130:133], v[206:209], v[50:53]
	v_mfma_f32_16x16x32_bf16 v[18:21], v[154:157], v[206:209], v[18:21]
	v_mfma_f32_16x16x32_bf16 v[38:41], v[130:133], v[214:217], v[38:41]
	v_mfma_f32_16x16x32_bf16 v[6:9], v[154:157], v[214:217], v[6:9]
	v_mfma_f32_16x16x32_bf16 v[62:65], v[134:137], v[194:197], v[62:65]
	v_mfma_f32_16x16x32_bf16 v[30:33], v[158:161], v[194:197], v[30:33]
	v_mfma_f32_16x16x32_bf16 v[54:57], v[134:137], v[202:205], v[54:57]
	v_mfma_f32_16x16x32_bf16 v[22:25], v[158:161], v[202:205], v[22:25]
	v_mfma_f32_16x16x32_bf16 v[50:53], v[134:137], v[210:213], v[50:53]
	v_mfma_f32_16x16x32_bf16 v[18:21], v[158:161], v[210:213], v[18:21]
	v_mfma_f32_16x16x32_bf16 v[38:41], v[134:137], v[218:221], v[38:41]
	v_mfma_f32_16x16x32_bf16 v[6:9], v[158:161], v[218:221], v[6:9]
	s_setprio 0
	s_setprio 1
	v_mfma_f32_16x16x32_bf16 v[58:61], v[162:165], v[190:193], v[58:61]
	v_mfma_f32_16x16x32_bf16 v[26:29], v[170:173], v[190:193], v[26:29]
	v_mfma_f32_16x16x32_bf16 v[46:49], v[162:165], v[198:201], v[46:49]
	v_mfma_f32_16x16x32_bf16 v[14:17], v[170:173], v[198:201], v[14:17]
	v_mfma_f32_16x16x32_bf16 v[42:45], v[162:165], v[206:209], v[42:45]
	v_mfma_f32_16x16x32_bf16 v[10:13], v[170:173], v[206:209], v[10:13]
	v_mfma_f32_16x16x32_bf16 v[34:37], v[162:165], v[214:217], v[34:37]
	v_mfma_f32_16x16x32_bf16 v[2:5], v[170:173], v[214:217], v[2:5]
	v_mfma_f32_16x16x32_bf16 v[58:61], v[166:169], v[194:197], v[58:61]
	v_mfma_f32_16x16x32_bf16 v[26:29], v[186:189], v[194:197], v[26:29]
	v_mfma_f32_16x16x32_bf16 v[46:49], v[166:169], v[202:205], v[46:49]
	v_mfma_f32_16x16x32_bf16 v[14:17], v[186:189], v[202:205], v[14:17]
	v_mfma_f32_16x16x32_bf16 v[42:45], v[166:169], v[210:213], v[42:45]
	v_mfma_f32_16x16x32_bf16 v[10:13], v[186:189], v[210:213], v[10:13]
	v_mfma_f32_16x16x32_bf16 v[34:37], v[166:169], v[218:221], v[34:37]
	v_mfma_f32_16x16x32_bf16 v[2:5], v[186:189], v[218:221], v[2:5]
	s_setprio 0
	s_barrier
; #define PG8_STAGE(bufoff, gbase, voff) do { _Pragma("unroll") for (int _i = 0; _i < 2; ++_i) \
;         __builtin_amdgcn_global_load_lds((const unsigned*)((const char*)(gbase) + (voff)[_i]), (PG8_LAS unsigned*)(lds + (bufoff) + ldsw + _i * 8192), 16, 0, 0); } while (0)
; #define PG8_LDA(dst, b, h) do { _Pragma("unroll") for (int m = 0; m < 4; ++m) _Pragma("unroll") for (int k = 0; k < 2; ++k) dst[m][k] = *(const PG8_LAS bf16x8*)(lds + PG8_SA(b, h) + aoff + m * 2048 + k * 1024); } while (0)
; #define PG8_LDB(dst, b, h) do { _Pragma("unroll") for (int n = 0; n < 2; ++n) _Pragma("unroll") for (int k = 0; k < 2; ++k) dst[n][k] = *(const PG8_LAS bf16x8*)(lds + PG8_SB(b, h) + boff + n * 2048 + k * 1024); } while (0)
; #define PG8_MMA(ai, bj, At, Bt) do { __builtin_amdgcn_s_setprio(1); _Pragma("unroll") for (int m = 0; m < 4; ++m) _Pragma("unroll") for (int n = 0; n < 2; ++n) _Pragma("unroll") for (int k = 0; k < 2; ++k) \
;         acc[ai][bj][m][n] = __builtin_amdgcn_mfma_f32_16x16x32_bf16(Bt[n][k], At[m][k], acc[ai][bj][m][n], 0, 0, 0); __builtin_amdgcn_s_setprio(0); } while (0)
; #define PG8_WAIT_V(n) asm volatile("s_waitcnt vmcnt(" #n ")" ::: "memory")
; #define PG8_WAIT_L(n) asm volatile("s_waitcnt lgkmcnt(" #n ")" ::: "memory")
; #define PG8_BAR __builtin_amdgcn_s_barrier()
; #define PG8_SCHED __builtin_amdgcn_sched_barrier(0)
; template <class Epi, class Sched, bool ALIGN_EPI = false, bool SP2 = false>
; __device__ __forceinline__ void gemm_phase(PG8_LAS unsigned char* lds, const Gemm g, const Sched& S, const Epi& E) {
;     ...
;             PG8_LDB(B0, 1, 0); PG8_LDB(B1, 1, 1); PG8_SCHED; PG8_LDA(At, 1, 0); PG8_STAGE(PG8_SA(0, 1), a2 + hstepA, voffA);
;             PG8_WAIT_V(8); PG8_WAIT_L(0); PG8_BAR; PG8_MMA(0, 0, At, B0); PG8_MMA(0, 1, At, B1); PG8_BAR; PG8_SCHED;
;             PG8_LDA(At, 1, 1); PG8_STAGE(PG8_SB(1, 0), b3, voffB); PG8_STAGE(PG8_SB(1, 1), b3 + hstepB, voffB); PG8_STAGE(PG8_SA(1, 0), a3, voffA);
;             PG8_WAIT_V(8); PG8_WAIT_L(0); PG8_BAR; PG8_MMA(1, 0, At, B0); PG8_MMA(1, 1, At, B1); PG8_BAR; PG8_SCHED;
	s_add_i32 s71, 0, 0x18000
	s_add_i32 s72, 0, 0x1c000
	v_add_u32_e32 v158, s71, v176
	v_add_u32_e32 v185, s72, v176
	ds_read_b128 v[130:133], v158
	ds_read_b128 v[134:137], v158 offset:1024
	ds_read_b128 v[154:157], v158 offset:2048
	ds_read_b128 v[158:161], v158 offset:3072
	ds_read_b128 v[162:165], v185
	ds_read_b128 v[166:169], v185 offset:1024
	ds_read_b128 v[170:173], v185 offset:2048
	ds_read_b128 v[186:189], v185 offset:3072
	s_add_u32 s46, s46, 0x40000
	s_addc_u32 s47, s47, 0
	s_mov_b32 m0, s53
	ds_read_b128 v[190:193], v184 offset:32768
	ds_read_b128 v[194:197], v184 offset:33792
	ds_read_b128 v[198:201], v184 offset:34816
	ds_read_b128 v[202:205], v184 offset:35840
	ds_read_b128 v[206:209], v184 offset:36864
	ds_read_b128 v[210:213], v184 offset:37888
	ds_read_b128 v[214:217], v184 offset:38912
	ds_read_b128 v[218:221], v184 offset:39936
	global_load_lds_dwordx4 v138, s[46:47]
	s_mov_b32 m0, s54
	s_nop 0
	global_load_lds_dwordx4 v142, s[46:47]
	s_waitcnt vmcnt(8)
	s_waitcnt lgkmcnt(0)
	s_barrier
	s_setprio 1
	s_waitcnt lgkmcnt(0)
	v_mfma_f32_16x16x32_bf16 v[126:129], v[130:133], v[190:193], v[126:129]
	v_mfma_f32_16x16x32_bf16 v[94:97], v[154:157], v[190:193], v[94:97]
	v_mfma_f32_16x16x32_bf16 v[118:121], v[130:133], v[198:201], v[118:121]
	v_mfma_f32_16x16x32_bf16 v[86:89], v[154:157], v[198:201], v[86:89]
	v_mfma_f32_16x16x32_bf16 v[114:117], v[130:133], v[206:209], v[114:117]
	v_mfma_f32_16x16x32_bf16 v[82:85], v[154:157], v[206:209], v[82:85]
	v_mfma_f32_16x16x32_bf16 v[102:105], v[130:133], v[214:217], v[102:105]
	v_mfma_f32_16x16x32_bf16 v[70:73], v[154:157], v[214:217], v[70:73]
	v_mfma_f32_16x16x32_bf16 v[126:129], v[134:137], v[194:197], v[126:129]
	v_mfma_f32_16x16x32_bf16 v[94:97], v[158:161], v[194:197], v[94:97]
	v_mfma_f32_16x16x32_bf16 v[118:121], v[134:137], v[202:205], v[118:121]
	v_mfma_f32_16x16x32_bf16 v[86:89], v[158:161], v[202:205], v[86:89]
	v_mfma_f32_16x16x32_bf16 v[114:117], v[134:137], v[210:213], v[114:117]
	v_mfma_f32_16x16x32_bf16 v[82:85], v[158:161], v[210:213], v[82:85]
	v_mfma_f32_16x16x32_bf16 v[102:105], v[134:137], v[218:221], v[102:105]
	v_mfma_f32_16x16x32_bf16 v[70:73], v[158:161], v[218:221], v[70:73]
	s_setprio 0
	s_setprio 1
	v_mfma_f32_16x16x32_bf16 v[122:125], v[162:165], v[190:193], v[122:125]
	v_mfma_f32_16x16x32_bf16 v[90:93], v[170:173], v[190:193], v[90:93]
	v_mfma_f32_16x16x32_bf16 v[110:113], v[162:165], v[198:201], v[110:113]
	v_mfma_f32_16x16x32_bf16 v[78:81], v[170:173], v[198:201], v[78:81]
	v_mfma_f32_16x16x32_bf16 v[106:109], v[162:165], v[206:209], v[106:109]
	v_mfma_f32_16x16x32_bf16 v[74:77], v[170:173], v[206:209], v[74:77]
	v_mfma_f32_16x16x32_bf16 v[98:101], v[162:165], v[214:217], v[98:101]
	v_mfma_f32_16x16x32_bf16 v[66:69], v[170:173], v[214:217], v[66:69]
	v_mfma_f32_16x16x32_bf16 v[122:125], v[166:169], v[194:197], v[122:125]
	v_mfma_f32_16x16x32_bf16 v[90:93], v[186:189], v[194:197], v[90:93]
	v_mfma_f32_16x16x32_bf16 v[110:113], v[166:169], v[202:205], v[110:113]
	v_mfma_f32_16x16x32_bf16 v[78:81], v[186:189], v[202:205], v[78:81]
	v_mfma_f32_16x16x32_bf16 v[106:109], v[166:169], v[210:213], v[106:109]
	v_mfma_f32_16x16x32_bf16 v[74:77], v[186:189], v[210:213], v[74:77]
	v_mfma_f32_16x16x32_bf16 v[98:101], v[166:169], v[218:221], v[98:101]
	v_mfma_f32_16x16x32_bf16 v[66:69], v[186:189], v[218:221], v[66:69]
	s_setprio 0
	s_barrier
	s_add_i32 s46, s71, s51
	s_mov_b32 m0, s46
	ds_read_b128 v[190:193], v184 offset:49152
	ds_read_b128 v[194:197], v184 offset:50176
	ds_read_b128 v[198:201], v184 offset:51200
	ds_read_b128 v[202:205], v184 offset:52224
	ds_read_b128 v[206:209], v184 offset:53248
	ds_read_b128 v[210:213], v184 offset:54272
	ds_read_b128 v[214:217], v184 offset:55296
	ds_read_b128 v[218:221], v184 offset:56320
	global_load_lds_dwordx4 v140, s[98:99]
	s_add_i32 m0, s46, 0x2000
	s_add_u32 s44, s44, 0x40080
	s_addc_u32 s45, s45, 0
	s_add_i32 s46, s72, s51
	global_load_lds_dwordx4 v144, s[98:99]
	s_mov_b32 m0, s46
	s_nop 0
	global_load_lds_dwordx4 v140, s[44:45]
	s_add_i32 m0, s46, 0x2000
	s_nop 0
	global_load_lds_dwordx4 v144, s[44:45]
	s_mov_b32 m0, s59
	s_nop 0
	global_load_lds_dwordx4 v138, s[100:101]
	v_lshl_add_u64 v[174:175], v[226:227], 0, s[24:25]
	s_mov_b32 m0, s60
	s_nop 0
	global_load_lds_dwordx4 v142, s[100:101]
	s_waitcnt vmcnt(8)
	s_waitcnt lgkmcnt(0)
	s_barrier
	s_setprio 1
	s_waitcnt lgkmcnt(0)
	v_mfma_f32_16x16x32_bf16 v[62:65], v[130:133], v[190:193], v[62:65]
	v_mfma_f32_16x16x32_bf16 v[30:33], v[154:157], v[190:193], v[30:33]
	v_mfma_f32_16x16x32_bf16 v[54:57], v[130:133], v[198:201], v[54:57]
	v_mfma_f32_16x16x32_bf16 v[22:25], v[154:157], v[198:201], v[22:25]
	v_mfma_f32_16x16x32_bf16 v[50:53], v[130:133], v[206:209], v[50:53]
	v_mfma_f32_16x16x32_bf16 v[18:21], v[154:157], v[206:209], v[18:21]
	v_mfma_f32_16x16x32_bf16 v[38:41], v[130:133], v[214:217], v[38:41]
	v_mfma_f32_16x16x32_bf16 v[6:9], v[154:157], v[214:217], v[6:9]
	v_mfma_f32_16x16x32_bf16 v[62:65], v[134:137], v[194:197], v[62:65]
	v_mfma_f32_16x16x32_bf16 v[30:33], v[158:161], v[194:197], v[30:33]
	v_mfma_f32_16x16x32_bf16 v[54:57], v[134:137], v[202:205], v[54:57]
	v_mfma_f32_16x16x32_bf16 v[22:25], v[158:161], v[202:205], v[22:25]
	v_mfma_f32_16x16x32_bf16 v[50:53], v[134:137], v[210:213], v[50:53]
	v_mfma_f32_16x16x32_bf16 v[18:21], v[158:161], v[210:213], v[18:21]
	v_mfma_f32_16x16x32_bf16 v[38:41], v[134:137], v[218:221], v[38:41]
	v_mfma_f32_16x16x32_bf16 v[6:9], v[158:161], v[218:221], v[6:9]
	s_setprio 0
	s_setprio 1
	v_mfma_f32_16x16x32_bf16 v[58:61], v[162:165], v[190:193], v[58:61]
	v_mfma_f32_16x16x32_bf16 v[26:29], v[170:173], v[190:193], v[26:29]
	v_mfma_f32_16x16x32_bf16 v[46:49], v[162:165], v[198:201], v[46:49]
	v_mfma_f32_16x16x32_bf16 v[14:17], v[170:173], v[198:201], v[14:17]
	v_mfma_f32_16x16x32_bf16 v[42:45], v[162:165], v[206:209], v[42:45]
	v_mfma_f32_16x16x32_bf16 v[10:13], v[170:173], v[206:209], v[10:13]
	v_mfma_f32_16x16x32_bf16 v[34:37], v[162:165], v[214:217], v[34:37]
	v_mfma_f32_16x16x32_bf16 v[2:5], v[170:173], v[214:217], v[2:5]
	v_mfma_f32_16x16x32_bf16 v[58:61], v[166:169], v[194:197], v[58:61]
	v_mfma_f32_16x16x32_bf16 v[26:29], v[186:189], v[194:197], v[26:29]
	v_mfma_f32_16x16x32_bf16 v[46:49], v[166:169], v[202:205], v[46:49]
	v_mfma_f32_16x16x32_bf16 v[14:17], v[186:189], v[202:205], v[14:17]
	v_mfma_f32_16x16x32_bf16 v[42:45], v[166:169], v[210:213], v[42:45]
	v_mfma_f32_16x16x32_bf16 v[10:13], v[186:189], v[210:213], v[10:13]
	v_mfma_f32_16x16x32_bf16 v[34:37], v[166:169], v[218:221], v[34:37]
	v_mfma_f32_16x16x32_bf16 v[2:5], v[186:189], v[218:221], v[2:5]
	s_setprio 0
	s_barrier
	s_add_i32 s70, s70, 2
	s_add_u32 s42, s42, 0x100
	s_addc_u32 s43, s43, 0
	s_add_u32 s68, s68, 0x100
	s_addc_u32 s69, s69, 0
	s_cmp_gt_u32 s70, 13
	s_cbranch_scc0 .LBB0_2613
	s_and_b64 vcc, exec, s[26:27]
	s_cbranch_vccz .LBB0_2616
	s_barrier

; #define PG8_STAGE(bufoff, gbase, voff) do { _Pragma("unroll") for (int _i = 0; _i < 2; ++_i) \
;         __builtin_amdgcn_global_load_lds((const unsigned*)((const char*)(gbase) + (voff)[_i]), (PG8_LAS unsigned*)(lds + (bufoff) + ldsw + _i * 8192), 16, 0, 0); } while (0)
; #define PG8_LDA(dst, b, h) do { _Pragma("unroll") for (int m = 0; m < 4; ++m) _Pragma("unroll") for (int k = 0; k < 2; ++k) dst[m][k] = *(const PG8_LAS bf16x8*)(lds + PG8_SA(b, h) + aoff + m * 2048 + k * 1024); } while (0)
; #define PG8_LDB(dst, b, h) do { _Pragma("unroll") for (int n = 0; n < 2; ++n) _Pragma("unroll") for (int k = 0; k < 2; ++k) dst[n][k] = *(const PG8_LAS bf16x8*)(lds + PG8_SB(b, h) + boff + n * 2048 + k * 1024); } while (0)
; #define PG8_MMA(ai, bj, At, Bt) do { __builtin_amdgcn_s_setprio(1); _Pragma("unroll") for (int m = 0; m < 4; ++m) _Pragma("unroll") for (int n = 0; n < 2; ++n) _Pragma("unroll") for (int k = 0; k < 2; ++k) \
;         acc[ai][bj][m][n] = __builtin_amdgcn_mfma_f32_16x16x32_bf16(Bt[n][k], At[m][k], acc[ai][bj][m][n], 0, 0, 0); __builtin_amdgcn_s_setprio(0); } while (0)
; #define PG8_WAIT_V(n) asm volatile("s_waitcnt vmcnt(" #n ")" ::: "memory")
; #define PG8_WAIT_L(n) asm volatile("s_waitcnt lgkmcnt(" #n ")" ::: "memory")
; template <class Epi, class Sched, bool ALIGN_EPI = false, bool SP2 = false>
; __device__ __forceinline__ void gemm_phase(PG8_LAS unsigned char* lds, const Gemm g, const Sched& S, const Epi& E) {
;     ...
;             const bool last = (t == nt - 2);
;             const char* a1 = cA + (size_t)(t + 1) * kstep;
;             const char* a2 = last ? nA : cA + (size_t)(t + 2) * kstep; const char* b2 = last ? nB : cB + (size_t)(t + 2) * kstep;
;             const char* a3 = a2 + kstep; const char* b3 = b2 + kstep;
;             if (last && has_next) S.a_ready(nxt);
;             if constexpr (SP2) {
;             PG8_LDB(B0, 0, 0); PG8_LDB(B1, 0, 1); PG8_SCHED; PG8_LDA(At, 0, 0); PG8_STAGE(PG8_SA(1, 1), a1 + hstepA, voffA);
;             PG8_WAIT_V(8); PG8_WAIT_L(0); PG8_BAR; PG8_MMA(0, 0, At, B0); PG8_MMA(0, 1, At, B1); PG8_BAR; PG8_SCHED;
;             PG8_LDA(At, 0, 1); PG8_STAGE(PG8_SB(0, 0), b2, voffB); PG8_STAGE(PG8_SB(0, 1), b2 + hstepB, voffB); PG8_STAGE(PG8_SA(0, 0), a2, voffA);
;             PG8_WAIT_V(8); PG8_WAIT_L(0); PG8_BAR; PG8_MMA(1, 0, At, B0); PG8_MMA(1, 1, At, B1); PG8_BAR; PG8_SCHED;
.LBB0_2807:
	v_add_u32_e32 v68, s49, v58
	ds_read_b128 v[60:63], v68
	ds_read_b128 v[64:67], v68 offset:1024
	ds_read_b128 v[162:165], v68 offset:2048
	ds_read_b128 v[166:169], v68 offset:3072
	v_add_u32_e32 v68, s50, v58
	s_add_u32 s22, s14, s20
	ds_read_b128 v[170:173], v68
	ds_read_b128 v[174:177], v68 offset:1024
	ds_read_b128 v[178:181], v68 offset:2048
	ds_read_b128 v[184:187], v68 offset:3072
	s_addc_u32 s23, s15, s21
	s_add_u32 s22, s22, 0x100
	s_addc_u32 s23, s23, 0
	s_add_u32 s57, s54, s20
	s_addc_u32 s58, s55, s21
	s_cmpk_eq_i32 s20, 0x1500
	s_cselect_b32 s25, s19, s23
	s_cselect_b32 s24, s18, s22
	s_cselect_b32 s23, s1, s58
	s_cselect_b32 s22, s0, s57
	v_lshl_add_u64 v[68:69], v[54:55], 0, s[20:21]
	s_add_i32 m0, s41, 0xc000
	ds_read_b128 v[188:191], v59
	ds_read_b128 v[192:195], v59 offset:1024
	ds_read_b128 v[196:199], v59 offset:2048
	ds_read_b128 v[200:203], v59 offset:3072
	ds_read_b128 v[204:207], v59 offset:4096
	ds_read_b128 v[208:211], v59 offset:5120
	ds_read_b128 v[212:215], v59 offset:6144
	ds_read_b128 v[216:219], v59 offset:7168
	global_load_lds_dwordx4 v[68:69], off
	v_lshl_add_u64 v[68:69], v[56:57], 0, s[20:21]
	s_add_i32 m0, s41, 0xe000
	s_nop 0
	global_load_lds_dwordx4 v[68:69], off
	s_waitcnt vmcnt(8)
	s_waitcnt lgkmcnt(0)
	s_barrier
	s_setprio 1
	s_waitcnt lgkmcnt(0)
	v_mfma_f32_16x16x32_bf16 v[158:161], v[60:63], v[188:191], v[158:161]
	v_mfma_f32_16x16x32_bf16 v[146:149], v[162:165], v[188:191], v[146:149]
	v_mfma_f32_16x16x32_bf16 v[150:153], v[60:63], v[196:199], v[150:153]
	v_mfma_f32_16x16x32_bf16 v[154:157], v[162:165], v[196:199], v[154:157]
	v_mfma_f32_16x16x32_bf16 v[142:145], v[60:63], v[204:207], v[142:145]
	v_mfma_f32_16x16x32_bf16 v[138:141], v[162:165], v[204:207], v[138:141]
	v_mfma_f32_16x16x32_bf16 v[134:137], v[60:63], v[212:215], v[134:137]
	v_mfma_f32_16x16x32_bf16 v[130:133], v[162:165], v[212:215], v[130:133]
	v_mfma_f32_16x16x32_bf16 v[158:161], v[64:67], v[192:195], v[158:161]
	v_mfma_f32_16x16x32_bf16 v[146:149], v[166:169], v[192:195], v[146:149]
	v_mfma_f32_16x16x32_bf16 v[150:153], v[64:67], v[200:203], v[150:153]
	v_mfma_f32_16x16x32_bf16 v[154:157], v[166:169], v[200:203], v[154:157]
	v_mfma_f32_16x16x32_bf16 v[142:145], v[64:67], v[208:211], v[142:145]
	v_mfma_f32_16x16x32_bf16 v[138:141], v[166:169], v[208:211], v[138:141]
	v_mfma_f32_16x16x32_bf16 v[134:137], v[64:67], v[216:219], v[134:137]
	v_mfma_f32_16x16x32_bf16 v[130:133], v[166:169], v[216:219], v[130:133]
	s_setprio 0
	s_setprio 1
	v_mfma_f32_16x16x32_bf16 v[78:81], v[170:173], v[188:191], v[78:81]
	v_mfma_f32_16x16x32_bf16 v[74:77], v[178:181], v[188:191], v[74:77]
	v_mfma_f32_16x16x32_bf16 v[86:89], v[170:173], v[196:199], v[86:89]
	v_mfma_f32_16x16x32_bf16 v[90:93], v[178:181], v[196:199], v[90:93]
	v_mfma_f32_16x16x32_bf16 v[118:121], v[170:173], v[204:207], v[118:121]
	v_mfma_f32_16x16x32_bf16 v[114:117], v[178:181], v[204:207], v[114:117]
	v_mfma_f32_16x16x32_bf16 v[122:125], v[170:173], v[212:215], v[122:125]
	v_mfma_f32_16x16x32_bf16 v[126:129], v[178:181], v[212:215], v[126:129]
	v_mfma_f32_16x16x32_bf16 v[78:81], v[174:177], v[192:195], v[78:81]
	v_mfma_f32_16x16x32_bf16 v[74:77], v[184:187], v[192:195], v[74:77]
	v_mfma_f32_16x16x32_bf16 v[86:89], v[174:177], v[200:203], v[86:89]
	v_mfma_f32_16x16x32_bf16 v[90:93], v[184:187], v[200:203], v[90:93]
	v_mfma_f32_16x16x32_bf16 v[118:121], v[174:177], v[208:211], v[118:121]
	v_mfma_f32_16x16x32_bf16 v[114:117], v[184:187], v[208:211], v[114:117]
	v_mfma_f32_16x16x32_bf16 v[122:125], v[174:177], v[216:219], v[122:125]
	v_mfma_f32_16x16x32_bf16 v[126:129], v[184:187], v[216:219], v[126:129]
	s_setprio 0
	s_barrier
	s_add_i32 s57, s49, s40
	s_add_u32 s98, s22, 0x80
	s_addc_u32 s99, s23, 0
	s_mov_b32 m0, s57
	ds_read_b128 v[188:191], v59 offset:16384
	ds_read_b128 v[192:195], v59 offset:17408
	ds_read_b128 v[196:199], v59 offset:18432
	ds_read_b128 v[200:203], v59 offset:19456
	ds_read_b128 v[204:207], v59 offset:20480
	ds_read_b128 v[208:211], v59 offset:21504
	ds_read_b128 v[212:215], v59 offset:22528
	ds_read_b128 v[216:219], v59 offset:23552
	global_load_lds_dwordx4 v8, s[22:23]
	s_add_i32 m0, s57, 0x2000
	s_add_u32 s58, s22, 0xb0000
	s_addc_u32 s59, s23, 0
	s_add_i32 s57, s50, s40
	global_load_lds_dwordx4 v12, s[22:23]
	s_mov_b32 m0, s57
	s_add_u32 s100, s24, 0x80
	s_addc_u32 s101, s25, 0
	global_load_lds_dwordx4 v8, s[58:59]
	s_add_i32 m0, s57, 0x2000
	s_nop 0
	global_load_lds_dwordx4 v12, s[58:59]
	s_mov_b32 m0, s41
	s_nop 0
	global_load_lds_dwordx4 v6, s[24:25]
	s_mov_b32 m0, s42
	s_nop 0
	global_load_lds_dwordx4 v10, s[24:25]
	s_waitcnt vmcnt(8)
	s_waitcnt lgkmcnt(0)
	s_barrier
; #define PG8_STAGE(bufoff, gbase, voff) do { _Pragma("unroll") for (int _i = 0; _i < 2; ++_i) \
;         __builtin_amdgcn_global_load_lds((const unsigned*)((const char*)(gbase) + (voff)[_i]), (PG8_LAS unsigned*)(lds + (bufoff) + ldsw + _i * 8192), 16, 0, 0); } while (0)
; #define PG8_LDA(dst, b, h) do { _Pragma("unroll") for (int m = 0; m < 4; ++m) _Pragma("unroll") for (int k = 0; k < 2; ++k) dst[m][k] = *(const PG8_LAS bf16x8*)(lds + PG8_SA(b, h) + aoff + m * 2048 + k * 1024); } while (0)
; #define PG8_LDB(dst, b, h) do { _Pragma("unroll") for (int n = 0; n < 2; ++n) _Pragma("unroll") for (int k = 0; k < 2; ++k) dst[n][k] = *(const PG8_LAS bf16x8*)(lds + PG8_SB(b, h) + boff + n * 2048 + k * 1024); } while (0)
; #define PG8_MMA(ai, bj, At, Bt) do { __builtin_amdgcn_s_setprio(1); _Pragma("unroll") for (int m = 0; m < 4; ++m) _Pragma("unroll") for (int n = 0; n < 2; ++n) _Pragma("unroll") for (int k = 0; k < 2; ++k) \
;         acc[ai][bj][m][n] = __builtin_amdgcn_mfma_f32_16x16x32_bf16(Bt[n][k], At[m][k], acc[ai][bj][m][n], 0, 0, 0); __builtin_amdgcn_s_setprio(0); } while (0)
; #define PG8_WAIT_V(n) asm volatile("s_waitcnt vmcnt(" #n ")" ::: "memory")
; #define PG8_WAIT_L(n) asm volatile("s_waitcnt lgkmcnt(" #n ")" ::: "memory")
; #define PG8_BAR __builtin_amdgcn_s_barrier()
; #define PG8_SCHED __builtin_amdgcn_sched_barrier(0)
; template <class Epi, class Sched, bool ALIGN_EPI = false, bool SP2 = false>
; __device__ __forceinline__ void gemm_phase(PG8_LAS unsigned char* lds, const Gemm g, const Sched& S, const Epi& E) {
;     ...
;             PG8_WAIT_V(8); PG8_WAIT_L(0); PG8_BAR; PG8_MMA(1, 0, At, B0); PG8_MMA(1, 1, At, B1); PG8_BAR; PG8_SCHED;
;             PG8_LDB(B0, 1, 0); PG8_LDB(B1, 1, 1); PG8_SCHED; PG8_LDA(At, 1, 0); PG8_STAGE(PG8_SA(0, 1), a2 + hstepA, voffA);
;             PG8_WAIT_V(8); PG8_WAIT_L(0); PG8_BAR; PG8_MMA(0, 0, At, B0); PG8_MMA(0, 1, At, B1); PG8_BAR; PG8_SCHED;
	s_setprio 1
	s_waitcnt lgkmcnt(0)
	v_mfma_f32_16x16x32_bf16 v[110:113], v[60:63], v[188:191], v[110:113]
	v_mfma_f32_16x16x32_bf16 v[106:109], v[162:165], v[188:191], v[106:109]
	v_mfma_f32_16x16x32_bf16 v[102:105], v[60:63], v[196:199], v[102:105]
	v_mfma_f32_16x16x32_bf16 v[98:101], v[162:165], v[196:199], v[98:101]
	v_mfma_f32_16x16x32_bf16 v[46:49], v[60:63], v[204:207], v[46:49]
	v_mfma_f32_16x16x32_bf16 v[42:45], v[162:165], v[204:207], v[42:45]
	v_mfma_f32_16x16x32_bf16 v[38:41], v[60:63], v[212:215], v[38:41]
	v_mfma_f32_16x16x32_bf16 v[34:37], v[162:165], v[212:215], v[34:37]
	v_mfma_f32_16x16x32_bf16 v[110:113], v[64:67], v[192:195], v[110:113]
	v_mfma_f32_16x16x32_bf16 v[106:109], v[166:169], v[192:195], v[106:109]
	v_mfma_f32_16x16x32_bf16 v[102:105], v[64:67], v[200:203], v[102:105]
	v_mfma_f32_16x16x32_bf16 v[98:101], v[166:169], v[200:203], v[98:101]
	v_mfma_f32_16x16x32_bf16 v[46:49], v[64:67], v[208:211], v[46:49]
	v_mfma_f32_16x16x32_bf16 v[42:45], v[166:169], v[208:211], v[42:45]
	v_mfma_f32_16x16x32_bf16 v[38:41], v[64:67], v[216:219], v[38:41]
	v_mfma_f32_16x16x32_bf16 v[34:37], v[166:169], v[216:219], v[34:37]
	s_setprio 0
	s_setprio 1
	v_mfma_f32_16x16x32_bf16 v[68:71], v[170:173], v[196:199], v[70:73]
	v_mfma_f32_16x16x32_bf16 v[50:53], v[178:181], v[196:199], v[50:53]
	v_mfma_f32_16x16x32_bf16 v[30:33], v[170:173], v[204:207], v[30:33]
	v_mfma_f32_16x16x32_bf16 v[26:29], v[178:181], v[204:207], v[26:29]
	v_mfma_f32_16x16x32_bf16 v[22:25], v[170:173], v[212:215], v[22:25]
	v_mfma_f32_16x16x32_bf16 v[2:5], v[178:181], v[212:215], v[2:5]
	v_mfma_f32_16x16x32_bf16 v[60:63], v[170:173], v[188:191], v[94:97]
	v_mfma_f32_16x16x32_bf16 v[64:67], v[178:181], v[188:191], v[82:85]
	v_mfma_f32_16x16x32_bf16 v[68:71], v[174:177], v[200:203], v[68:71]
	v_mfma_f32_16x16x32_bf16 v[50:53], v[184:187], v[200:203], v[50:53]
	v_mfma_f32_16x16x32_bf16 v[30:33], v[174:177], v[208:211], v[30:33]
	v_mfma_f32_16x16x32_bf16 v[26:29], v[184:187], v[208:211], v[26:29]
	v_mfma_f32_16x16x32_bf16 v[22:25], v[174:177], v[216:219], v[22:25]
	v_mfma_f32_16x16x32_bf16 v[2:5], v[184:187], v[216:219], v[2:5]
	v_mfma_f32_16x16x32_bf16 v[60:63], v[174:177], v[192:195], v[60:63]
	v_mfma_f32_16x16x32_bf16 v[64:67], v[184:187], v[192:195], v[64:67]
	s_setprio 0
	s_barrier
	s_add_i32 s57, 0, 0x18000
	v_add_u32_e32 v72, s57, v58
	s_add_i32 s58, 0, 0x1c000
	ds_read_b128 v[82:85], v72
	ds_read_b128 v[94:97], v72 offset:1024
	ds_read_b128 v[162:165], v72 offset:2048
	ds_read_b128 v[166:169], v72 offset:3072
	v_add_u32_e32 v72, s58, v58
	ds_read_b128 v[170:173], v72
	ds_read_b128 v[174:177], v72 offset:1024
	ds_read_b128 v[178:181], v72 offset:2048
	ds_read_b128 v[184:187], v72 offset:3072
	s_add_u32 s24, s24, 0xb0000
	s_addc_u32 s25, s25, 0
	s_mov_b32 m0, s44
	ds_read_b128 v[188:191], v59 offset:32768
	ds_read_b128 v[192:195], v59 offset:33792
	ds_read_b128 v[196:199], v59 offset:34816
	ds_read_b128 v[200:203], v59 offset:35840
	ds_read_b128 v[204:207], v59 offset:36864
	ds_read_b128 v[208:211], v59 offset:37888
	ds_read_b128 v[212:215], v59 offset:38912
	ds_read_b128 v[216:219], v59 offset:39936
	global_load_lds_dwordx4 v6, s[24:25]
	s_mov_b32 m0, s45
	s_nop 0
	global_load_lds_dwordx4 v10, s[24:25]
	s_waitcnt vmcnt(8)
	s_waitcnt lgkmcnt(0)
	s_barrier
	s_setprio 1
	s_waitcnt lgkmcnt(0)
	v_mfma_f32_16x16x32_bf16 v[158:161], v[82:85], v[188:191], v[158:161]
	v_mfma_f32_16x16x32_bf16 v[146:149], v[162:165], v[188:191], v[146:149]
	v_mfma_f32_16x16x32_bf16 v[150:153], v[82:85], v[196:199], v[150:153]
	v_mfma_f32_16x16x32_bf16 v[154:157], v[162:165], v[196:199], v[154:157]
	v_mfma_f32_16x16x32_bf16 v[142:145], v[82:85], v[204:207], v[142:145]
	v_mfma_f32_16x16x32_bf16 v[138:141], v[162:165], v[204:207], v[138:141]
	v_mfma_f32_16x16x32_bf16 v[134:137], v[82:85], v[212:215], v[134:137]
	v_mfma_f32_16x16x32_bf16 v[130:133], v[162:165], v[212:215], v[130:133]
	v_mfma_f32_16x16x32_bf16 v[158:161], v[94:97], v[192:195], v[158:161]
	v_mfma_f32_16x16x32_bf16 v[146:149], v[166:169], v[192:195], v[146:149]
	v_mfma_f32_16x16x32_bf16 v[150:153], v[94:97], v[200:203], v[150:153]
	v_mfma_f32_16x16x32_bf16 v[154:157], v[166:169], v[200:203], v[154:157]
	v_mfma_f32_16x16x32_bf16 v[142:145], v[94:97], v[208:211], v[142:145]
	v_mfma_f32_16x16x32_bf16 v[138:141], v[166:169], v[208:211], v[138:141]
	v_mfma_f32_16x16x32_bf16 v[134:137], v[94:97], v[216:219], v[134:137]
	v_mfma_f32_16x16x32_bf16 v[130:133], v[166:169], v[216:219], v[130:133]
	s_setprio 0
	s_setprio 1
	v_mfma_f32_16x16x32_bf16 v[78:81], v[170:173], v[188:191], v[78:81]
	v_mfma_f32_16x16x32_bf16 v[72:75], v[178:181], v[188:191], v[74:77]
	v_mfma_f32_16x16x32_bf16 v[86:89], v[170:173], v[196:199], v[86:89]
	v_mfma_f32_16x16x32_bf16 v[90:93], v[178:181], v[196:199], v[90:93]
	v_mfma_f32_16x16x32_bf16 v[118:121], v[170:173], v[204:207], v[118:121]
	v_mfma_f32_16x16x32_bf16 v[114:117], v[178:181], v[204:207], v[114:117]
	v_mfma_f32_16x16x32_bf16 v[122:125], v[170:173], v[212:215], v[122:125]
	v_mfma_f32_16x16x32_bf16 v[126:129], v[178:181], v[212:215], v[126:129]
	v_mfma_f32_16x16x32_bf16 v[78:81], v[174:177], v[192:195], v[78:81]
	v_mfma_f32_16x16x32_bf16 v[74:77], v[184:187], v[192:195], v[72:75]
	v_mfma_f32_16x16x32_bf16 v[86:89], v[174:177], v[200:203], v[86:89]
	v_mfma_f32_16x16x32_bf16 v[90:93], v[184:187], v[200:203], v[90:93]
	v_mfma_f32_16x16x32_bf16 v[118:121], v[174:177], v[208:211], v[118:121]
	v_mfma_f32_16x16x32_bf16 v[114:117], v[184:187], v[208:211], v[114:117]
	v_mfma_f32_16x16x32_bf16 v[122:125], v[174:177], v[216:219], v[122:125]
	v_mfma_f32_16x16x32_bf16 v[126:129], v[184:187], v[216:219], v[126:129]
	s_setprio 0
	s_barrier
; #define PG8_STAGE(bufoff, gbase, voff) do { _Pragma("unroll") for (int _i = 0; _i < 2; ++_i) \
;         __builtin_amdgcn_global_load_lds((const unsigned*)((const char*)(gbase) + (voff)[_i]), (PG8_LAS unsigned*)(lds + (bufoff) + ldsw + _i * 8192), 16, 0, 0); } while (0)
; #define PG8_LDA(dst, b, h) do { _Pragma("unroll") for (int m = 0; m < 4; ++m) _Pragma("unroll") for (int k = 0; k < 2; ++k) dst[m][k] = *(const PG8_LAS bf16x8*)(lds + PG8_SA(b, h) + aoff + m * 2048 + k * 1024); } while (0)
; #define PG8_MMA(ai, bj, At, Bt) do { __builtin_amdgcn_s_setprio(1); _Pragma("unroll") for (int m = 0; m < 4; ++m) _Pragma("unroll") for (int n = 0; n < 2; ++n) _Pragma("unroll") for (int k = 0; k < 2; ++k) \
;         acc[ai][bj][m][n] = __builtin_amdgcn_mfma_f32_16x16x32_bf16(Bt[n][k], At[m][k], acc[ai][bj][m][n], 0, 0, 0); __builtin_amdgcn_s_setprio(0); } while (0)
; #define PG8_WAIT_V(n) asm volatile("s_waitcnt vmcnt(" #n ")" ::: "memory")
; #define PG8_WAIT_L(n) asm volatile("s_waitcnt lgkmcnt(" #n ")" ::: "memory")
; #define PG8_BAR __builtin_amdgcn_s_barrier()
; #define PG8_SCHED __builtin_amdgcn_sched_barrier(0)
; template <class Epi, class Sched, bool ALIGN_EPI = false, bool SP2 = false>
; __device__ __forceinline__ void gemm_phase(PG8_LAS unsigned char* lds, const Gemm g, const Sched& S, const Epi& E) {
;     ...
;             PG8_LDA(At, 1, 1); PG8_STAGE(PG8_SB(1, 0), b3, voffB); PG8_STAGE(PG8_SB(1, 1), b3 + hstepB, voffB); PG8_STAGE(PG8_SA(1, 0), a3, voffA);
;             PG8_WAIT_V(8); PG8_WAIT_L(0); PG8_BAR; PG8_MMA(1, 0, At, B0); PG8_MMA(1, 1, At, B1); PG8_BAR; PG8_SCHED;
;     ...
; #pragma unroll
;         for (int a = 0; a < 2; ++a)
; #pragma unroll
;             for (int b = 0; b < 2; ++b)
; #pragma unroll
;                 for (int m = 0; m < 4; ++m)
; #pragma unroll
;                     for (int n = 0; n < 2; ++n) acc[a][b][m][n] = (f32x4){0.f, 0.f, 0.f, 0.f};
;         cur = nxt; cA = nA; cB = nB; ++ui;
	s_add_i32 s24, s57, s40
	s_mov_b32 m0, s24
	ds_read_b128 v[188:191], v59 offset:49152
	ds_read_b128 v[192:195], v59 offset:50176
	ds_read_b128 v[196:199], v59 offset:51200
	ds_read_b128 v[200:203], v59 offset:52224
	ds_read_b128 v[204:207], v59 offset:53248
	ds_read_b128 v[208:211], v59 offset:54272
	ds_read_b128 v[212:215], v59 offset:55296
	ds_read_b128 v[216:219], v59 offset:56320
	global_load_lds_dwordx4 v8, s[98:99]
	s_add_i32 m0, s24, 0x2000
	s_add_u32 s22, s22, 0xb0080
	s_addc_u32 s23, s23, 0
	s_add_i32 s24, s58, s40
	global_load_lds_dwordx4 v12, s[98:99]
	s_mov_b32 m0, s24
	s_nop 0
	global_load_lds_dwordx4 v8, s[22:23]
	s_add_i32 m0, s24, 0x2000
	s_nop 0
	global_load_lds_dwordx4 v12, s[22:23]
	s_mov_b32 m0, s47
	s_nop 0
	global_load_lds_dwordx4 v6, s[100:101]
	s_mov_b32 m0, s48
	s_nop 0
	global_load_lds_dwordx4 v10, s[100:101]
	s_waitcnt vmcnt(8)
	s_waitcnt lgkmcnt(0)
	s_barrier
	s_setprio 1
	s_waitcnt lgkmcnt(0)
	v_mfma_f32_16x16x32_bf16 v[110:113], v[82:85], v[188:191], v[110:113]
	v_mfma_f32_16x16x32_bf16 v[106:109], v[162:165], v[188:191], v[106:109]
	v_mfma_f32_16x16x32_bf16 v[102:105], v[82:85], v[196:199], v[102:105]
	v_mfma_f32_16x16x32_bf16 v[98:101], v[162:165], v[196:199], v[98:101]
	v_mfma_f32_16x16x32_bf16 v[46:49], v[82:85], v[204:207], v[46:49]
	v_mfma_f32_16x16x32_bf16 v[42:45], v[162:165], v[204:207], v[42:45]
	v_mfma_f32_16x16x32_bf16 v[38:41], v[82:85], v[212:215], v[38:41]
	v_mfma_f32_16x16x32_bf16 v[34:37], v[162:165], v[212:215], v[34:37]
	v_mfma_f32_16x16x32_bf16 v[110:113], v[94:97], v[192:195], v[110:113]
	v_mfma_f32_16x16x32_bf16 v[106:109], v[166:169], v[192:195], v[106:109]
	v_mfma_f32_16x16x32_bf16 v[102:105], v[94:97], v[200:203], v[102:105]
	v_mfma_f32_16x16x32_bf16 v[98:101], v[166:169], v[200:203], v[98:101]
	v_mfma_f32_16x16x32_bf16 v[46:49], v[94:97], v[208:211], v[46:49]
	v_mfma_f32_16x16x32_bf16 v[42:45], v[166:169], v[208:211], v[42:45]
	v_mfma_f32_16x16x32_bf16 v[38:41], v[94:97], v[216:219], v[38:41]
	v_mfma_f32_16x16x32_bf16 v[34:37], v[166:169], v[216:219], v[34:37]
	s_setprio 0
	s_setprio 1
	v_mfma_f32_16x16x32_bf16 v[60:63], v[170:173], v[188:191], v[60:63]
	v_mfma_f32_16x16x32_bf16 v[94:97], v[174:177], v[192:195], v[60:63]
	v_mfma_f32_16x16x32_bf16 v[60:63], v[178:181], v[188:191], v[64:67]
	v_mfma_f32_16x16x32_bf16 v[82:85], v[184:187], v[192:195], v[60:63]
	v_mfma_f32_16x16x32_bf16 v[60:63], v[170:173], v[196:199], v[68:71]
	v_mfma_f32_16x16x32_bf16 v[50:53], v[178:181], v[196:199], v[50:53]
	v_mfma_f32_16x16x32_bf16 v[30:33], v[170:173], v[204:207], v[30:33]
	v_mfma_f32_16x16x32_bf16 v[26:29], v[178:181], v[204:207], v[26:29]
	v_mfma_f32_16x16x32_bf16 v[22:25], v[170:173], v[212:215], v[22:25]
	v_mfma_f32_16x16x32_bf16 v[2:5], v[178:181], v[212:215], v[2:5]
	v_mfma_f32_16x16x32_bf16 v[70:73], v[174:177], v[200:203], v[60:63]
	v_mfma_f32_16x16x32_bf16 v[50:53], v[184:187], v[200:203], v[50:53]
	v_mfma_f32_16x16x32_bf16 v[30:33], v[174:177], v[208:211], v[30:33]
	v_mfma_f32_16x16x32_bf16 v[26:29], v[184:187], v[208:211], v[26:29]
	v_mfma_f32_16x16x32_bf16 v[22:25], v[174:177], v[216:219], v[22:25]
	v_mfma_f32_16x16x32_bf16 v[2:5], v[184:187], v[216:219], v[2:5]
	s_setprio 0
	s_barrier
	s_add_i32 s56, s56, 2
	s_add_u32 s20, s20, 0x100
	s_addc_u32 s21, s21, 0
	s_cmp_gt_u32 s56, 41
	s_cbranch_scc0 .LBB0_2807
	s_add_u32 s20, s54, 0xffffff00
	s_addc_u32 s21, s55, -1
	s_and_b64 vcc, exec, s[4:5]
	s_cbranch_vccnz .LBB0_2794
	v_mov_b32_e32 v2, 0
	s_mov_b32 s12, s51
	s_mov_b32 s27, s52
	s_mov_b64 s[14:15], s[18:19]
	s_mov_b32 s46, s53
	v_mov_b32_e32 v3, v2
	v_mov_b32_e32 v4, v2
	v_mov_b32_e32 v5, v2
	v_mov_b32_e32 v22, v2
	v_mov_b32_e32 v23, v2
	v_mov_b32_e32 v24, v2
	v_mov_b32_e32 v25, v2
	v_mov_b32_e32 v26, v2
	v_mov_b32_e32 v27, v2
	v_mov_b32_e32 v28, v2
	v_mov_b32_e32 v29, v2
	v_mov_b32_e32 v30, v2
	v_mov_b32_e32 v31, v2
	v_mov_b32_e32 v32, v2
	v_mov_b32_e32 v33, v2
	v_mov_b32_e32 v50, v2
	v_mov_b32_e32 v51, v2
	v_mov_b32_e32 v52, v2
	v_mov_b32_e32 v53, v2
	v_mov_b32_e32 v70, v2
	v_mov_b32_e32 v71, v2
	v_mov_b32_e32 v72, v2
	v_mov_b32_e32 v73, v2
	v_mov_b32_e32 v82, v2
	v_mov_b32_e32 v83, v2
	v_mov_b32_e32 v84, v2
	v_mov_b32_e32 v85, v2
	v_mov_b32_e32 v94, v2
	v_mov_b32_e32 v95, v2
	v_mov_b32_e32 v96, v2
	v_mov_b32_e32 v97, v2
	v_mov_b32_e32 v34, v2
	v_mov_b32_e32 v35, v2
	v_mov_b32_e32 v36, v2
	v_mov_b32_e32 v37, v2
	v_mov_b32_e32 v38, v2
	v_mov_b32_e32 v39, v2
	v_mov_b32_e32 v40, v2
	v_mov_b32_e32 v41, v2
	v_mov_b32_e32 v42, v2
	v_mov_b32_e32 v43, v2
	v_mov_b32_e32 v44, v2
	v_mov_b32_e32 v45, v2
	v_mov_b32_e32 v46, v2
	v_mov_b32_e32 v47, v2
	v_mov_b32_e32 v48, v2
	v_mov_b32_e32 v49, v2
	v_mov_b32_e32 v98, v2
	v_mov_b32_e32 v99, v2
	v_mov_b32_e32 v100, v2
	v_mov_b32_e32 v101, v2
	v_mov_b32_e32 v102, v2
	v_mov_b32_e32 v103, v2
	v_mov_b32_e32 v104, v2
	v_mov_b32_e32 v105, v2
	v_mov_b32_e32 v106, v2
	v_mov_b32_e32 v107, v2
	v_mov_b32_e32 v108, v2
	v_mov_b32_e32 v109, v2
	v_mov_b32_e32 v110, v2
	v_mov_b32_e32 v111, v2
	v_mov_b32_e32 v112, v2
	v_mov_b32_e32 v113, v2
	v_mov_b32_e32 v126, v2
	v_mov_b32_e32 v127, v2
	v_mov_b32_e32 v128, v2
	v_mov_b32_e32 v129, v2
	v_mov_b32_e32 v122, v2
	v_mov_b32_e32 v123, v2
	v_mov_b32_e32 v124, v2
	v_mov_b32_e32 v125, v2
	v_mov_b32_e32 v114, v2
	v_mov_b32_e32 v115, v2
	v_mov_b32_e32 v116, v2
	v_mov_b32_e32 v117, v2
	v_mov_b32_e32 v118, v2
	v_mov_b32_e32 v119, v2
	v_mov_b32_e32 v120, v2
	v_mov_b32_e32 v121, v2
	v_mov_b32_e32 v90, v2
	v_mov_b32_e32 v91, v2
	v_mov_b32_e32 v92, v2
	v_mov_b32_e32 v93, v2
	v_mov_b32_e32 v86, v2
	v_mov_b32_e32 v87, v2
	v_mov_b32_e32 v88, v2
	v_mov_b32_e32 v89, v2
	v_mov_b32_e32 v74, v2
	v_mov_b32_e32 v75, v2
	v_mov_b32_e32 v76, v2
	v_mov_b32_e32 v77, v2
	v_mov_b32_e32 v78, v2
	v_mov_b32_e32 v79, v2
	v_mov_b32_e32 v80, v2
	v_mov_b32_e32 v81, v2
	v_mov_b32_e32 v130, v2
	v_mov_b32_e32 v131, v2
	v_mov_b32_e32 v132, v2
	v_mov_b32_e32 v133, v2
	v_mov_b32_e32 v134, v2
	v_mov_b32_e32 v135, v2
	v_mov_b32_e32 v136, v2
	v_mov_b32_e32 v137, v2
	v_mov_b32_e32 v138, v2
	v_mov_b32_e32 v139, v2
	v_mov_b32_e32 v140, v2
	v_mov_b32_e32 v141, v2
	v_mov_b32_e32 v142, v2
	v_mov_b32_e32 v143, v2
	v_mov_b32_e32 v144, v2
	v_mov_b32_e32 v145, v2
	v_mov_b32_e32 v154, v2
	v_mov_b32_e32 v155, v2
	v_mov_b32_e32 v156, v2
	v_mov_b32_e32 v157, v2
	v_mov_b32_e32 v150, v2
	v_mov_b32_e32 v151, v2
	v_mov_b32_e32 v152, v2
	v_mov_b32_e32 v153, v2
	v_mov_b32_e32 v146, v2
	v_mov_b32_e32 v147, v2
	v_mov_b32_e32 v148, v2
	v_mov_b32_e32 v149, v2
	v_mov_b32_e32 v158, v2
	v_mov_b32_e32 v159, v2
	v_mov_b32_e32 v160, v2
	v_mov_b32_e32 v161, v2
	s_andn2_b64 vcc, exec, s[2:3]
	s_cbranch_vccnz .LBB0_2795

; __global__ void __launch_bounds__(NWAVES * 64, 2) mk_fwd(Args args) {
	.amdhsa_kernel _Z6mk_fwd4Args
		.amdhsa_group_segment_fixed_size 0
		.amdhsa_private_segment_fixed_size 0
		.amdhsa_kernarg_size 528
		.amdhsa_user_sgpr_count 2
		.amdhsa_user_sgpr_dispatch_ptr 0
		.amdhsa_user_sgpr_queue_ptr 0
		.amdhsa_user_sgpr_kernarg_segment_ptr 1
		.amdhsa_user_sgpr_dispatch_id 0
		.amdhsa_user_sgpr_kernarg_preload_length 0
		.amdhsa_user_sgpr_kernarg_preload_offset 0
		.amdhsa_user_sgpr_private_segment_size 0
		.amdhsa_uses_dynamic_stack 0
		.amdhsa_enable_private_segment 0
		.amdhsa_system_sgpr_workgroup_id_x 1
		.amdhsa_system_sgpr_workgroup_id_y 0
		.amdhsa_system_sgpr_workgroup_id_z 0
		.amdhsa_system_sgpr_workgroup_info 0
		.amdhsa_system_vgpr_workitem_id 0
		.amdhsa_next_free_vgpr 255
		.amdhsa_next_free_sgpr 102
		.amdhsa_accum_offset 256
		.amdhsa_reserve_vcc 1
		.amdhsa_float_round_mode_32 0
		.amdhsa_float_round_mode_16_64 0
		.amdhsa_float_denorm_mode_32 3
		.amdhsa_float_denorm_mode_16_64 3
		.amdhsa_dx10_clamp 1
		.amdhsa_ieee_mode 1
		.amdhsa_fp16_overflow 0
		.amdhsa_tg_split 0
		.amdhsa_exception_fp_ieee_invalid_op 0
		.amdhsa_exception_fp_denorm_src 0
		.amdhsa_exception_fp_ieee_div_zero 0
		.amdhsa_exception_fp_ieee_overflow 0
		.amdhsa_exception_fp_ieee_underflow 0
		.amdhsa_exception_fp_ieee_inexact 0
		.amdhsa_exception_int_div_zero 0
	.end_amdhsa_kernel

; __global__ void __launch_bounds__(NWAVES * 64, 2) mk_fwd(Args args) {
amdhsa.kernels:
  - .agpr_count:     0
    .args:
      - .offset:         0
        .size:           272
        .value_kind:     by_value
      - .offset:         272
        .size:           4
        .value_kind:     hidden_block_count_x
      - .offset:         276
        .size:           4
        .value_kind:     hidden_block_count_y
      - .offset:         280
        .size:           4
        .value_kind:     hidden_block_count_z
      - .offset:         284
        .size:           2
        .value_kind:     hidden_group_size_x
      - .offset:         286
        .size:           2
        .value_kind:     hidden_group_size_y
      - .offset:         288
        .size:           2
        .value_kind:     hidden_group_size_z
      - .offset:         290
        .size:           2
        .value_kind:     hidden_remainder_x
      - .offset:         292
        .size:           2
        .value_kind:     hidden_remainder_y
      - .offset:         294
        .size:           2
        .value_kind:     hidden_remainder_z
      - .offset:         312
        .size:           8
        .value_kind:     hidden_global_offset_x
      - .offset:         320
        .size:           8
        .value_kind:     hidden_global_offset_y
      - .offset:         328
        .size:           8
        .value_kind:     hidden_global_offset_z
      - .offset:         336
        .size:           2
        .value_kind:     hidden_grid_dims
      - .offset:         392
        .size:           4
        .value_kind:     hidden_dynamic_lds_size
    .group_segment_fixed_size: 0
    .kernarg_segment_align: 8
    .kernarg_segment_size: 528
    .language:       OpenCL C
    .language_version:
      - 2
      - 0
    .max_flat_workgroup_size: 512
    .name:           _Z6mk_fwd4Args
    .private_segment_fixed_size: 0
    .sgpr_count:     108
    .sgpr_spill_count: 28
    .symbol:         _Z6mk_fwd4Args.kd
    .uniform_work_group_size: 1
    .uses_dynamic_stack: false
    .vgpr_count:     255
    .vgpr_spill_count: 0
    .wavefront_size: 64
